# refined saddr conversion: all K-loop LDS-DMA loads use SGPR bases where the base is still live, dead VALU address adds removed
# baseline (speedup 1.0000x reference)
; #define PG8_STAGE(bufoff, gbase, voff) do { _Pragma("unroll") for (int _i = 0; _i < 2; ++_i) \
;     __builtin_amdgcn_global_load_lds((const unsigned*)((const char*)(gbase) + (voff)[_i]), (LAS unsigned*)(lds + (bufoff) + ldsw + _i * 8192), 16, 0, 0); } while (0)
; #define PG8_LDA(dst, b, h) do { _Pragma("unroll") for (int m = 0; m < 4; ++m) _Pragma("unroll") for (int k = 0; k < 2; ++k) dst[m][k] = *(const LAS bf16x8*)(lds + PG8_SA(b, h) + aoff + m * 2048 + k * 1024); } while (0)
; #define PG8_LDB(dst, b, h) do { _Pragma("unroll") for (int n = 0; n < 2; ++n) _Pragma("unroll") for (int k = 0; k < 2; ++k) dst[n][k] = *(const LAS bf16x8*)(lds + PG8_SB(b, h) + boff + n * 2048 + k * 1024); } while (0)
; #define PG8_MMA(ai, bj, At, Bt) do { __builtin_amdgcn_s_setprio(1); _Pragma("unroll") for (int m = 0; m < 4; ++m) _Pragma("unroll") for (int n = 0; n < 2; ++n) _Pragma("unroll") for (int k = 0; k < 2; ++k) \
;     acc[ai][bj][m][n] = __builtin_amdgcn_mfma_f32_16x16x32_bf16(Bt[n][k], At[m][k], acc[ai][bj][m][n], 0, 0, 0); __builtin_amdgcn_s_setprio(0); } while (0)
; #define PG8_WAIT_V(n) asm volatile("s_waitcnt vmcnt(" #n ")" ::: "memory")
; #define PG8_WAIT_L(n) asm volatile("s_waitcnt lgkmcnt(" #n ")" ::: "memory")
; #define PG8_BAR __builtin_amdgcn_s_barrier()
; template <class Epi, class Sched>
; __device__ __forceinline__ void gemm_phase(LAS unsigned char* lds, const Gemm g, const Sched& S, const Epi& E) {
;     ...
;     for (int t = 0; t < nt; t += 2) {
;       const bool last = (t == nt - 2);
;       const char* a1 = cA + (size_t)(t + 1) * kstep;
;       const char* a2 = last ? nA : cA + (size_t)(t + 2) * kstep; const char* b2 = last ? nB : cB + (size_t)(t + 2) * kstep;
;       const char* a3 = a2 + kstep; const char* b3 = b2 + kstep;
;       if (last && has_next) S.a_ready(nxt);
;       PG8_LDB(B0, 0, 0); PG8_SCHED; PG8_LDA(At, 0, 0); PG8_STAGE(PG8_SA(1, 1), a1 + hstep, voffA);
;       PG8_WAIT_L(8); PG8_BAR; PG8_WAIT_L(0); PG8_MMA(0, 0, At, B0); PG8_BAR; PG8_SCHED;
;       PG8_LDB(B1, 0, 1); PG8_STAGE(PG8_SB(0, 0), b2, voffB);
;       PG8_BAR; PG8_WAIT_L(0); PG8_MMA(0, 1, At, B1); PG8_BAR;
;       PG8_LDA(At, 0, 1); PG8_STAGE(PG8_SA(0, 0), a2, voffA);
;       PG8_BAR; PG8_WAIT_L(0); PG8_MMA(1, 0, At, B0); PG8_BAR; PG8_SCHED;
;       PG8_STAGE(PG8_SB(0, 1), b2 + hstep, voffB);
;       PG8_WAIT_V(6); PG8_BAR; PG8_MMA(1, 1, At, B1); PG8_BAR;
.Lxs_e3:
.LBB0_707:
	s_add_u32 s48, s34, 0xfffc0080
	s_addc_u32 s49, s35, -1
	s_add_i32 s73, 0, 0x10000
	v_add_u32_e32 v140, s73, v201
	ds_read_b128 v[120:123], v140
	ds_read_b128 v[124:127], v140 offset:1024
	ds_read_b128 v[136:139], v140 offset:2048
	ds_read_b128 v[140:143], v140 offset:3072
	s_cmp_eq_u32 s72, 12
	s_cselect_b32 s49, s20, s49
	s_cselect_b32 s48, s45, s48
	s_cselect_b32 vcc_hi, s43, s52
	s_cselect_b32 vcc_lo, s68, s69
	s_add_i32 m0, s65, 0xc000
	ds_read_b128 v[144:147], v203
	ds_read_b128 v[148:151], v203 offset:1024
	ds_read_b128 v[152:155], v203 offset:2048
	ds_read_b128 v[186:189], v203 offset:3072
	ds_read_b128 v[190:193], v203 offset:4096
	ds_read_b128 v[194:197], v203 offset:5120
	ds_read_b128 v[204:207], v203 offset:6144
	ds_read_b128 v[208:211], v203 offset:7168
	global_load_lds_dwordx4 v182, s[34:35]
	s_add_i32 m0, s65, 0xe000
	s_nop 0
	global_load_lds_dwordx4 v184, s[34:35]
	s_waitcnt lgkmcnt(8)
	s_barrier
	s_waitcnt lgkmcnt(0)
	s_waitcnt lgkmcnt(0)
	v_mfma_f32_16x16x32_bf16 v[132:135], v[120:123], v[144:147], v[132:135]
	v_mfma_f32_16x16x32_bf16 v[128:131], v[136:139], v[144:147], v[128:131]
	v_mfma_f32_16x16x32_bf16 v[108:111], v[120:123], v[152:155], v[108:111]
	v_mfma_f32_16x16x32_bf16 v[104:107], v[136:139], v[152:155], v[104:107]
	v_mfma_f32_16x16x32_bf16 v[92:95], v[120:123], v[190:193], v[92:95]
	v_mfma_f32_16x16x32_bf16 v[88:91], v[136:139], v[190:193], v[88:91]
	v_mfma_f32_16x16x32_bf16 v[76:79], v[120:123], v[204:207], v[76:79]
	v_mfma_f32_16x16x32_bf16 v[72:75], v[136:139], v[204:207], v[72:75]
	v_mfma_f32_16x16x32_bf16 v[132:135], v[124:127], v[148:151], v[132:135]
	v_mfma_f32_16x16x32_bf16 v[128:131], v[140:143], v[148:151], v[128:131]
	v_mfma_f32_16x16x32_bf16 v[108:111], v[124:127], v[186:189], v[108:111]
	v_mfma_f32_16x16x32_bf16 v[104:107], v[140:143], v[186:189], v[104:107]
	v_mfma_f32_16x16x32_bf16 v[92:95], v[124:127], v[194:197], v[92:95]
	v_mfma_f32_16x16x32_bf16 v[88:91], v[140:143], v[194:197], v[88:91]
	v_mfma_f32_16x16x32_bf16 v[76:79], v[124:127], v[208:211], v[76:79]
	v_mfma_f32_16x16x32_bf16 v[72:75], v[140:143], v[208:211], v[72:75]
	s_barrier
	s_add_i32 s76, 0, 0x14000
	s_add_i32 s73, s73, s64
	v_add_u32_e32 v160, s76, v201
	s_mov_b32 m0, s73
	ds_read_b128 v[226:229], v160
	ds_read_b128 v[232:235], v160 offset:1024
	ds_read_b128 v[236:239], v160 offset:2048
	ds_read_b128 v[240:243], v160 offset:3072
	global_load_lds_dwordx4 v174, vcc
	s_add_i32 m0, s73, 0x2000
	s_nop 0
	global_load_lds_dwordx4 v156, vcc
	s_barrier
	s_waitcnt lgkmcnt(0)
	s_waitcnt lgkmcnt(0)
	v_mfma_f32_16x16x32_bf16 v[116:119], v[226:229], v[144:147], v[116:119]
	v_mfma_f32_16x16x32_bf16 v[112:115], v[236:239], v[144:147], v[112:115]
	v_mfma_f32_16x16x32_bf16 v[100:103], v[226:229], v[152:155], v[100:103]
	v_mfma_f32_16x16x32_bf16 v[96:99], v[236:239], v[152:155], v[96:99]
	v_mfma_f32_16x16x32_bf16 v[84:87], v[226:229], v[190:193], v[84:87]
	v_mfma_f32_16x16x32_bf16 v[80:83], v[236:239], v[190:193], v[80:83]
	v_mfma_f32_16x16x32_bf16 v[68:71], v[226:229], v[204:207], v[68:71]
	v_mfma_f32_16x16x32_bf16 v[64:67], v[236:239], v[204:207], v[64:67]
	v_mfma_f32_16x16x32_bf16 v[116:119], v[232:235], v[148:151], v[116:119]
	v_mfma_f32_16x16x32_bf16 v[112:115], v[240:243], v[148:151], v[112:115]
	v_mfma_f32_16x16x32_bf16 v[100:103], v[232:235], v[186:189], v[100:103]
	v_mfma_f32_16x16x32_bf16 v[96:99], v[240:243], v[186:189], v[96:99]
	v_mfma_f32_16x16x32_bf16 v[84:87], v[232:235], v[194:197], v[84:87]
	v_mfma_f32_16x16x32_bf16 v[80:83], v[240:243], v[194:197], v[80:83]
	v_mfma_f32_16x16x32_bf16 v[68:71], v[232:235], v[208:211], v[68:71]
	v_mfma_f32_16x16x32_bf16 v[64:67], v[240:243], v[208:211], v[64:67]
	s_mov_b32 m0, s65
	v_lshl_add_u64 v[222:223], s[48:49], 0, v[176:177]
	s_barrier
	ds_read_b128 v[144:147], v203 offset:16384
	ds_read_b128 v[148:151], v203 offset:17408
	ds_read_b128 v[152:155], v203 offset:18432
	ds_read_b128 v[186:189], v203 offset:19456
	ds_read_b128 v[190:193], v203 offset:20480
	ds_read_b128 v[194:197], v203 offset:21504
	ds_read_b128 v[204:207], v203 offset:22528
	ds_read_b128 v[208:211], v203 offset:23552
	global_load_lds_dwordx4 v176, s[48:49]
	v_lshl_add_u64 v[244:245], s[48:49], 0, v[158:159]
	s_mov_b32 m0, s51
	s_nop 0
	global_load_lds_dwordx4 v158, s[48:49]
	s_barrier
	s_waitcnt lgkmcnt(0)
	s_waitcnt lgkmcnt(0)
	v_mfma_f32_16x16x32_bf16 v[60:63], v[120:123], v[144:147], v[60:63]
	v_mfma_f32_16x16x32_bf16 v[56:59], v[136:139], v[144:147], v[56:59]
	v_mfma_f32_16x16x32_bf16 v[44:47], v[120:123], v[152:155], v[44:47]
	v_mfma_f32_16x16x32_bf16 v[40:43], v[136:139], v[152:155], v[40:43]
	v_mfma_f32_16x16x32_bf16 v[28:31], v[120:123], v[190:193], v[28:31]
	v_mfma_f32_16x16x32_bf16 v[24:27], v[136:139], v[190:193], v[24:27]
	v_mfma_f32_16x16x32_bf16 v[12:15], v[120:123], v[204:207], v[12:15]
	v_mfma_f32_16x16x32_bf16 v[8:11], v[136:139], v[204:207], v[8:11]
	v_mfma_f32_16x16x32_bf16 v[60:63], v[124:127], v[148:151], v[60:63]
	v_mfma_f32_16x16x32_bf16 v[56:59], v[140:143], v[148:151], v[56:59]
	v_mfma_f32_16x16x32_bf16 v[44:47], v[124:127], v[186:189], v[44:47]
	v_mfma_f32_16x16x32_bf16 v[40:43], v[140:143], v[186:189], v[40:43]
	v_mfma_f32_16x16x32_bf16 v[28:31], v[124:127], v[194:197], v[28:31]
	v_mfma_f32_16x16x32_bf16 v[24:27], v[140:143], v[194:197], v[24:27]
	v_mfma_f32_16x16x32_bf16 v[12:15], v[124:127], v[208:211], v[12:15]
	v_mfma_f32_16x16x32_bf16 v[8:11], v[140:143], v[208:211], v[8:11]
	s_barrier
	s_add_u32 s74, vcc_lo, 0x40000
	s_addc_u32 s75, vcc_hi, 0
	s_add_i32 s73, s76, s64
	s_mov_b32 m0, s73
	s_nop 0
	global_load_lds_dwordx4 v174, s[74:75]
	s_add_i32 m0, s73, 0x2000
	s_nop 0
	global_load_lds_dwordx4 v156, s[74:75]
	s_waitcnt vmcnt(6)
	s_barrier
; #define PG8_STAGE(bufoff, gbase, voff) do { _Pragma("unroll") for (int _i = 0; _i < 2; ++_i) \
;     __builtin_amdgcn_global_load_lds((const unsigned*)((const char*)(gbase) + (voff)[_i]), (LAS unsigned*)(lds + (bufoff) + ldsw + _i * 8192), 16, 0, 0); } while (0)
; #define PG8_LDA(dst, b, h) do { _Pragma("unroll") for (int m = 0; m < 4; ++m) _Pragma("unroll") for (int k = 0; k < 2; ++k) dst[m][k] = *(const LAS bf16x8*)(lds + PG8_SA(b, h) + aoff + m * 2048 + k * 1024); } while (0)
; #define PG8_LDB(dst, b, h) do { _Pragma("unroll") for (int n = 0; n < 2; ++n) _Pragma("unroll") for (int k = 0; k < 2; ++k) dst[n][k] = *(const LAS bf16x8*)(lds + PG8_SB(b, h) + boff + n * 2048 + k * 1024); } while (0)
; #define PG8_MMA(ai, bj, At, Bt) do { __builtin_amdgcn_s_setprio(1); _Pragma("unroll") for (int m = 0; m < 4; ++m) _Pragma("unroll") for (int n = 0; n < 2; ++n) _Pragma("unroll") for (int k = 0; k < 2; ++k) \
;     acc[ai][bj][m][n] = __builtin_amdgcn_mfma_f32_16x16x32_bf16(Bt[n][k], At[m][k], acc[ai][bj][m][n], 0, 0, 0); __builtin_amdgcn_s_setprio(0); } while (0)
; #define PG8_WAIT_V(n) asm volatile("s_waitcnt vmcnt(" #n ")" ::: "memory")
; #define PG8_WAIT_L(n) asm volatile("s_waitcnt lgkmcnt(" #n ")" ::: "memory")
; #define PG8_BAR __builtin_amdgcn_s_barrier()
; #define PG8_SCHED __builtin_amdgcn_sched_barrier(0)
; template <class Epi, class Sched>
; __device__ __forceinline__ void gemm_phase(LAS unsigned char* lds, const Gemm g, const Sched& S, const Epi& E) {
;     ...
;       PG8_WAIT_V(6); PG8_BAR; PG8_MMA(1, 1, At, B1); PG8_BAR;
;       PG8_LDB(B0, 1, 0); PG8_SCHED; PG8_LDA(At, 1, 0); PG8_STAGE(PG8_SA(0, 1), a2 + hstep, voffA);
;       PG8_WAIT_L(8); PG8_BAR; PG8_WAIT_L(0); PG8_MMA(0, 0, At, B0); PG8_BAR; PG8_SCHED;
;       PG8_LDB(B1, 1, 1); PG8_STAGE(PG8_SB(1, 0), b3, voffB);
	v_mfma_f32_16x16x32_bf16 v[52:55], v[226:229], v[144:147], v[52:55]
	v_mfma_f32_16x16x32_bf16 v[48:51], v[236:239], v[144:147], v[48:51]
	v_mfma_f32_16x16x32_bf16 v[36:39], v[226:229], v[152:155], v[36:39]
	v_mfma_f32_16x16x32_bf16 v[32:35], v[236:239], v[152:155], v[32:35]
	v_mfma_f32_16x16x32_bf16 v[20:23], v[226:229], v[190:193], v[20:23]
	v_mfma_f32_16x16x32_bf16 v[16:19], v[236:239], v[190:193], v[16:19]
	v_mfma_f32_16x16x32_bf16 v[4:7], v[226:229], v[204:207], v[4:7]
	v_mfma_f32_16x16x32_bf16 v[0:3], v[236:239], v[204:207], v[0:3]
	v_mfma_f32_16x16x32_bf16 v[52:55], v[232:235], v[148:151], v[52:55]
	v_mfma_f32_16x16x32_bf16 v[48:51], v[240:243], v[148:151], v[48:51]
	v_mfma_f32_16x16x32_bf16 v[36:39], v[232:235], v[186:189], v[36:39]
	v_mfma_f32_16x16x32_bf16 v[32:35], v[240:243], v[186:189], v[32:35]
	v_mfma_f32_16x16x32_bf16 v[20:23], v[232:235], v[194:197], v[20:23]
	v_mfma_f32_16x16x32_bf16 v[16:19], v[240:243], v[194:197], v[16:19]
	v_mfma_f32_16x16x32_bf16 v[4:7], v[232:235], v[208:211], v[4:7]
	v_mfma_f32_16x16x32_bf16 v[0:3], v[240:243], v[208:211], v[0:3]
	s_add_i32 s73, 0, 0x18000
	v_add_u32_e32 v140, s73, v201
	s_barrier
	ds_read_b128 v[120:123], v140
	ds_read_b128 v[124:127], v140 offset:1024
	ds_read_b128 v[136:139], v140 offset:2048
	ds_read_b128 v[140:143], v140 offset:3072
	s_add_u32 s48, s48, 0x40000
	s_addc_u32 s49, s49, 0
	s_mov_b32 m0, s62
	ds_read_b128 v[144:147], v203 offset:32768
	ds_read_b128 v[148:151], v203 offset:33792
	ds_read_b128 v[152:155], v203 offset:34816
	ds_read_b128 v[186:189], v203 offset:35840
	ds_read_b128 v[190:193], v203 offset:36864
	ds_read_b128 v[194:197], v203 offset:37888
	ds_read_b128 v[204:207], v203 offset:38912
	ds_read_b128 v[208:211], v203 offset:39936
	global_load_lds_dwordx4 v176, s[48:49]
	s_mov_b32 m0, s63
	s_nop 0
	global_load_lds_dwordx4 v158, s[48:49]
	s_waitcnt lgkmcnt(8)
	s_barrier
	s_waitcnt lgkmcnt(0)
	s_waitcnt lgkmcnt(0)
	v_mfma_f32_16x16x32_bf16 v[132:135], v[120:123], v[144:147], v[132:135]
	v_mfma_f32_16x16x32_bf16 v[128:131], v[136:139], v[144:147], v[128:131]
	v_mfma_f32_16x16x32_bf16 v[108:111], v[120:123], v[152:155], v[108:111]
	v_mfma_f32_16x16x32_bf16 v[104:107], v[136:139], v[152:155], v[104:107]
	v_mfma_f32_16x16x32_bf16 v[92:95], v[120:123], v[190:193], v[92:95]
	v_mfma_f32_16x16x32_bf16 v[88:91], v[136:139], v[190:193], v[88:91]
	v_mfma_f32_16x16x32_bf16 v[76:79], v[120:123], v[204:207], v[76:79]
	v_mfma_f32_16x16x32_bf16 v[72:75], v[136:139], v[204:207], v[72:75]
	v_mfma_f32_16x16x32_bf16 v[132:135], v[124:127], v[148:151], v[132:135]
	v_mfma_f32_16x16x32_bf16 v[128:131], v[140:143], v[148:151], v[128:131]
	v_mfma_f32_16x16x32_bf16 v[108:111], v[124:127], v[186:189], v[108:111]
	v_mfma_f32_16x16x32_bf16 v[104:107], v[140:143], v[186:189], v[104:107]
	v_mfma_f32_16x16x32_bf16 v[92:95], v[124:127], v[194:197], v[92:95]
	v_mfma_f32_16x16x32_bf16 v[88:91], v[140:143], v[194:197], v[88:91]
	v_mfma_f32_16x16x32_bf16 v[76:79], v[124:127], v[208:211], v[76:79]
	v_mfma_f32_16x16x32_bf16 v[72:75], v[140:143], v[208:211], v[72:75]
	s_barrier
	s_add_i32 s74, 0, 0x1c000
	s_add_i32 s48, s73, s64
	v_add_u32_e32 v160, s74, v201
	s_add_u32 s98, vcc_lo, s80
	s_addc_u32 s99, vcc_hi, s81
	s_mov_b32 m0, s48
	ds_read_b128 v[226:229], v160
	ds_read_b128 v[232:235], v160 offset:1024
	ds_read_b128 v[236:239], v160 offset:2048
	ds_read_b128 v[240:243], v160 offset:3072
	global_load_lds_dwordx4 v174, s[98:99]
	s_add_i32 m0, s48, 0x2000
	s_nop 0
	global_load_lds_dwordx4 v156, s[98:99]
	s_barrier
; #define PG8_STAGE(bufoff, gbase, voff) do { _Pragma("unroll") for (int _i = 0; _i < 2; ++_i) \
;     __builtin_amdgcn_global_load_lds((const unsigned*)((const char*)(gbase) + (voff)[_i]), (LAS unsigned*)(lds + (bufoff) + ldsw + _i * 8192), 16, 0, 0); } while (0)
; #define PG8_LDA(dst, b, h) do { _Pragma("unroll") for (int m = 0; m < 4; ++m) _Pragma("unroll") for (int k = 0; k < 2; ++k) dst[m][k] = *(const LAS bf16x8*)(lds + PG8_SA(b, h) + aoff + m * 2048 + k * 1024); } while (0)
; #define PG8_MMA(ai, bj, At, Bt) do { __builtin_amdgcn_s_setprio(1); _Pragma("unroll") for (int m = 0; m < 4; ++m) _Pragma("unroll") for (int n = 0; n < 2; ++n) _Pragma("unroll") for (int k = 0; k < 2; ++k) \
;     acc[ai][bj][m][n] = __builtin_amdgcn_mfma_f32_16x16x32_bf16(Bt[n][k], At[m][k], acc[ai][bj][m][n], 0, 0, 0); __builtin_amdgcn_s_setprio(0); } while (0)
; #define PG8_WAIT_V(n) asm volatile("s_waitcnt vmcnt(" #n ")" ::: "memory")
; #define PG8_WAIT_L(n) asm volatile("s_waitcnt lgkmcnt(" #n ")" ::: "memory")
; #define PG8_BAR __builtin_amdgcn_s_barrier()
; #define PG8_SCHED __builtin_amdgcn_sched_barrier(0)
; template <class Epi, class Sched>
; __device__ __forceinline__ void gemm_phase(LAS unsigned char* lds, const Gemm g, const Sched& S, const Epi& E) {
;     ...
;       PG8_BAR; PG8_WAIT_L(0); PG8_MMA(0, 1, At, B1); PG8_BAR;
;       PG8_LDA(At, 1, 1); PG8_STAGE(PG8_SA(1, 0), a3, voffA);
;       PG8_BAR; PG8_WAIT_L(0); PG8_MMA(1, 0, At, B0); PG8_BAR; PG8_SCHED;
;       PG8_STAGE(PG8_SB(1, 1), b3 + hstep, voffB);
;       PG8_WAIT_V(6); PG8_BAR; PG8_MMA(1, 1, At, B1); PG8_BAR;
	s_waitcnt lgkmcnt(0)
	s_waitcnt lgkmcnt(0)
	v_mfma_f32_16x16x32_bf16 v[116:119], v[226:229], v[144:147], v[116:119]
	v_mfma_f32_16x16x32_bf16 v[112:115], v[236:239], v[144:147], v[112:115]
	v_mfma_f32_16x16x32_bf16 v[100:103], v[226:229], v[152:155], v[100:103]
	v_mfma_f32_16x16x32_bf16 v[96:99], v[236:239], v[152:155], v[96:99]
	v_mfma_f32_16x16x32_bf16 v[84:87], v[226:229], v[190:193], v[84:87]
	v_mfma_f32_16x16x32_bf16 v[80:83], v[236:239], v[190:193], v[80:83]
	v_mfma_f32_16x16x32_bf16 v[68:71], v[226:229], v[204:207], v[68:71]
	v_mfma_f32_16x16x32_bf16 v[64:67], v[236:239], v[204:207], v[64:67]
	v_mfma_f32_16x16x32_bf16 v[116:119], v[232:235], v[148:151], v[116:119]
	v_mfma_f32_16x16x32_bf16 v[112:115], v[240:243], v[148:151], v[112:115]
	v_mfma_f32_16x16x32_bf16 v[100:103], v[232:235], v[186:189], v[100:103]
	v_mfma_f32_16x16x32_bf16 v[96:99], v[240:243], v[186:189], v[96:99]
	v_mfma_f32_16x16x32_bf16 v[84:87], v[232:235], v[194:197], v[84:87]
	v_mfma_f32_16x16x32_bf16 v[80:83], v[240:243], v[194:197], v[80:83]
	v_mfma_f32_16x16x32_bf16 v[68:71], v[232:235], v[208:211], v[68:71]
	v_mfma_f32_16x16x32_bf16 v[64:67], v[240:243], v[208:211], v[64:67]
	s_mov_b32 m0, s70
	v_lshl_add_u64 v[198:199], v[222:223], 0, s[80:81]
	s_barrier
	ds_read_b128 v[144:147], v203 offset:49152
	ds_read_b128 v[148:151], v203 offset:50176
	ds_read_b128 v[152:155], v203 offset:51200
	ds_read_b128 v[186:189], v203 offset:52224
	ds_read_b128 v[190:193], v203 offset:53248
	ds_read_b128 v[194:197], v203 offset:54272
	ds_read_b128 v[204:207], v203 offset:55296
	ds_read_b128 v[208:211], v203 offset:56320
	global_load_lds_dwordx4 v[198:199], off
	v_lshl_add_u64 v[198:199], v[244:245], 0, s[80:81]
	s_mov_b32 m0, s71
	s_nop 0
	global_load_lds_dwordx4 v[198:199], off
	s_barrier
	s_waitcnt lgkmcnt(0)
	s_waitcnt lgkmcnt(0)
	v_mfma_f32_16x16x32_bf16 v[60:63], v[120:123], v[144:147], v[60:63]
	v_mfma_f32_16x16x32_bf16 v[56:59], v[136:139], v[144:147], v[56:59]
	v_mfma_f32_16x16x32_bf16 v[44:47], v[120:123], v[152:155], v[44:47]
	v_mfma_f32_16x16x32_bf16 v[40:43], v[136:139], v[152:155], v[40:43]
	v_mfma_f32_16x16x32_bf16 v[28:31], v[120:123], v[190:193], v[28:31]
	v_mfma_f32_16x16x32_bf16 v[24:27], v[136:139], v[190:193], v[24:27]
	v_mfma_f32_16x16x32_bf16 v[12:15], v[120:123], v[204:207], v[12:15]
	v_mfma_f32_16x16x32_bf16 v[8:11], v[136:139], v[204:207], v[8:11]
	v_mfma_f32_16x16x32_bf16 v[60:63], v[124:127], v[148:151], v[60:63]
	v_mfma_f32_16x16x32_bf16 v[56:59], v[140:143], v[148:151], v[56:59]
	v_mfma_f32_16x16x32_bf16 v[44:47], v[124:127], v[186:189], v[44:47]
	v_mfma_f32_16x16x32_bf16 v[40:43], v[140:143], v[186:189], v[40:43]
	v_mfma_f32_16x16x32_bf16 v[28:31], v[124:127], v[194:197], v[28:31]
	v_mfma_f32_16x16x32_bf16 v[24:27], v[140:143], v[194:197], v[24:27]
	v_mfma_f32_16x16x32_bf16 v[12:15], v[124:127], v[208:211], v[12:15]
	v_mfma_f32_16x16x32_bf16 v[8:11], v[140:143], v[208:211], v[8:11]
	s_barrier
	s_add_u32 s48, vcc_lo, 0x40080
	s_addc_u32 s49, vcc_hi, 0
	s_add_i32 s73, s74, s64
	s_mov_b32 m0, s73
	s_nop 0
	global_load_lds_dwordx4 v174, s[48:49]
	s_add_i32 m0, s73, 0x2000
	s_nop 0
	global_load_lds_dwordx4 v156, s[48:49]
	s_waitcnt vmcnt(6)
	s_barrier
	v_mfma_f32_16x16x32_bf16 v[52:55], v[226:229], v[144:147], v[52:55]
	v_mfma_f32_16x16x32_bf16 v[48:51], v[236:239], v[144:147], v[48:51]
	v_mfma_f32_16x16x32_bf16 v[36:39], v[226:229], v[152:155], v[36:39]
	v_mfma_f32_16x16x32_bf16 v[32:35], v[236:239], v[152:155], v[32:35]
	v_mfma_f32_16x16x32_bf16 v[20:23], v[226:229], v[190:193], v[20:23]
	v_mfma_f32_16x16x32_bf16 v[16:19], v[236:239], v[190:193], v[16:19]
	v_mfma_f32_16x16x32_bf16 v[4:7], v[226:229], v[204:207], v[4:7]
	v_mfma_f32_16x16x32_bf16 v[0:3], v[236:239], v[204:207], v[0:3]
	v_mfma_f32_16x16x32_bf16 v[52:55], v[232:235], v[148:151], v[52:55]
	v_mfma_f32_16x16x32_bf16 v[48:51], v[240:243], v[148:151], v[48:51]
	v_mfma_f32_16x16x32_bf16 v[36:39], v[232:235], v[186:189], v[36:39]
	v_mfma_f32_16x16x32_bf16 v[32:35], v[240:243], v[186:189], v[32:35]
	v_mfma_f32_16x16x32_bf16 v[20:23], v[232:235], v[194:197], v[20:23]
	v_mfma_f32_16x16x32_bf16 v[16:19], v[240:243], v[194:197], v[16:19]
	v_mfma_f32_16x16x32_bf16 v[4:7], v[232:235], v[208:211], v[4:7]
	v_mfma_f32_16x16x32_bf16 v[0:3], v[240:243], v[208:211], v[0:3]
	s_add_i32 s72, s72, 2
	s_add_u32 s34, s34, 0x100
	s_addc_u32 s35, s35, 0
	s_add_u32 s69, s69, 0x100
	s_addc_u32 s52, s52, 0
	s_cmp_gt_u32 s72, 13
	s_barrier
	s_cbranch_scc0 .LBB0_707
	s_cmp_lt_u32 s101, 0x100
	s_cbranch_scc0 .Lxa_3
	s_barrier

; #define PG8_STAGE(bufoff, gbase, voff) do { _Pragma("unroll") for (int _i = 0; _i < 2; ++_i) \
;     __builtin_amdgcn_global_load_lds((const unsigned*)((const char*)(gbase) + (voff)[_i]), (LAS unsigned*)(lds + (bufoff) + ldsw + _i * 8192), 16, 0, 0); } while (0)
; #define PG8_LDA(dst, b, h) do { _Pragma("unroll") for (int m = 0; m < 4; ++m) _Pragma("unroll") for (int k = 0; k < 2; ++k) dst[m][k] = *(const LAS bf16x8*)(lds + PG8_SA(b, h) + aoff + m * 2048 + k * 1024); } while (0)
; #define PG8_LDB(dst, b, h) do { _Pragma("unroll") for (int n = 0; n < 2; ++n) _Pragma("unroll") for (int k = 0; k < 2; ++k) dst[n][k] = *(const LAS bf16x8*)(lds + PG8_SB(b, h) + boff + n * 2048 + k * 1024); } while (0)
; #define PG8_MMA(ai, bj, At, Bt) do { __builtin_amdgcn_s_setprio(1); _Pragma("unroll") for (int m = 0; m < 4; ++m) _Pragma("unroll") for (int n = 0; n < 2; ++n) _Pragma("unroll") for (int k = 0; k < 2; ++k) \
;     acc[ai][bj][m][n] = __builtin_amdgcn_mfma_f32_16x16x32_bf16(Bt[n][k], At[m][k], acc[ai][bj][m][n], 0, 0, 0); __builtin_amdgcn_s_setprio(0); } while (0)
; #define PG8_WAIT_V(n) asm volatile("s_waitcnt vmcnt(" #n ")" ::: "memory")
; #define PG8_WAIT_L(n) asm volatile("s_waitcnt lgkmcnt(" #n ")" ::: "memory")
; #define PG8_BAR __builtin_amdgcn_s_barrier()
; template <class Epi, class Sched>
; __device__ __forceinline__ void gemm_phase(LAS unsigned char* lds, const Gemm g, const Sched& S, const Epi& E) {
;     ...
;     for (int t = 0; t < nt; t += 2) {
;       const bool last = (t == nt - 2);
;       const char* a1 = cA + (size_t)(t + 1) * kstep;
;       const char* a2 = last ? nA : cA + (size_t)(t + 2) * kstep; const char* b2 = last ? nB : cB + (size_t)(t + 2) * kstep;
;       const char* a3 = a2 + kstep; const char* b3 = b2 + kstep;
;       if (last && has_next) S.a_ready(nxt);
;       PG8_LDB(B0, 0, 0); PG8_SCHED; PG8_LDA(At, 0, 0); PG8_STAGE(PG8_SA(1, 1), a1 + hstep, voffA);
;       PG8_WAIT_L(8); PG8_BAR; PG8_WAIT_L(0); PG8_MMA(0, 0, At, B0); PG8_BAR; PG8_SCHED;
;       PG8_LDB(B1, 0, 1); PG8_STAGE(PG8_SB(0, 0), b2, voffB);
;       PG8_BAR; PG8_WAIT_L(0); PG8_MMA(0, 1, At, B1); PG8_BAR;
;       PG8_LDA(At, 0, 1); PG8_STAGE(PG8_SA(0, 0), a2, voffA);
;       PG8_BAR; PG8_WAIT_L(0); PG8_MMA(1, 0, At, B0); PG8_BAR; PG8_SCHED;
;       PG8_STAGE(PG8_SB(0, 1), b2 + hstep, voffB);
;       PG8_WAIT_V(6); PG8_BAR; PG8_MMA(1, 1, At, B1); PG8_BAR;
.Lxs_e4:
.LBB0_778:
	s_add_u32 s44, s34, 0xfffe0080
	s_addc_u32 s45, s35, -1
	s_add_i32 s73, 0, 0x10000
	v_add_u32_e32 v150, s73, v177
	ds_read_b128 v[138:141], v150
	ds_read_b128 v[142:145], v150 offset:1024
	ds_read_b128 v[146:149], v150 offset:2048
	ds_read_b128 v[150:153], v150 offset:3072
	s_cmp_eq_u32 s72, 4
	s_cselect_b32 s49, s37, s45
	s_cselect_b32 s48, s69, s44
	s_cselect_b32 s45, s23, s52
	s_cselect_b32 s44, s70, s71
	s_add_i32 m0, s12, 0xc000
	ds_read_b128 v[154:157], v179
	ds_read_b128 v[180:183], v179 offset:1024
	ds_read_b128 v[184:187], v179 offset:2048
	ds_read_b128 v[188:191], v179 offset:3072
	ds_read_b128 v[192:195], v179 offset:4096
	ds_read_b128 v[196:199], v179 offset:5120
	ds_read_b128 v[200:203], v179 offset:6144
	ds_read_b128 v[204:207], v179 offset:7168
	global_load_lds_dwordx4 v134, s[34:35]
	s_add_i32 m0, s12, 0xe000
	s_nop 0
	global_load_lds_dwordx4 v136, s[34:35]
	s_waitcnt lgkmcnt(8)
	s_barrier
	s_waitcnt lgkmcnt(0)
	s_waitcnt lgkmcnt(0)
	v_mfma_f32_16x16x32_bf16 v[124:127], v[138:141], v[154:157], v[124:127]
	v_mfma_f32_16x16x32_bf16 v[120:123], v[146:149], v[154:157], v[120:123]
	v_mfma_f32_16x16x32_bf16 v[108:111], v[138:141], v[184:187], v[108:111]
	v_mfma_f32_16x16x32_bf16 v[104:107], v[146:149], v[184:187], v[104:107]
	v_mfma_f32_16x16x32_bf16 v[92:95], v[138:141], v[192:195], v[92:95]
	v_mfma_f32_16x16x32_bf16 v[88:91], v[146:149], v[192:195], v[88:91]
	v_mfma_f32_16x16x32_bf16 v[76:79], v[138:141], v[200:203], v[76:79]
	v_mfma_f32_16x16x32_bf16 v[72:75], v[146:149], v[200:203], v[72:75]
	v_mfma_f32_16x16x32_bf16 v[124:127], v[142:145], v[180:183], v[124:127]
	v_mfma_f32_16x16x32_bf16 v[120:123], v[150:153], v[180:183], v[120:123]
	v_mfma_f32_16x16x32_bf16 v[108:111], v[142:145], v[188:191], v[108:111]
	v_mfma_f32_16x16x32_bf16 v[104:107], v[150:153], v[188:191], v[104:107]
	v_mfma_f32_16x16x32_bf16 v[92:95], v[142:145], v[196:199], v[92:95]
	v_mfma_f32_16x16x32_bf16 v[88:91], v[150:153], v[196:199], v[88:91]
	v_mfma_f32_16x16x32_bf16 v[76:79], v[142:145], v[204:207], v[76:79]
	v_mfma_f32_16x16x32_bf16 v[72:75], v[150:153], v[204:207], v[72:75]
	s_barrier
	s_add_i32 s76, 0, 0x14000
	v_add_u32_e32 v158, s76, v177
	s_add_i32 s73, s73, s7
	ds_read_b128 v[208:211], v158
	ds_read_b128 v[226:229], v158 offset:1024
	ds_read_b128 v[232:235], v158 offset:2048
	ds_read_b128 v[236:239], v158 offset:3072
	s_mov_b32 m0, s73
	s_nop 0
	global_load_lds_dwordx4 v160, s[44:45]
	s_add_i32 m0, s73, 0x2000
	s_nop 0
	global_load_lds_dwordx4 v128, s[44:45]
	s_barrier
	s_waitcnt lgkmcnt(0)
	s_waitcnt lgkmcnt(0)
	v_mfma_f32_16x16x32_bf16 v[116:119], v[208:211], v[154:157], v[116:119]
	v_mfma_f32_16x16x32_bf16 v[112:115], v[232:235], v[154:157], v[112:115]
	v_mfma_f32_16x16x32_bf16 v[100:103], v[208:211], v[184:187], v[100:103]
	v_mfma_f32_16x16x32_bf16 v[96:99], v[232:235], v[184:187], v[96:99]
	v_mfma_f32_16x16x32_bf16 v[84:87], v[208:211], v[192:195], v[84:87]
	v_mfma_f32_16x16x32_bf16 v[80:83], v[232:235], v[192:195], v[80:83]
	v_mfma_f32_16x16x32_bf16 v[68:71], v[208:211], v[200:203], v[68:71]
	v_mfma_f32_16x16x32_bf16 v[64:67], v[232:235], v[200:203], v[64:67]
	v_mfma_f32_16x16x32_bf16 v[116:119], v[226:229], v[180:183], v[116:119]
	v_mfma_f32_16x16x32_bf16 v[112:115], v[236:239], v[180:183], v[112:115]
	v_mfma_f32_16x16x32_bf16 v[100:103], v[226:229], v[188:191], v[100:103]
	v_mfma_f32_16x16x32_bf16 v[96:99], v[236:239], v[188:191], v[96:99]
	v_mfma_f32_16x16x32_bf16 v[84:87], v[226:229], v[196:199], v[84:87]
	v_mfma_f32_16x16x32_bf16 v[80:83], v[236:239], v[196:199], v[80:83]
	v_mfma_f32_16x16x32_bf16 v[68:71], v[226:229], v[204:207], v[68:71]
	v_mfma_f32_16x16x32_bf16 v[64:67], v[236:239], v[204:207], v[64:67]
	s_mov_b32 m0, s12
	v_lshl_add_u64 v[212:213], s[48:49], 0, v[132:133]
	s_barrier
	ds_read_b128 v[154:157], v179 offset:16384
	ds_read_b128 v[180:183], v179 offset:17408
	ds_read_b128 v[184:187], v179 offset:18432
	ds_read_b128 v[188:191], v179 offset:19456
	ds_read_b128 v[192:195], v179 offset:20480
	ds_read_b128 v[196:199], v179 offset:21504
	ds_read_b128 v[200:203], v179 offset:22528
	ds_read_b128 v[204:207], v179 offset:23552
	global_load_lds_dwordx4 v132, s[48:49]
	v_lshl_add_u64 v[222:223], s[48:49], 0, v[130:131]
	s_mov_b32 m0, s13
	s_nop 0
	global_load_lds_dwordx4 v130, s[48:49]
	s_barrier
	s_waitcnt lgkmcnt(0)
	s_waitcnt lgkmcnt(0)
	v_mfma_f32_16x16x32_bf16 v[60:63], v[138:141], v[154:157], v[60:63]
	v_mfma_f32_16x16x32_bf16 v[56:59], v[146:149], v[154:157], v[56:59]
	v_mfma_f32_16x16x32_bf16 v[44:47], v[138:141], v[184:187], v[44:47]
	v_mfma_f32_16x16x32_bf16 v[40:43], v[146:149], v[184:187], v[40:43]
	v_mfma_f32_16x16x32_bf16 v[28:31], v[138:141], v[192:195], v[28:31]
	v_mfma_f32_16x16x32_bf16 v[24:27], v[146:149], v[192:195], v[24:27]
	v_mfma_f32_16x16x32_bf16 v[12:15], v[138:141], v[200:203], v[12:15]
	v_mfma_f32_16x16x32_bf16 v[8:11], v[146:149], v[200:203], v[8:11]
	v_mfma_f32_16x16x32_bf16 v[60:63], v[142:145], v[180:183], v[60:63]
	v_mfma_f32_16x16x32_bf16 v[56:59], v[150:153], v[180:183], v[56:59]
	v_mfma_f32_16x16x32_bf16 v[44:47], v[142:145], v[188:191], v[44:47]
	v_mfma_f32_16x16x32_bf16 v[40:43], v[150:153], v[188:191], v[40:43]
	v_mfma_f32_16x16x32_bf16 v[28:31], v[142:145], v[196:199], v[28:31]
	v_mfma_f32_16x16x32_bf16 v[24:27], v[150:153], v[196:199], v[24:27]
	v_mfma_f32_16x16x32_bf16 v[12:15], v[142:145], v[204:207], v[12:15]
	v_mfma_f32_16x16x32_bf16 v[8:11], v[150:153], v[204:207], v[8:11]
	s_barrier
	s_add_u32 s74, s44, 0x20000
	s_addc_u32 s75, s45, 0
	s_add_i32 s73, s76, s7
	s_mov_b32 m0, s73
	s_nop 0
	global_load_lds_dwordx4 v160, s[74:75]
	s_add_i32 m0, s73, 0x2000
	s_nop 0
	global_load_lds_dwordx4 v128, s[74:75]
	s_waitcnt vmcnt(6)
	s_barrier
; #define PG8_STAGE(bufoff, gbase, voff) do { _Pragma("unroll") for (int _i = 0; _i < 2; ++_i) \
;     __builtin_amdgcn_global_load_lds((const unsigned*)((const char*)(gbase) + (voff)[_i]), (LAS unsigned*)(lds + (bufoff) + ldsw + _i * 8192), 16, 0, 0); } while (0)
; #define PG8_LDA(dst, b, h) do { _Pragma("unroll") for (int m = 0; m < 4; ++m) _Pragma("unroll") for (int k = 0; k < 2; ++k) dst[m][k] = *(const LAS bf16x8*)(lds + PG8_SA(b, h) + aoff + m * 2048 + k * 1024); } while (0)
; #define PG8_LDB(dst, b, h) do { _Pragma("unroll") for (int n = 0; n < 2; ++n) _Pragma("unroll") for (int k = 0; k < 2; ++k) dst[n][k] = *(const LAS bf16x8*)(lds + PG8_SB(b, h) + boff + n * 2048 + k * 1024); } while (0)
; #define PG8_MMA(ai, bj, At, Bt) do { __builtin_amdgcn_s_setprio(1); _Pragma("unroll") for (int m = 0; m < 4; ++m) _Pragma("unroll") for (int n = 0; n < 2; ++n) _Pragma("unroll") for (int k = 0; k < 2; ++k) \
;     acc[ai][bj][m][n] = __builtin_amdgcn_mfma_f32_16x16x32_bf16(Bt[n][k], At[m][k], acc[ai][bj][m][n], 0, 0, 0); __builtin_amdgcn_s_setprio(0); } while (0)
; #define PG8_WAIT_V(n) asm volatile("s_waitcnt vmcnt(" #n ")" ::: "memory")
; #define PG8_WAIT_L(n) asm volatile("s_waitcnt lgkmcnt(" #n ")" ::: "memory")
; #define PG8_BAR __builtin_amdgcn_s_barrier()
; #define PG8_SCHED __builtin_amdgcn_sched_barrier(0)
; template <class Epi, class Sched>
; __device__ __forceinline__ void gemm_phase(LAS unsigned char* lds, const Gemm g, const Sched& S, const Epi& E) {
;     ...
;       PG8_WAIT_V(6); PG8_BAR; PG8_MMA(1, 1, At, B1); PG8_BAR;
;       PG8_LDB(B0, 1, 0); PG8_SCHED; PG8_LDA(At, 1, 0); PG8_STAGE(PG8_SA(0, 1), a2 + hstep, voffA);
;       PG8_WAIT_L(8); PG8_BAR; PG8_WAIT_L(0); PG8_MMA(0, 0, At, B0); PG8_BAR; PG8_SCHED;
;       PG8_LDB(B1, 1, 1); PG8_STAGE(PG8_SB(1, 0), b3, voffB);
	v_mfma_f32_16x16x32_bf16 v[52:55], v[208:211], v[154:157], v[52:55]
	v_mfma_f32_16x16x32_bf16 v[48:51], v[232:235], v[154:157], v[48:51]
	v_mfma_f32_16x16x32_bf16 v[36:39], v[208:211], v[184:187], v[36:39]
	v_mfma_f32_16x16x32_bf16 v[32:35], v[232:235], v[184:187], v[32:35]
	v_mfma_f32_16x16x32_bf16 v[20:23], v[208:211], v[192:195], v[20:23]
	v_mfma_f32_16x16x32_bf16 v[16:19], v[232:235], v[192:195], v[16:19]
	v_mfma_f32_16x16x32_bf16 v[4:7], v[208:211], v[200:203], v[4:7]
	v_mfma_f32_16x16x32_bf16 v[0:3], v[232:235], v[200:203], v[0:3]
	v_mfma_f32_16x16x32_bf16 v[52:55], v[226:229], v[180:183], v[52:55]
	v_mfma_f32_16x16x32_bf16 v[48:51], v[236:239], v[180:183], v[48:51]
	v_mfma_f32_16x16x32_bf16 v[36:39], v[226:229], v[188:191], v[36:39]
	v_mfma_f32_16x16x32_bf16 v[32:35], v[236:239], v[188:191], v[32:35]
	v_mfma_f32_16x16x32_bf16 v[20:23], v[226:229], v[196:199], v[20:23]
	v_mfma_f32_16x16x32_bf16 v[16:19], v[236:239], v[196:199], v[16:19]
	v_mfma_f32_16x16x32_bf16 v[4:7], v[226:229], v[204:207], v[4:7]
	v_mfma_f32_16x16x32_bf16 v[0:3], v[236:239], v[204:207], v[0:3]
	s_add_i32 s73, 0, 0x18000
	v_add_u32_e32 v150, s73, v177
	s_barrier
	ds_read_b128 v[138:141], v150
	ds_read_b128 v[142:145], v150 offset:1024
	ds_read_b128 v[146:149], v150 offset:2048
	ds_read_b128 v[150:153], v150 offset:3072
	s_add_u32 s48, s48, 0x20000
	s_addc_u32 s49, s49, 0
	s_mov_b32 m0, s20
	ds_read_b128 v[154:157], v179 offset:32768
	ds_read_b128 v[180:183], v179 offset:33792
	ds_read_b128 v[184:187], v179 offset:34816
	ds_read_b128 v[188:191], v179 offset:35840
	ds_read_b128 v[192:195], v179 offset:36864
	ds_read_b128 v[196:199], v179 offset:37888
	ds_read_b128 v[200:203], v179 offset:38912
	ds_read_b128 v[204:207], v179 offset:39936
	global_load_lds_dwordx4 v132, s[48:49]
	s_mov_b32 m0, s51
	s_nop 0
	global_load_lds_dwordx4 v130, s[48:49]
	s_waitcnt lgkmcnt(8)
	s_barrier
	s_waitcnt lgkmcnt(0)
	s_waitcnt lgkmcnt(0)
	v_mfma_f32_16x16x32_bf16 v[124:127], v[138:141], v[154:157], v[124:127]
	v_mfma_f32_16x16x32_bf16 v[120:123], v[146:149], v[154:157], v[120:123]
	v_mfma_f32_16x16x32_bf16 v[108:111], v[138:141], v[184:187], v[108:111]
	v_mfma_f32_16x16x32_bf16 v[104:107], v[146:149], v[184:187], v[104:107]
	v_mfma_f32_16x16x32_bf16 v[92:95], v[138:141], v[192:195], v[92:95]
	v_mfma_f32_16x16x32_bf16 v[88:91], v[146:149], v[192:195], v[88:91]
	v_mfma_f32_16x16x32_bf16 v[76:79], v[138:141], v[200:203], v[76:79]
	v_mfma_f32_16x16x32_bf16 v[72:75], v[146:149], v[200:203], v[72:75]
	v_mfma_f32_16x16x32_bf16 v[124:127], v[142:145], v[180:183], v[124:127]
	v_mfma_f32_16x16x32_bf16 v[120:123], v[150:153], v[180:183], v[120:123]
	v_mfma_f32_16x16x32_bf16 v[108:111], v[142:145], v[188:191], v[108:111]
	v_mfma_f32_16x16x32_bf16 v[104:107], v[150:153], v[188:191], v[104:107]
	v_mfma_f32_16x16x32_bf16 v[92:95], v[142:145], v[196:199], v[92:95]
	v_mfma_f32_16x16x32_bf16 v[88:91], v[150:153], v[196:199], v[88:91]
	v_mfma_f32_16x16x32_bf16 v[76:79], v[142:145], v[204:207], v[76:79]
	v_mfma_f32_16x16x32_bf16 v[72:75], v[150:153], v[204:207], v[72:75]
	s_barrier
	s_add_i32 s48, 0, 0x1c000
	s_add_i32 s49, s73, s7
	v_add_u32_e32 v225, s48, v177
	s_add_u32 s98, s44, s80
	s_addc_u32 s99, s45, s81
	s_mov_b32 m0, s49
	ds_read_b128 v[208:211], v225
	ds_read_b128 v[226:229], v225 offset:1024
	ds_read_b128 v[232:235], v225 offset:2048
	ds_read_b128 v[236:239], v225 offset:3072
	global_load_lds_dwordx4 v160, s[98:99]
	s_add_i32 m0, s49, 0x2000
	s_nop 0
	global_load_lds_dwordx4 v128, s[98:99]
	s_barrier
; #define PG8_STAGE(bufoff, gbase, voff) do { _Pragma("unroll") for (int _i = 0; _i < 2; ++_i) \
;     __builtin_amdgcn_global_load_lds((const unsigned*)((const char*)(gbase) + (voff)[_i]), (LAS unsigned*)(lds + (bufoff) + ldsw + _i * 8192), 16, 0, 0); } while (0)
; #define PG8_LDA(dst, b, h) do { _Pragma("unroll") for (int m = 0; m < 4; ++m) _Pragma("unroll") for (int k = 0; k < 2; ++k) dst[m][k] = *(const LAS bf16x8*)(lds + PG8_SA(b, h) + aoff + m * 2048 + k * 1024); } while (0)
; #define PG8_MMA(ai, bj, At, Bt) do { __builtin_amdgcn_s_setprio(1); _Pragma("unroll") for (int m = 0; m < 4; ++m) _Pragma("unroll") for (int n = 0; n < 2; ++n) _Pragma("unroll") for (int k = 0; k < 2; ++k) \
;     acc[ai][bj][m][n] = __builtin_amdgcn_mfma_f32_16x16x32_bf16(Bt[n][k], At[m][k], acc[ai][bj][m][n], 0, 0, 0); __builtin_amdgcn_s_setprio(0); } while (0)
; #define PG8_WAIT_V(n) asm volatile("s_waitcnt vmcnt(" #n ")" ::: "memory")
; #define PG8_WAIT_L(n) asm volatile("s_waitcnt lgkmcnt(" #n ")" ::: "memory")
; #define PG8_BAR __builtin_amdgcn_s_barrier()
; #define PG8_SCHED __builtin_amdgcn_sched_barrier(0)
; template <class Epi, class Sched>
; __device__ __forceinline__ void gemm_phase(LAS unsigned char* lds, const Gemm g, const Sched& S, const Epi& E) {
;     ...
;       PG8_BAR; PG8_WAIT_L(0); PG8_MMA(0, 1, At, B1); PG8_BAR;
;       PG8_LDA(At, 1, 1); PG8_STAGE(PG8_SA(1, 0), a3, voffA);
;       PG8_BAR; PG8_WAIT_L(0); PG8_MMA(1, 0, At, B0); PG8_BAR; PG8_SCHED;
;       PG8_STAGE(PG8_SB(1, 1), b3 + hstep, voffB);
;       PG8_WAIT_V(6); PG8_BAR; PG8_MMA(1, 1, At, B1); PG8_BAR;
	s_waitcnt lgkmcnt(0)
	s_waitcnt lgkmcnt(0)
	v_mfma_f32_16x16x32_bf16 v[116:119], v[208:211], v[154:157], v[116:119]
	v_mfma_f32_16x16x32_bf16 v[112:115], v[232:235], v[154:157], v[112:115]
	v_mfma_f32_16x16x32_bf16 v[100:103], v[208:211], v[184:187], v[100:103]
	v_mfma_f32_16x16x32_bf16 v[96:99], v[232:235], v[184:187], v[96:99]
	v_mfma_f32_16x16x32_bf16 v[84:87], v[208:211], v[192:195], v[84:87]
	v_mfma_f32_16x16x32_bf16 v[80:83], v[232:235], v[192:195], v[80:83]
	v_mfma_f32_16x16x32_bf16 v[68:71], v[208:211], v[200:203], v[68:71]
	v_mfma_f32_16x16x32_bf16 v[64:67], v[232:235], v[200:203], v[64:67]
	v_mfma_f32_16x16x32_bf16 v[116:119], v[226:229], v[180:183], v[116:119]
	v_mfma_f32_16x16x32_bf16 v[112:115], v[236:239], v[180:183], v[112:115]
	v_mfma_f32_16x16x32_bf16 v[100:103], v[226:229], v[188:191], v[100:103]
	v_mfma_f32_16x16x32_bf16 v[96:99], v[236:239], v[188:191], v[96:99]
	v_mfma_f32_16x16x32_bf16 v[84:87], v[226:229], v[196:199], v[84:87]
	v_mfma_f32_16x16x32_bf16 v[80:83], v[236:239], v[196:199], v[80:83]
	v_mfma_f32_16x16x32_bf16 v[68:71], v[226:229], v[204:207], v[68:71]
	v_mfma_f32_16x16x32_bf16 v[64:67], v[236:239], v[204:207], v[64:67]
	s_mov_b32 m0, s62
	v_lshl_add_u64 v[158:159], v[212:213], 0, s[80:81]
	s_barrier
	ds_read_b128 v[154:157], v179 offset:49152
	ds_read_b128 v[180:183], v179 offset:50176
	ds_read_b128 v[184:187], v179 offset:51200
	ds_read_b128 v[188:191], v179 offset:52224
	ds_read_b128 v[192:195], v179 offset:53248
	ds_read_b128 v[196:199], v179 offset:54272
	ds_read_b128 v[200:203], v179 offset:55296
	ds_read_b128 v[204:207], v179 offset:56320
	global_load_lds_dwordx4 v[158:159], off
	v_lshl_add_u64 v[158:159], v[222:223], 0, s[80:81]
	s_mov_b32 m0, s63
	s_nop 0
	global_load_lds_dwordx4 v[158:159], off
	s_barrier
	s_waitcnt lgkmcnt(0)
	s_waitcnt lgkmcnt(0)
	v_mfma_f32_16x16x32_bf16 v[60:63], v[138:141], v[154:157], v[60:63]
	v_mfma_f32_16x16x32_bf16 v[56:59], v[146:149], v[154:157], v[56:59]
	v_mfma_f32_16x16x32_bf16 v[44:47], v[138:141], v[184:187], v[44:47]
	v_mfma_f32_16x16x32_bf16 v[40:43], v[146:149], v[184:187], v[40:43]
	v_mfma_f32_16x16x32_bf16 v[28:31], v[138:141], v[192:195], v[28:31]
	v_mfma_f32_16x16x32_bf16 v[24:27], v[146:149], v[192:195], v[24:27]
	v_mfma_f32_16x16x32_bf16 v[12:15], v[138:141], v[200:203], v[12:15]
	v_mfma_f32_16x16x32_bf16 v[8:11], v[146:149], v[200:203], v[8:11]
	v_mfma_f32_16x16x32_bf16 v[60:63], v[142:145], v[180:183], v[60:63]
	v_mfma_f32_16x16x32_bf16 v[56:59], v[150:153], v[180:183], v[56:59]
	v_mfma_f32_16x16x32_bf16 v[44:47], v[142:145], v[188:191], v[44:47]
	v_mfma_f32_16x16x32_bf16 v[40:43], v[150:153], v[188:191], v[40:43]
	v_mfma_f32_16x16x32_bf16 v[28:31], v[142:145], v[196:199], v[28:31]
	v_mfma_f32_16x16x32_bf16 v[24:27], v[150:153], v[196:199], v[24:27]
	v_mfma_f32_16x16x32_bf16 v[12:15], v[142:145], v[204:207], v[12:15]
	v_mfma_f32_16x16x32_bf16 v[8:11], v[150:153], v[204:207], v[8:11]
	s_barrier
	s_add_u32 s44, s44, 0x20080
	s_addc_u32 s45, s45, 0
	s_add_i32 s48, s48, s7
	s_mov_b32 m0, s48
	s_nop 0
	global_load_lds_dwordx4 v160, s[44:45]
	s_add_i32 m0, s48, 0x2000
	s_nop 0
	global_load_lds_dwordx4 v128, s[44:45]
	s_waitcnt vmcnt(6)
	s_barrier
	v_mfma_f32_16x16x32_bf16 v[52:55], v[208:211], v[154:157], v[52:55]
	v_mfma_f32_16x16x32_bf16 v[48:51], v[232:235], v[154:157], v[48:51]
	v_mfma_f32_16x16x32_bf16 v[36:39], v[208:211], v[184:187], v[36:39]
	v_mfma_f32_16x16x32_bf16 v[32:35], v[232:235], v[184:187], v[32:35]
	v_mfma_f32_16x16x32_bf16 v[20:23], v[208:211], v[192:195], v[20:23]
	v_mfma_f32_16x16x32_bf16 v[16:19], v[232:235], v[192:195], v[16:19]
	v_mfma_f32_16x16x32_bf16 v[4:7], v[208:211], v[200:203], v[4:7]
	v_mfma_f32_16x16x32_bf16 v[0:3], v[232:235], v[200:203], v[0:3]
	v_mfma_f32_16x16x32_bf16 v[52:55], v[226:229], v[180:183], v[52:55]
	v_mfma_f32_16x16x32_bf16 v[48:51], v[236:239], v[180:183], v[48:51]
	v_mfma_f32_16x16x32_bf16 v[36:39], v[226:229], v[188:191], v[36:39]
	v_mfma_f32_16x16x32_bf16 v[32:35], v[236:239], v[188:191], v[32:35]
	v_mfma_f32_16x16x32_bf16 v[20:23], v[226:229], v[196:199], v[20:23]
	v_mfma_f32_16x16x32_bf16 v[16:19], v[236:239], v[196:199], v[16:19]
	v_mfma_f32_16x16x32_bf16 v[4:7], v[226:229], v[204:207], v[4:7]
	v_mfma_f32_16x16x32_bf16 v[0:3], v[236:239], v[204:207], v[0:3]
	s_add_i32 s72, s72, 2
	s_add_u32 s34, s34, 0x100
	s_addc_u32 s35, s35, 0
	s_add_u32 s71, s71, 0x100
	s_addc_u32 s52, s52, 0
	s_cmp_gt_u32 s72, 5
	s_barrier
	s_cbranch_scc0 .LBB0_778
	s_cmp_lt_u32 s101, 0x100
	s_cbranch_scc0 .Lxa_4
	s_barrier

; #define PG8_STAGE(bufoff, gbase, voff) do { _Pragma("unroll") for (int _i = 0; _i < 2; ++_i) \
;     __builtin_amdgcn_global_load_lds((const unsigned*)((const char*)(gbase) + (voff)[_i]), (LAS unsigned*)(lds + (bufoff) + ldsw + _i * 8192), 16, 0, 0); } while (0)
; #define PG8_LDA(dst, b, h) do { _Pragma("unroll") for (int m = 0; m < 4; ++m) _Pragma("unroll") for (int k = 0; k < 2; ++k) dst[m][k] = *(const LAS bf16x8*)(lds + PG8_SA(b, h) + aoff + m * 2048 + k * 1024); } while (0)
; #define PG8_LDB(dst, b, h) do { _Pragma("unroll") for (int n = 0; n < 2; ++n) _Pragma("unroll") for (int k = 0; k < 2; ++k) dst[n][k] = *(const LAS bf16x8*)(lds + PG8_SB(b, h) + boff + n * 2048 + k * 1024); } while (0)
; #define PG8_MMA(ai, bj, At, Bt) do { __builtin_amdgcn_s_setprio(1); _Pragma("unroll") for (int m = 0; m < 4; ++m) _Pragma("unroll") for (int n = 0; n < 2; ++n) _Pragma("unroll") for (int k = 0; k < 2; ++k) \
;     acc[ai][bj][m][n] = __builtin_amdgcn_mfma_f32_16x16x32_bf16(Bt[n][k], At[m][k], acc[ai][bj][m][n], 0, 0, 0); __builtin_amdgcn_s_setprio(0); } while (0)
; #define PG8_WAIT_V(n) asm volatile("s_waitcnt vmcnt(" #n ")" ::: "memory")
; #define PG8_WAIT_L(n) asm volatile("s_waitcnt lgkmcnt(" #n ")" ::: "memory")
; #define PG8_BAR __builtin_amdgcn_s_barrier()
; #define PG8_SCHED __builtin_amdgcn_sched_barrier(0)
; template <class Epi, class Sched>
; __device__ __forceinline__ void gemm_phase(LAS unsigned char* lds, const Gemm g, const Sched& S, const Epi& E) {
;     ...
;       PG8_LDB(B0, 0, 0); PG8_SCHED; PG8_LDA(At, 0, 0); PG8_STAGE(PG8_SA(1, 1), a1 + hstep, voffA);
;       PG8_WAIT_L(8); PG8_BAR; PG8_WAIT_L(0); PG8_MMA(0, 0, At, B0); PG8_BAR; PG8_SCHED;
;       PG8_LDB(B1, 0, 1); PG8_STAGE(PG8_SB(0, 0), b2, voffB);
;       PG8_BAR; PG8_WAIT_L(0); PG8_MMA(0, 1, At, B1); PG8_BAR;
;       PG8_LDA(At, 0, 1); PG8_STAGE(PG8_SA(0, 0), a2, voffA);
;       PG8_BAR; PG8_WAIT_L(0); PG8_MMA(1, 0, At, B0); PG8_BAR; PG8_SCHED;
;       PG8_STAGE(PG8_SB(0, 1), b2 + hstep, voffB);
;       PG8_WAIT_V(6); PG8_BAR; PG8_MMA(1, 1, At, B1); PG8_BAR;
.Lxs_e5:
.LBB0_794:
	s_add_u32 s44, s34, 0xfffc0080
	s_addc_u32 s45, s35, -1
	s_add_i32 s73, 0, 0x10000
	v_add_u32_e32 v140, s73, v226
	ds_read_b128 v[128:131], v140
	ds_read_b128 v[132:135], v140 offset:1024
	ds_read_b128 v[136:139], v140 offset:2048
	ds_read_b128 v[140:143], v140 offset:3072
	s_cmp_eq_u32 s72, 12
	s_cselect_b32 s49, s37, s45
	s_cselect_b32 s48, s69, s44
	s_cselect_b32 s45, s23, s52
	s_cselect_b32 s44, s70, s71
	s_add_i32 m0, s12, 0xc000
	ds_read_b128 v[144:147], v228
	ds_read_b128 v[148:151], v228 offset:1024
	ds_read_b128 v[152:155], v228 offset:2048
	ds_read_b128 v[156:159], v228 offset:3072
	ds_read_b128 v[184:187], v228 offset:4096
	ds_read_b128 v[188:191], v228 offset:5120
	ds_read_b128 v[192:195], v228 offset:6144
	ds_read_b128 v[196:199], v228 offset:7168
	global_load_lds_dwordx4 v180, s[34:35]
	s_add_i32 m0, s12, 0xe000
	s_nop 0
	global_load_lds_dwordx4 v182, s[34:35]
	s_waitcnt lgkmcnt(8)
	s_barrier
	s_waitcnt lgkmcnt(0)
	s_waitcnt lgkmcnt(0)
	v_mfma_f32_16x16x32_bf16 v[124:127], v[128:131], v[144:147], v[124:127]
	v_mfma_f32_16x16x32_bf16 v[120:123], v[136:139], v[144:147], v[120:123]
	v_mfma_f32_16x16x32_bf16 v[108:111], v[128:131], v[152:155], v[108:111]
	v_mfma_f32_16x16x32_bf16 v[104:107], v[136:139], v[152:155], v[104:107]
	v_mfma_f32_16x16x32_bf16 v[92:95], v[128:131], v[184:187], v[92:95]
	v_mfma_f32_16x16x32_bf16 v[88:91], v[136:139], v[184:187], v[88:91]
	v_mfma_f32_16x16x32_bf16 v[76:79], v[128:131], v[192:195], v[76:79]
	v_mfma_f32_16x16x32_bf16 v[72:75], v[136:139], v[192:195], v[72:75]
	v_mfma_f32_16x16x32_bf16 v[124:127], v[132:135], v[148:151], v[124:127]
	v_mfma_f32_16x16x32_bf16 v[120:123], v[140:143], v[148:151], v[120:123]
	v_mfma_f32_16x16x32_bf16 v[108:111], v[132:135], v[156:159], v[108:111]
	v_mfma_f32_16x16x32_bf16 v[104:107], v[140:143], v[156:159], v[104:107]
	v_mfma_f32_16x16x32_bf16 v[92:95], v[132:135], v[188:191], v[92:95]
	v_mfma_f32_16x16x32_bf16 v[88:91], v[140:143], v[188:191], v[88:91]
	v_mfma_f32_16x16x32_bf16 v[76:79], v[132:135], v[196:199], v[76:79]
	v_mfma_f32_16x16x32_bf16 v[72:75], v[140:143], v[196:199], v[72:75]
	s_barrier
	s_add_i32 s76, 0, 0x14000
	v_add_u32_e32 v212, s76, v226
	s_add_i32 s73, s73, s7
	ds_read_b128 v[200:203], v212
	ds_read_b128 v[204:207], v212 offset:1024
	ds_read_b128 v[208:211], v212 offset:2048
	ds_read_b128 v[232:235], v212 offset:3072
	s_mov_b32 m0, s73
	s_nop 0
	global_load_lds_dwordx4 v160, s[44:45]
	s_add_i32 m0, s73, 0x2000
	s_nop 0
	global_load_lds_dwordx4 v174, s[44:45]
	s_barrier
	s_waitcnt lgkmcnt(0)
	s_waitcnt lgkmcnt(0)
	v_mfma_f32_16x16x32_bf16 v[116:119], v[200:203], v[144:147], v[116:119]
	v_mfma_f32_16x16x32_bf16 v[112:115], v[208:211], v[144:147], v[112:115]
	v_mfma_f32_16x16x32_bf16 v[100:103], v[200:203], v[152:155], v[100:103]
	v_mfma_f32_16x16x32_bf16 v[96:99], v[208:211], v[152:155], v[96:99]
	v_mfma_f32_16x16x32_bf16 v[84:87], v[200:203], v[184:187], v[84:87]
	v_mfma_f32_16x16x32_bf16 v[80:83], v[208:211], v[184:187], v[80:83]
	v_mfma_f32_16x16x32_bf16 v[68:71], v[200:203], v[192:195], v[68:71]
	v_mfma_f32_16x16x32_bf16 v[64:67], v[208:211], v[192:195], v[64:67]
	v_mfma_f32_16x16x32_bf16 v[116:119], v[204:207], v[148:151], v[116:119]
	v_mfma_f32_16x16x32_bf16 v[112:115], v[232:235], v[148:151], v[112:115]
	v_mfma_f32_16x16x32_bf16 v[100:103], v[204:207], v[156:159], v[100:103]
	v_mfma_f32_16x16x32_bf16 v[96:99], v[232:235], v[156:159], v[96:99]
	v_mfma_f32_16x16x32_bf16 v[84:87], v[204:207], v[188:191], v[84:87]
	v_mfma_f32_16x16x32_bf16 v[80:83], v[232:235], v[188:191], v[80:83]
	v_mfma_f32_16x16x32_bf16 v[68:71], v[204:207], v[196:199], v[68:71]
	v_mfma_f32_16x16x32_bf16 v[64:67], v[232:235], v[196:199], v[64:67]
	s_mov_b32 m0, s12
	v_lshl_add_u64 v[236:237], s[48:49], 0, v[178:179]
	s_barrier
	ds_read_b128 v[144:147], v228 offset:16384
	ds_read_b128 v[148:151], v228 offset:17408
	ds_read_b128 v[152:155], v228 offset:18432
	ds_read_b128 v[156:159], v228 offset:19456
	ds_read_b128 v[184:187], v228 offset:20480
	ds_read_b128 v[188:191], v228 offset:21504
	ds_read_b128 v[192:195], v228 offset:22528
	ds_read_b128 v[196:199], v228 offset:23552
	global_load_lds_dwordx4 v178, s[48:49]
	v_lshl_add_u64 v[238:239], s[48:49], 0, v[176:177]
	s_mov_b32 m0, s13
	s_nop 0
	global_load_lds_dwordx4 v176, s[48:49]
	s_barrier
	s_waitcnt lgkmcnt(0)
	s_waitcnt lgkmcnt(0)
	v_mfma_f32_16x16x32_bf16 v[60:63], v[128:131], v[144:147], v[60:63]
	v_mfma_f32_16x16x32_bf16 v[56:59], v[136:139], v[144:147], v[56:59]
	v_mfma_f32_16x16x32_bf16 v[44:47], v[128:131], v[152:155], v[44:47]
	v_mfma_f32_16x16x32_bf16 v[40:43], v[136:139], v[152:155], v[40:43]
	v_mfma_f32_16x16x32_bf16 v[28:31], v[128:131], v[184:187], v[28:31]
	v_mfma_f32_16x16x32_bf16 v[24:27], v[136:139], v[184:187], v[24:27]
	v_mfma_f32_16x16x32_bf16 v[12:15], v[128:131], v[192:195], v[12:15]
	v_mfma_f32_16x16x32_bf16 v[8:11], v[136:139], v[192:195], v[8:11]
	v_mfma_f32_16x16x32_bf16 v[60:63], v[132:135], v[148:151], v[60:63]
	v_mfma_f32_16x16x32_bf16 v[56:59], v[140:143], v[148:151], v[56:59]
	v_mfma_f32_16x16x32_bf16 v[44:47], v[132:135], v[156:159], v[44:47]
	v_mfma_f32_16x16x32_bf16 v[40:43], v[140:143], v[156:159], v[40:43]
	v_mfma_f32_16x16x32_bf16 v[28:31], v[132:135], v[188:191], v[28:31]
	v_mfma_f32_16x16x32_bf16 v[24:27], v[140:143], v[188:191], v[24:27]
	v_mfma_f32_16x16x32_bf16 v[12:15], v[132:135], v[196:199], v[12:15]
	v_mfma_f32_16x16x32_bf16 v[8:11], v[140:143], v[196:199], v[8:11]
	s_barrier
	s_add_u32 s74, s44, 0x40000
	s_addc_u32 s75, s45, 0
	s_add_i32 s73, s76, s7
	s_mov_b32 m0, s73
	s_nop 0
	global_load_lds_dwordx4 v160, s[74:75]
	s_add_i32 m0, s73, 0x2000
	s_nop 0
	global_load_lds_dwordx4 v174, s[74:75]
	s_waitcnt vmcnt(6)
	s_barrier
; #define PG8_STAGE(bufoff, gbase, voff) do { _Pragma("unroll") for (int _i = 0; _i < 2; ++_i) \
;     __builtin_amdgcn_global_load_lds((const unsigned*)((const char*)(gbase) + (voff)[_i]), (LAS unsigned*)(lds + (bufoff) + ldsw + _i * 8192), 16, 0, 0); } while (0)
; #define PG8_LDA(dst, b, h) do { _Pragma("unroll") for (int m = 0; m < 4; ++m) _Pragma("unroll") for (int k = 0; k < 2; ++k) dst[m][k] = *(const LAS bf16x8*)(lds + PG8_SA(b, h) + aoff + m * 2048 + k * 1024); } while (0)
; #define PG8_LDB(dst, b, h) do { _Pragma("unroll") for (int n = 0; n < 2; ++n) _Pragma("unroll") for (int k = 0; k < 2; ++k) dst[n][k] = *(const LAS bf16x8*)(lds + PG8_SB(b, h) + boff + n * 2048 + k * 1024); } while (0)
; #define PG8_MMA(ai, bj, At, Bt) do { __builtin_amdgcn_s_setprio(1); _Pragma("unroll") for (int m = 0; m < 4; ++m) _Pragma("unroll") for (int n = 0; n < 2; ++n) _Pragma("unroll") for (int k = 0; k < 2; ++k) \
;     acc[ai][bj][m][n] = __builtin_amdgcn_mfma_f32_16x16x32_bf16(Bt[n][k], At[m][k], acc[ai][bj][m][n], 0, 0, 0); __builtin_amdgcn_s_setprio(0); } while (0)
; #define PG8_WAIT_V(n) asm volatile("s_waitcnt vmcnt(" #n ")" ::: "memory")
; #define PG8_WAIT_L(n) asm volatile("s_waitcnt lgkmcnt(" #n ")" ::: "memory")
; #define PG8_BAR __builtin_amdgcn_s_barrier()
; #define PG8_SCHED __builtin_amdgcn_sched_barrier(0)
; template <class Epi, class Sched>
; __device__ __forceinline__ void gemm_phase(LAS unsigned char* lds, const Gemm g, const Sched& S, const Epi& E) {
;     ...
;       PG8_WAIT_V(6); PG8_BAR; PG8_MMA(1, 1, At, B1); PG8_BAR;
;       PG8_LDB(B0, 1, 0); PG8_SCHED; PG8_LDA(At, 1, 0); PG8_STAGE(PG8_SA(0, 1), a2 + hstep, voffA);
;       PG8_WAIT_L(8); PG8_BAR; PG8_WAIT_L(0); PG8_MMA(0, 0, At, B0); PG8_BAR; PG8_SCHED;
;       PG8_LDB(B1, 1, 1); PG8_STAGE(PG8_SB(1, 0), b3, voffB);
	v_mfma_f32_16x16x32_bf16 v[52:55], v[200:203], v[144:147], v[52:55]
	v_mfma_f32_16x16x32_bf16 v[48:51], v[208:211], v[144:147], v[48:51]
	v_mfma_f32_16x16x32_bf16 v[36:39], v[200:203], v[152:155], v[36:39]
	v_mfma_f32_16x16x32_bf16 v[32:35], v[208:211], v[152:155], v[32:35]
	v_mfma_f32_16x16x32_bf16 v[20:23], v[200:203], v[184:187], v[20:23]
	v_mfma_f32_16x16x32_bf16 v[16:19], v[208:211], v[184:187], v[16:19]
	v_mfma_f32_16x16x32_bf16 v[4:7], v[200:203], v[192:195], v[4:7]
	v_mfma_f32_16x16x32_bf16 v[0:3], v[208:211], v[192:195], v[0:3]
	v_mfma_f32_16x16x32_bf16 v[52:55], v[204:207], v[148:151], v[52:55]
	v_mfma_f32_16x16x32_bf16 v[48:51], v[232:235], v[148:151], v[48:51]
	v_mfma_f32_16x16x32_bf16 v[36:39], v[204:207], v[156:159], v[36:39]
	v_mfma_f32_16x16x32_bf16 v[32:35], v[232:235], v[156:159], v[32:35]
	v_mfma_f32_16x16x32_bf16 v[20:23], v[204:207], v[188:191], v[20:23]
	v_mfma_f32_16x16x32_bf16 v[16:19], v[232:235], v[188:191], v[16:19]
	v_mfma_f32_16x16x32_bf16 v[4:7], v[204:207], v[196:199], v[4:7]
	v_mfma_f32_16x16x32_bf16 v[0:3], v[232:235], v[196:199], v[0:3]
	s_add_i32 s73, 0, 0x18000
	v_add_u32_e32 v140, s73, v226
	s_barrier
	ds_read_b128 v[128:131], v140
	ds_read_b128 v[132:135], v140 offset:1024
	ds_read_b128 v[136:139], v140 offset:2048
	ds_read_b128 v[140:143], v140 offset:3072
	s_add_u32 s48, s48, 0x40000
	s_addc_u32 s49, s49, 0
	s_mov_b32 m0, s20
	ds_read_b128 v[144:147], v228 offset:32768
	ds_read_b128 v[148:151], v228 offset:33792
	ds_read_b128 v[152:155], v228 offset:34816
	ds_read_b128 v[156:159], v228 offset:35840
	ds_read_b128 v[184:187], v228 offset:36864
	ds_read_b128 v[188:191], v228 offset:37888
	ds_read_b128 v[192:195], v228 offset:38912
	ds_read_b128 v[196:199], v228 offset:39936
	global_load_lds_dwordx4 v178, s[48:49]
	s_mov_b32 m0, s51
	s_nop 0
	global_load_lds_dwordx4 v176, s[48:49]
	s_waitcnt lgkmcnt(8)
	s_barrier
	s_waitcnt lgkmcnt(0)
	s_waitcnt lgkmcnt(0)
	v_mfma_f32_16x16x32_bf16 v[124:127], v[128:131], v[144:147], v[124:127]
	v_mfma_f32_16x16x32_bf16 v[120:123], v[136:139], v[144:147], v[120:123]
	v_mfma_f32_16x16x32_bf16 v[108:111], v[128:131], v[152:155], v[108:111]
	v_mfma_f32_16x16x32_bf16 v[104:107], v[136:139], v[152:155], v[104:107]
	v_mfma_f32_16x16x32_bf16 v[92:95], v[128:131], v[184:187], v[92:95]
	v_mfma_f32_16x16x32_bf16 v[88:91], v[136:139], v[184:187], v[88:91]
	v_mfma_f32_16x16x32_bf16 v[76:79], v[128:131], v[192:195], v[76:79]
	v_mfma_f32_16x16x32_bf16 v[72:75], v[136:139], v[192:195], v[72:75]
	v_mfma_f32_16x16x32_bf16 v[124:127], v[132:135], v[148:151], v[124:127]
	v_mfma_f32_16x16x32_bf16 v[120:123], v[140:143], v[148:151], v[120:123]
	v_mfma_f32_16x16x32_bf16 v[108:111], v[132:135], v[156:159], v[108:111]
	v_mfma_f32_16x16x32_bf16 v[104:107], v[140:143], v[156:159], v[104:107]
	v_mfma_f32_16x16x32_bf16 v[92:95], v[132:135], v[188:191], v[92:95]
	v_mfma_f32_16x16x32_bf16 v[88:91], v[140:143], v[188:191], v[88:91]
	v_mfma_f32_16x16x32_bf16 v[76:79], v[132:135], v[196:199], v[76:79]
	v_mfma_f32_16x16x32_bf16 v[72:75], v[140:143], v[196:199], v[72:75]
	s_barrier
	s_add_i32 s48, 0, 0x1c000
	s_add_i32 s49, s73, s7
	v_add_u32_e32 v229, s48, v226
	s_add_u32 s98, s44, s80
	s_addc_u32 s99, s45, s81
	s_mov_b32 m0, s49
	ds_read_b128 v[200:203], v229
	ds_read_b128 v[204:207], v229 offset:1024
	ds_read_b128 v[208:211], v229 offset:2048
	ds_read_b128 v[232:235], v229 offset:3072
	global_load_lds_dwordx4 v160, s[98:99]
	s_add_i32 m0, s49, 0x2000
	s_nop 0
	global_load_lds_dwordx4 v174, s[98:99]
	s_barrier
; #define PG8_STAGE(bufoff, gbase, voff) do { _Pragma("unroll") for (int _i = 0; _i < 2; ++_i) \
;     __builtin_amdgcn_global_load_lds((const unsigned*)((const char*)(gbase) + (voff)[_i]), (LAS unsigned*)(lds + (bufoff) + ldsw + _i * 8192), 16, 0, 0); } while (0)
; #define PG8_LDA(dst, b, h) do { _Pragma("unroll") for (int m = 0; m < 4; ++m) _Pragma("unroll") for (int k = 0; k < 2; ++k) dst[m][k] = *(const LAS bf16x8*)(lds + PG8_SA(b, h) + aoff + m * 2048 + k * 1024); } while (0)
; #define PG8_MMA(ai, bj, At, Bt) do { __builtin_amdgcn_s_setprio(1); _Pragma("unroll") for (int m = 0; m < 4; ++m) _Pragma("unroll") for (int n = 0; n < 2; ++n) _Pragma("unroll") for (int k = 0; k < 2; ++k) \
;     acc[ai][bj][m][n] = __builtin_amdgcn_mfma_f32_16x16x32_bf16(Bt[n][k], At[m][k], acc[ai][bj][m][n], 0, 0, 0); __builtin_amdgcn_s_setprio(0); } while (0)
; #define PG8_WAIT_V(n) asm volatile("s_waitcnt vmcnt(" #n ")" ::: "memory")
; #define PG8_WAIT_L(n) asm volatile("s_waitcnt lgkmcnt(" #n ")" ::: "memory")
; #define PG8_BAR __builtin_amdgcn_s_barrier()
; #define PG8_SCHED __builtin_amdgcn_sched_barrier(0)
; template <class Epi, class Sched>
; __device__ __forceinline__ void gemm_phase(LAS unsigned char* lds, const Gemm g, const Sched& S, const Epi& E) {
;     ...
;       PG8_BAR; PG8_WAIT_L(0); PG8_MMA(0, 1, At, B1); PG8_BAR;
;       PG8_LDA(At, 1, 1); PG8_STAGE(PG8_SA(1, 0), a3, voffA);
;       PG8_BAR; PG8_WAIT_L(0); PG8_MMA(1, 0, At, B0); PG8_BAR; PG8_SCHED;
;       PG8_STAGE(PG8_SB(1, 1), b3 + hstep, voffB);
;       PG8_WAIT_V(6); PG8_BAR; PG8_MMA(1, 1, At, B1); PG8_BAR;
	s_waitcnt lgkmcnt(0)
	s_waitcnt lgkmcnt(0)
	v_mfma_f32_16x16x32_bf16 v[116:119], v[200:203], v[144:147], v[116:119]
	v_mfma_f32_16x16x32_bf16 v[112:115], v[208:211], v[144:147], v[112:115]
	v_mfma_f32_16x16x32_bf16 v[100:103], v[200:203], v[152:155], v[100:103]
	v_mfma_f32_16x16x32_bf16 v[96:99], v[208:211], v[152:155], v[96:99]
	v_mfma_f32_16x16x32_bf16 v[84:87], v[200:203], v[184:187], v[84:87]
	v_mfma_f32_16x16x32_bf16 v[80:83], v[208:211], v[184:187], v[80:83]
	v_mfma_f32_16x16x32_bf16 v[68:71], v[200:203], v[192:195], v[68:71]
	v_mfma_f32_16x16x32_bf16 v[64:67], v[208:211], v[192:195], v[64:67]
	v_mfma_f32_16x16x32_bf16 v[116:119], v[204:207], v[148:151], v[116:119]
	v_mfma_f32_16x16x32_bf16 v[112:115], v[232:235], v[148:151], v[112:115]
	v_mfma_f32_16x16x32_bf16 v[100:103], v[204:207], v[156:159], v[100:103]
	v_mfma_f32_16x16x32_bf16 v[96:99], v[232:235], v[156:159], v[96:99]
	v_mfma_f32_16x16x32_bf16 v[84:87], v[204:207], v[188:191], v[84:87]
	v_mfma_f32_16x16x32_bf16 v[80:83], v[232:235], v[188:191], v[80:83]
	v_mfma_f32_16x16x32_bf16 v[68:71], v[204:207], v[196:199], v[68:71]
	v_mfma_f32_16x16x32_bf16 v[64:67], v[232:235], v[196:199], v[64:67]
	s_mov_b32 m0, s62
	v_lshl_add_u64 v[212:213], v[236:237], 0, s[80:81]
	s_barrier
	ds_read_b128 v[144:147], v228 offset:49152
	ds_read_b128 v[148:151], v228 offset:50176
	ds_read_b128 v[152:155], v228 offset:51200
	ds_read_b128 v[156:159], v228 offset:52224
	ds_read_b128 v[184:187], v228 offset:53248
	ds_read_b128 v[188:191], v228 offset:54272
	ds_read_b128 v[192:195], v228 offset:55296
	ds_read_b128 v[196:199], v228 offset:56320
	global_load_lds_dwordx4 v[212:213], off
	v_lshl_add_u64 v[212:213], v[238:239], 0, s[80:81]
	s_mov_b32 m0, s63
	s_nop 0
	global_load_lds_dwordx4 v[212:213], off
	s_barrier
	s_waitcnt lgkmcnt(0)
	s_waitcnt lgkmcnt(0)
	v_mfma_f32_16x16x32_bf16 v[60:63], v[128:131], v[144:147], v[60:63]
	v_mfma_f32_16x16x32_bf16 v[56:59], v[136:139], v[144:147], v[56:59]
	v_mfma_f32_16x16x32_bf16 v[44:47], v[128:131], v[152:155], v[44:47]
	v_mfma_f32_16x16x32_bf16 v[40:43], v[136:139], v[152:155], v[40:43]
	v_mfma_f32_16x16x32_bf16 v[28:31], v[128:131], v[184:187], v[28:31]
	v_mfma_f32_16x16x32_bf16 v[24:27], v[136:139], v[184:187], v[24:27]
	v_mfma_f32_16x16x32_bf16 v[12:15], v[128:131], v[192:195], v[12:15]
	v_mfma_f32_16x16x32_bf16 v[8:11], v[136:139], v[192:195], v[8:11]
	v_mfma_f32_16x16x32_bf16 v[60:63], v[132:135], v[148:151], v[60:63]
	v_mfma_f32_16x16x32_bf16 v[56:59], v[140:143], v[148:151], v[56:59]
	v_mfma_f32_16x16x32_bf16 v[44:47], v[132:135], v[156:159], v[44:47]
	v_mfma_f32_16x16x32_bf16 v[40:43], v[140:143], v[156:159], v[40:43]
	v_mfma_f32_16x16x32_bf16 v[28:31], v[132:135], v[188:191], v[28:31]
	v_mfma_f32_16x16x32_bf16 v[24:27], v[140:143], v[188:191], v[24:27]
	v_mfma_f32_16x16x32_bf16 v[12:15], v[132:135], v[196:199], v[12:15]
	v_mfma_f32_16x16x32_bf16 v[8:11], v[140:143], v[196:199], v[8:11]
	s_barrier
	s_add_u32 s44, s44, 0x40080
	s_addc_u32 s45, s45, 0
	s_add_i32 s48, s48, s7
	s_mov_b32 m0, s48
	s_nop 0
	global_load_lds_dwordx4 v160, s[44:45]
	s_add_i32 m0, s48, 0x2000
	s_nop 0
	global_load_lds_dwordx4 v174, s[44:45]
	s_waitcnt vmcnt(6)
	s_barrier
	v_mfma_f32_16x16x32_bf16 v[52:55], v[200:203], v[144:147], v[52:55]
	v_mfma_f32_16x16x32_bf16 v[48:51], v[208:211], v[144:147], v[48:51]
	v_mfma_f32_16x16x32_bf16 v[36:39], v[200:203], v[152:155], v[36:39]
	v_mfma_f32_16x16x32_bf16 v[32:35], v[208:211], v[152:155], v[32:35]
	v_mfma_f32_16x16x32_bf16 v[20:23], v[200:203], v[184:187], v[20:23]
	v_mfma_f32_16x16x32_bf16 v[16:19], v[208:211], v[184:187], v[16:19]
	v_mfma_f32_16x16x32_bf16 v[4:7], v[200:203], v[192:195], v[4:7]
	v_mfma_f32_16x16x32_bf16 v[0:3], v[208:211], v[192:195], v[0:3]
	v_mfma_f32_16x16x32_bf16 v[52:55], v[204:207], v[148:151], v[52:55]
	v_mfma_f32_16x16x32_bf16 v[48:51], v[232:235], v[148:151], v[48:51]
	v_mfma_f32_16x16x32_bf16 v[36:39], v[204:207], v[156:159], v[36:39]
	v_mfma_f32_16x16x32_bf16 v[32:35], v[232:235], v[156:159], v[32:35]
	v_mfma_f32_16x16x32_bf16 v[20:23], v[204:207], v[188:191], v[20:23]
	v_mfma_f32_16x16x32_bf16 v[16:19], v[232:235], v[188:191], v[16:19]
	v_mfma_f32_16x16x32_bf16 v[4:7], v[204:207], v[196:199], v[4:7]
	v_mfma_f32_16x16x32_bf16 v[0:3], v[232:235], v[196:199], v[0:3]
	s_add_i32 s72, s72, 2
	s_add_u32 s34, s34, 0x100
	s_addc_u32 s35, s35, 0
	s_add_u32 s71, s71, 0x100
	s_addc_u32 s52, s52, 0
	s_cmp_gt_u32 s72, 13
	s_barrier
	s_cbranch_scc0 .LBB0_794
	s_cmp_lt_u32 s101, 0x100
	s_cbranch_scc0 .Lxa_5
	s_barrier

; #define PG8_STAGE(bufoff, gbase, voff) do { _Pragma("unroll") for (int _i = 0; _i < 2; ++_i) \
;     __builtin_amdgcn_global_load_lds((const unsigned*)((const char*)(gbase) + (voff)[_i]), (LAS unsigned*)(lds + (bufoff) + ldsw + _i * 8192), 16, 0, 0); } while (0)
; #define PG8_LDA(dst, b, h) do { _Pragma("unroll") for (int m = 0; m < 4; ++m) _Pragma("unroll") for (int k = 0; k < 2; ++k) dst[m][k] = *(const LAS bf16x8*)(lds + PG8_SA(b, h) + aoff + m * 2048 + k * 1024); } while (0)
; #define PG8_LDB(dst, b, h) do { _Pragma("unroll") for (int n = 0; n < 2; ++n) _Pragma("unroll") for (int k = 0; k < 2; ++k) dst[n][k] = *(const LAS bf16x8*)(lds + PG8_SB(b, h) + boff + n * 2048 + k * 1024); } while (0)
; #define PG8_MMA(ai, bj, At, Bt) do { __builtin_amdgcn_s_setprio(1); _Pragma("unroll") for (int m = 0; m < 4; ++m) _Pragma("unroll") for (int n = 0; n < 2; ++n) _Pragma("unroll") for (int k = 0; k < 2; ++k) \
;     acc[ai][bj][m][n] = __builtin_amdgcn_mfma_f32_16x16x32_bf16(Bt[n][k], At[m][k], acc[ai][bj][m][n], 0, 0, 0); __builtin_amdgcn_s_setprio(0); } while (0)
; #define PG8_WAIT_V(n) asm volatile("s_waitcnt vmcnt(" #n ")" ::: "memory")
; #define PG8_WAIT_L(n) asm volatile("s_waitcnt lgkmcnt(" #n ")" ::: "memory")
; #define PG8_BAR __builtin_amdgcn_s_barrier()
; #define PG8_SCHED __builtin_amdgcn_sched_barrier(0)
; template <class Epi, class Sched>
; __device__ __forceinline__ void gemm_phase(LAS unsigned char* lds, const Gemm g, const Sched& S, const Epi& E) {
;     ...
;       PG8_LDB(B0, 0, 0); PG8_SCHED; PG8_LDA(At, 0, 0); PG8_STAGE(PG8_SA(1, 1), a1 + hstep, voffA);
;       PG8_WAIT_L(8); PG8_BAR; PG8_WAIT_L(0); PG8_MMA(0, 0, At, B0); PG8_BAR; PG8_SCHED;
;       PG8_LDB(B1, 0, 1); PG8_STAGE(PG8_SB(0, 0), b2, voffB);
;       PG8_BAR; PG8_WAIT_L(0); PG8_MMA(0, 1, At, B1); PG8_BAR;
;       PG8_LDA(At, 0, 1); PG8_STAGE(PG8_SA(0, 0), a2, voffA);
;       PG8_BAR; PG8_WAIT_L(0); PG8_MMA(1, 0, At, B0); PG8_BAR; PG8_SCHED;
;       PG8_STAGE(PG8_SB(0, 1), b2 + hstep, voffB);
;       PG8_WAIT_V(6); PG8_BAR; PG8_MMA(1, 1, At, B1); PG8_BAR;
.Lxs_e6:
.LBB0_863:
	s_add_u32 s48, s34, 0xfffc0080
	s_addc_u32 s49, s35, -1
	s_add_i32 s74, 0, 0x10000
	v_add_u32_e32 v140, s74, v202
	ds_read_b128 v[128:131], v140
	ds_read_b128 v[132:135], v140 offset:1024
	ds_read_b128 v[136:139], v140 offset:2048
	ds_read_b128 v[140:143], v140 offset:3072
	s_cmp_eq_u32 s73, 12
	s_cselect_b32 s49, s37, s49
	s_cselect_b32 s48, s68, s48
	s_cselect_b32 vcc_hi, s23, s72
	s_cselect_b32 vcc_lo, s69, s52
	s_add_i32 m0, s51, 0xc000
	ds_read_b128 v[144:147], v203
	ds_read_b128 v[148:151], v203 offset:1024
	ds_read_b128 v[152:155], v203 offset:2048
	ds_read_b128 v[186:189], v203 offset:3072
	ds_read_b128 v[190:193], v203 offset:4096
	ds_read_b128 v[194:197], v203 offset:5120
	ds_read_b128 v[198:201], v203 offset:6144
	ds_read_b128 v[204:207], v203 offset:7168
	global_load_lds_dwordx4 v182, s[34:35]
	s_add_i32 m0, s51, 0xe000
	s_nop 0
	global_load_lds_dwordx4 v184, s[34:35]
	s_waitcnt lgkmcnt(8)
	s_barrier
	s_waitcnt lgkmcnt(0)
	s_waitcnt lgkmcnt(0)
	v_mfma_f32_16x16x32_bf16 v[124:127], v[128:131], v[144:147], v[124:127]
	v_mfma_f32_16x16x32_bf16 v[120:123], v[136:139], v[144:147], v[120:123]
	v_mfma_f32_16x16x32_bf16 v[108:111], v[128:131], v[152:155], v[108:111]
	v_mfma_f32_16x16x32_bf16 v[104:107], v[136:139], v[152:155], v[104:107]
	v_mfma_f32_16x16x32_bf16 v[92:95], v[128:131], v[190:193], v[92:95]
	v_mfma_f32_16x16x32_bf16 v[88:91], v[136:139], v[190:193], v[88:91]
	v_mfma_f32_16x16x32_bf16 v[76:79], v[128:131], v[198:201], v[76:79]
	v_mfma_f32_16x16x32_bf16 v[72:75], v[136:139], v[198:201], v[72:75]
	v_mfma_f32_16x16x32_bf16 v[124:127], v[132:135], v[148:151], v[124:127]
	v_mfma_f32_16x16x32_bf16 v[120:123], v[140:143], v[148:151], v[120:123]
	v_mfma_f32_16x16x32_bf16 v[108:111], v[132:135], v[186:189], v[108:111]
	v_mfma_f32_16x16x32_bf16 v[104:107], v[140:143], v[186:189], v[104:107]
	v_mfma_f32_16x16x32_bf16 v[92:95], v[132:135], v[194:197], v[92:95]
	v_mfma_f32_16x16x32_bf16 v[88:91], v[140:143], v[194:197], v[88:91]
	v_mfma_f32_16x16x32_bf16 v[76:79], v[132:135], v[204:207], v[76:79]
	v_mfma_f32_16x16x32_bf16 v[72:75], v[140:143], v[204:207], v[72:75]
	s_barrier
	s_add_i32 s76, 0, 0x14000
	s_add_i32 s74, s74, s7
	v_add_u32_e32 v160, s76, v202
	s_mov_b32 m0, s74
	ds_read_b128 v[208:211], v160
	ds_read_b128 v[226:229], v160 offset:1024
	ds_read_b128 v[232:235], v160 offset:2048
	ds_read_b128 v[236:239], v160 offset:3072
	global_load_lds_dwordx4 v174, vcc
	s_add_i32 m0, s74, 0x2000
	s_nop 0
	global_load_lds_dwordx4 v156, vcc
	s_barrier
	s_waitcnt lgkmcnt(0)
	s_waitcnt lgkmcnt(0)
	v_mfma_f32_16x16x32_bf16 v[116:119], v[208:211], v[144:147], v[116:119]
	v_mfma_f32_16x16x32_bf16 v[112:115], v[232:235], v[144:147], v[112:115]
	v_mfma_f32_16x16x32_bf16 v[100:103], v[208:211], v[152:155], v[100:103]
	v_mfma_f32_16x16x32_bf16 v[96:99], v[232:235], v[152:155], v[96:99]
	v_mfma_f32_16x16x32_bf16 v[84:87], v[208:211], v[190:193], v[84:87]
	v_mfma_f32_16x16x32_bf16 v[80:83], v[232:235], v[190:193], v[80:83]
	v_mfma_f32_16x16x32_bf16 v[68:71], v[208:211], v[198:201], v[68:71]
	v_mfma_f32_16x16x32_bf16 v[64:67], v[232:235], v[198:201], v[64:67]
	v_mfma_f32_16x16x32_bf16 v[116:119], v[226:229], v[148:151], v[116:119]
	v_mfma_f32_16x16x32_bf16 v[112:115], v[236:239], v[148:151], v[112:115]
	v_mfma_f32_16x16x32_bf16 v[100:103], v[226:229], v[186:189], v[100:103]
	v_mfma_f32_16x16x32_bf16 v[96:99], v[236:239], v[186:189], v[96:99]
	v_mfma_f32_16x16x32_bf16 v[84:87], v[226:229], v[194:197], v[84:87]
	v_mfma_f32_16x16x32_bf16 v[80:83], v[236:239], v[194:197], v[80:83]
	v_mfma_f32_16x16x32_bf16 v[68:71], v[226:229], v[204:207], v[68:71]
	v_mfma_f32_16x16x32_bf16 v[64:67], v[236:239], v[204:207], v[64:67]
	s_mov_b32 m0, s51
	v_lshl_add_u64 v[240:241], s[48:49], 0, v[176:177]
	s_barrier
	ds_read_b128 v[144:147], v203 offset:16384
	ds_read_b128 v[148:151], v203 offset:17408
	ds_read_b128 v[152:155], v203 offset:18432
	ds_read_b128 v[186:189], v203 offset:19456
	ds_read_b128 v[190:193], v203 offset:20480
	ds_read_b128 v[194:197], v203 offset:21504
	ds_read_b128 v[198:201], v203 offset:22528
	ds_read_b128 v[204:207], v203 offset:23552
	global_load_lds_dwordx4 v176, s[48:49]
	v_lshl_add_u64 v[242:243], s[48:49], 0, v[158:159]
	s_mov_b32 m0, s62
	s_nop 0
	global_load_lds_dwordx4 v158, s[48:49]
	s_barrier
	s_waitcnt lgkmcnt(0)
	s_waitcnt lgkmcnt(0)
	v_mfma_f32_16x16x32_bf16 v[60:63], v[128:131], v[144:147], v[60:63]
	v_mfma_f32_16x16x32_bf16 v[56:59], v[136:139], v[144:147], v[56:59]
	v_mfma_f32_16x16x32_bf16 v[44:47], v[128:131], v[152:155], v[44:47]
	v_mfma_f32_16x16x32_bf16 v[40:43], v[136:139], v[152:155], v[40:43]
	v_mfma_f32_16x16x32_bf16 v[28:31], v[128:131], v[190:193], v[28:31]
	v_mfma_f32_16x16x32_bf16 v[24:27], v[136:139], v[190:193], v[24:27]
	v_mfma_f32_16x16x32_bf16 v[12:15], v[128:131], v[198:201], v[12:15]
	v_mfma_f32_16x16x32_bf16 v[8:11], v[136:139], v[198:201], v[8:11]
	v_mfma_f32_16x16x32_bf16 v[60:63], v[132:135], v[148:151], v[60:63]
	v_mfma_f32_16x16x32_bf16 v[56:59], v[140:143], v[148:151], v[56:59]
	v_mfma_f32_16x16x32_bf16 v[44:47], v[132:135], v[186:189], v[44:47]
	v_mfma_f32_16x16x32_bf16 v[40:43], v[140:143], v[186:189], v[40:43]
	v_mfma_f32_16x16x32_bf16 v[28:31], v[132:135], v[194:197], v[28:31]
	v_mfma_f32_16x16x32_bf16 v[24:27], v[140:143], v[194:197], v[24:27]
	v_mfma_f32_16x16x32_bf16 v[12:15], v[132:135], v[204:207], v[12:15]
	v_mfma_f32_16x16x32_bf16 v[8:11], v[140:143], v[204:207], v[8:11]
	s_barrier
	s_add_u32 s74, vcc_lo, 0x40000
	s_addc_u32 s75, vcc_hi, 0
	s_add_i32 s76, s76, s7
	s_mov_b32 m0, s76
	s_nop 0
	global_load_lds_dwordx4 v174, s[74:75]
	s_add_i32 m0, s76, 0x2000
	s_nop 0
	global_load_lds_dwordx4 v156, s[74:75]
	s_waitcnt vmcnt(6)
	s_barrier
; #define PG8_STAGE(bufoff, gbase, voff) do { _Pragma("unroll") for (int _i = 0; _i < 2; ++_i) \
;     __builtin_amdgcn_global_load_lds((const unsigned*)((const char*)(gbase) + (voff)[_i]), (LAS unsigned*)(lds + (bufoff) + ldsw + _i * 8192), 16, 0, 0); } while (0)
; #define PG8_LDA(dst, b, h) do { _Pragma("unroll") for (int m = 0; m < 4; ++m) _Pragma("unroll") for (int k = 0; k < 2; ++k) dst[m][k] = *(const LAS bf16x8*)(lds + PG8_SA(b, h) + aoff + m * 2048 + k * 1024); } while (0)
; #define PG8_LDB(dst, b, h) do { _Pragma("unroll") for (int n = 0; n < 2; ++n) _Pragma("unroll") for (int k = 0; k < 2; ++k) dst[n][k] = *(const LAS bf16x8*)(lds + PG8_SB(b, h) + boff + n * 2048 + k * 1024); } while (0)
; #define PG8_MMA(ai, bj, At, Bt) do { __builtin_amdgcn_s_setprio(1); _Pragma("unroll") for (int m = 0; m < 4; ++m) _Pragma("unroll") for (int n = 0; n < 2; ++n) _Pragma("unroll") for (int k = 0; k < 2; ++k) \
;     acc[ai][bj][m][n] = __builtin_amdgcn_mfma_f32_16x16x32_bf16(Bt[n][k], At[m][k], acc[ai][bj][m][n], 0, 0, 0); __builtin_amdgcn_s_setprio(0); } while (0)
; #define PG8_WAIT_V(n) asm volatile("s_waitcnt vmcnt(" #n ")" ::: "memory")
; #define PG8_WAIT_L(n) asm volatile("s_waitcnt lgkmcnt(" #n ")" ::: "memory")
; #define PG8_BAR __builtin_amdgcn_s_barrier()
; #define PG8_SCHED __builtin_amdgcn_sched_barrier(0)
; template <class Epi, class Sched>
; __device__ __forceinline__ void gemm_phase(LAS unsigned char* lds, const Gemm g, const Sched& S, const Epi& E) {
;     ...
;       PG8_WAIT_V(6); PG8_BAR; PG8_MMA(1, 1, At, B1); PG8_BAR;
;       PG8_LDB(B0, 1, 0); PG8_SCHED; PG8_LDA(At, 1, 0); PG8_STAGE(PG8_SA(0, 1), a2 + hstep, voffA);
;       PG8_WAIT_L(8); PG8_BAR; PG8_WAIT_L(0); PG8_MMA(0, 0, At, B0); PG8_BAR; PG8_SCHED;
;       PG8_LDB(B1, 1, 1); PG8_STAGE(PG8_SB(1, 0), b3, voffB);
	v_mfma_f32_16x16x32_bf16 v[52:55], v[208:211], v[144:147], v[52:55]
	v_mfma_f32_16x16x32_bf16 v[48:51], v[232:235], v[144:147], v[48:51]
	v_mfma_f32_16x16x32_bf16 v[36:39], v[208:211], v[152:155], v[36:39]
	v_mfma_f32_16x16x32_bf16 v[32:35], v[232:235], v[152:155], v[32:35]
	v_mfma_f32_16x16x32_bf16 v[20:23], v[208:211], v[190:193], v[20:23]
	v_mfma_f32_16x16x32_bf16 v[16:19], v[232:235], v[190:193], v[16:19]
	v_mfma_f32_16x16x32_bf16 v[4:7], v[208:211], v[198:201], v[4:7]
	v_mfma_f32_16x16x32_bf16 v[0:3], v[232:235], v[198:201], v[0:3]
	v_mfma_f32_16x16x32_bf16 v[52:55], v[226:229], v[148:151], v[52:55]
	v_mfma_f32_16x16x32_bf16 v[48:51], v[236:239], v[148:151], v[48:51]
	v_mfma_f32_16x16x32_bf16 v[36:39], v[226:229], v[186:189], v[36:39]
	v_mfma_f32_16x16x32_bf16 v[32:35], v[236:239], v[186:189], v[32:35]
	v_mfma_f32_16x16x32_bf16 v[20:23], v[226:229], v[194:197], v[20:23]
	v_mfma_f32_16x16x32_bf16 v[16:19], v[236:239], v[194:197], v[16:19]
	v_mfma_f32_16x16x32_bf16 v[4:7], v[226:229], v[204:207], v[4:7]
	v_mfma_f32_16x16x32_bf16 v[0:3], v[236:239], v[204:207], v[0:3]
	s_add_i32 s74, 0, 0x18000
	v_add_u32_e32 v140, s74, v202
	s_barrier
	ds_read_b128 v[128:131], v140
	ds_read_b128 v[132:135], v140 offset:1024
	ds_read_b128 v[136:139], v140 offset:2048
	ds_read_b128 v[140:143], v140 offset:3072
	s_add_u32 s48, s48, 0x40000
	s_addc_u32 s49, s49, 0
	s_mov_b32 m0, s63
	ds_read_b128 v[144:147], v203 offset:32768
	ds_read_b128 v[148:151], v203 offset:33792
	ds_read_b128 v[152:155], v203 offset:34816
	ds_read_b128 v[186:189], v203 offset:35840
	ds_read_b128 v[190:193], v203 offset:36864
	ds_read_b128 v[194:197], v203 offset:37888
	ds_read_b128 v[198:201], v203 offset:38912
	ds_read_b128 v[204:207], v203 offset:39936
	global_load_lds_dwordx4 v176, s[48:49]
	s_mov_b32 m0, s64
	s_nop 0
	global_load_lds_dwordx4 v158, s[48:49]
	s_waitcnt lgkmcnt(8)
	s_barrier
	s_waitcnt lgkmcnt(0)
	s_waitcnt lgkmcnt(0)
	v_mfma_f32_16x16x32_bf16 v[124:127], v[128:131], v[144:147], v[124:127]
	v_mfma_f32_16x16x32_bf16 v[120:123], v[136:139], v[144:147], v[120:123]
	v_mfma_f32_16x16x32_bf16 v[108:111], v[128:131], v[152:155], v[108:111]
	v_mfma_f32_16x16x32_bf16 v[104:107], v[136:139], v[152:155], v[104:107]
	v_mfma_f32_16x16x32_bf16 v[92:95], v[128:131], v[190:193], v[92:95]
	v_mfma_f32_16x16x32_bf16 v[88:91], v[136:139], v[190:193], v[88:91]
	v_mfma_f32_16x16x32_bf16 v[76:79], v[128:131], v[198:201], v[76:79]
	v_mfma_f32_16x16x32_bf16 v[72:75], v[136:139], v[198:201], v[72:75]
	v_mfma_f32_16x16x32_bf16 v[124:127], v[132:135], v[148:151], v[124:127]
	v_mfma_f32_16x16x32_bf16 v[120:123], v[140:143], v[148:151], v[120:123]
	v_mfma_f32_16x16x32_bf16 v[108:111], v[132:135], v[186:189], v[108:111]
	v_mfma_f32_16x16x32_bf16 v[104:107], v[140:143], v[186:189], v[104:107]
	v_mfma_f32_16x16x32_bf16 v[92:95], v[132:135], v[194:197], v[92:95]
	v_mfma_f32_16x16x32_bf16 v[88:91], v[140:143], v[194:197], v[88:91]
	v_mfma_f32_16x16x32_bf16 v[76:79], v[132:135], v[204:207], v[76:79]
	v_mfma_f32_16x16x32_bf16 v[72:75], v[140:143], v[204:207], v[72:75]
	s_barrier
	s_add_i32 s75, 0, 0x1c000
	s_add_i32 s48, s74, s7
	v_add_u32_e32 v160, s75, v202
	s_add_u32 s98, vcc_lo, s80
	s_addc_u32 s99, vcc_hi, s81
	s_mov_b32 m0, s48
	ds_read_b128 v[208:211], v160
	ds_read_b128 v[226:229], v160 offset:1024
	ds_read_b128 v[232:235], v160 offset:2048
	ds_read_b128 v[236:239], v160 offset:3072
	global_load_lds_dwordx4 v174, s[98:99]
	s_add_i32 m0, s48, 0x2000
	s_nop 0
	global_load_lds_dwordx4 v156, s[98:99]
	s_barrier
; #define PG8_STAGE(bufoff, gbase, voff) do { _Pragma("unroll") for (int _i = 0; _i < 2; ++_i) \
;     __builtin_amdgcn_global_load_lds((const unsigned*)((const char*)(gbase) + (voff)[_i]), (LAS unsigned*)(lds + (bufoff) + ldsw + _i * 8192), 16, 0, 0); } while (0)
; #define PG8_LDA(dst, b, h) do { _Pragma("unroll") for (int m = 0; m < 4; ++m) _Pragma("unroll") for (int k = 0; k < 2; ++k) dst[m][k] = *(const LAS bf16x8*)(lds + PG8_SA(b, h) + aoff + m * 2048 + k * 1024); } while (0)
; #define PG8_MMA(ai, bj, At, Bt) do { __builtin_amdgcn_s_setprio(1); _Pragma("unroll") for (int m = 0; m < 4; ++m) _Pragma("unroll") for (int n = 0; n < 2; ++n) _Pragma("unroll") for (int k = 0; k < 2; ++k) \
;     acc[ai][bj][m][n] = __builtin_amdgcn_mfma_f32_16x16x32_bf16(Bt[n][k], At[m][k], acc[ai][bj][m][n], 0, 0, 0); __builtin_amdgcn_s_setprio(0); } while (0)
; #define PG8_WAIT_V(n) asm volatile("s_waitcnt vmcnt(" #n ")" ::: "memory")
; #define PG8_WAIT_L(n) asm volatile("s_waitcnt lgkmcnt(" #n ")" ::: "memory")
; #define PG8_BAR __builtin_amdgcn_s_barrier()
; #define PG8_SCHED __builtin_amdgcn_sched_barrier(0)
; template <class Epi, class Sched>
; __device__ __forceinline__ void gemm_phase(LAS unsigned char* lds, const Gemm g, const Sched& S, const Epi& E) {
;     ...
;       PG8_BAR; PG8_WAIT_L(0); PG8_MMA(0, 1, At, B1); PG8_BAR;
;       PG8_LDA(At, 1, 1); PG8_STAGE(PG8_SA(1, 0), a3, voffA);
;       PG8_BAR; PG8_WAIT_L(0); PG8_MMA(1, 0, At, B0); PG8_BAR; PG8_SCHED;
;       PG8_STAGE(PG8_SB(1, 1), b3 + hstep, voffB);
;       PG8_WAIT_V(6); PG8_BAR; PG8_MMA(1, 1, At, B1); PG8_BAR;
	s_waitcnt lgkmcnt(0)
	s_waitcnt lgkmcnt(0)
	v_mfma_f32_16x16x32_bf16 v[116:119], v[208:211], v[144:147], v[116:119]
	v_mfma_f32_16x16x32_bf16 v[112:115], v[232:235], v[144:147], v[112:115]
	v_mfma_f32_16x16x32_bf16 v[100:103], v[208:211], v[152:155], v[100:103]
	v_mfma_f32_16x16x32_bf16 v[96:99], v[232:235], v[152:155], v[96:99]
	v_mfma_f32_16x16x32_bf16 v[84:87], v[208:211], v[190:193], v[84:87]
	v_mfma_f32_16x16x32_bf16 v[80:83], v[232:235], v[190:193], v[80:83]
	v_mfma_f32_16x16x32_bf16 v[68:71], v[208:211], v[198:201], v[68:71]
	v_mfma_f32_16x16x32_bf16 v[64:67], v[232:235], v[198:201], v[64:67]
	v_mfma_f32_16x16x32_bf16 v[116:119], v[226:229], v[148:151], v[116:119]
	v_mfma_f32_16x16x32_bf16 v[112:115], v[236:239], v[148:151], v[112:115]
	v_mfma_f32_16x16x32_bf16 v[100:103], v[226:229], v[186:189], v[100:103]
	v_mfma_f32_16x16x32_bf16 v[96:99], v[236:239], v[186:189], v[96:99]
	v_mfma_f32_16x16x32_bf16 v[84:87], v[226:229], v[194:197], v[84:87]
	v_mfma_f32_16x16x32_bf16 v[80:83], v[236:239], v[194:197], v[80:83]
	v_mfma_f32_16x16x32_bf16 v[68:71], v[226:229], v[204:207], v[68:71]
	v_mfma_f32_16x16x32_bf16 v[64:67], v[236:239], v[204:207], v[64:67]
	s_mov_b32 m0, s65
	v_lshl_add_u64 v[212:213], v[240:241], 0, s[80:81]
	s_barrier
	ds_read_b128 v[144:147], v203 offset:49152
	ds_read_b128 v[148:151], v203 offset:50176
	ds_read_b128 v[152:155], v203 offset:51200
	ds_read_b128 v[186:189], v203 offset:52224
	ds_read_b128 v[190:193], v203 offset:53248
	ds_read_b128 v[194:197], v203 offset:54272
	ds_read_b128 v[198:201], v203 offset:55296
	ds_read_b128 v[204:207], v203 offset:56320
	global_load_lds_dwordx4 v[212:213], off
	v_lshl_add_u64 v[212:213], v[242:243], 0, s[80:81]
	s_mov_b32 m0, s70
	s_nop 0
	global_load_lds_dwordx4 v[212:213], off
	s_barrier
	s_waitcnt lgkmcnt(0)
	s_waitcnt lgkmcnt(0)
	v_mfma_f32_16x16x32_bf16 v[60:63], v[128:131], v[144:147], v[60:63]
	v_mfma_f32_16x16x32_bf16 v[56:59], v[136:139], v[144:147], v[56:59]
	v_mfma_f32_16x16x32_bf16 v[44:47], v[128:131], v[152:155], v[44:47]
	v_mfma_f32_16x16x32_bf16 v[40:43], v[136:139], v[152:155], v[40:43]
	v_mfma_f32_16x16x32_bf16 v[28:31], v[128:131], v[190:193], v[28:31]
	v_mfma_f32_16x16x32_bf16 v[24:27], v[136:139], v[190:193], v[24:27]
	v_mfma_f32_16x16x32_bf16 v[12:15], v[128:131], v[198:201], v[12:15]
	v_mfma_f32_16x16x32_bf16 v[8:11], v[136:139], v[198:201], v[8:11]
	v_mfma_f32_16x16x32_bf16 v[60:63], v[132:135], v[148:151], v[60:63]
	v_mfma_f32_16x16x32_bf16 v[56:59], v[140:143], v[148:151], v[56:59]
	v_mfma_f32_16x16x32_bf16 v[44:47], v[132:135], v[186:189], v[44:47]
	v_mfma_f32_16x16x32_bf16 v[40:43], v[140:143], v[186:189], v[40:43]
	v_mfma_f32_16x16x32_bf16 v[28:31], v[132:135], v[194:197], v[28:31]
	v_mfma_f32_16x16x32_bf16 v[24:27], v[140:143], v[194:197], v[24:27]
	v_mfma_f32_16x16x32_bf16 v[12:15], v[132:135], v[204:207], v[12:15]
	v_mfma_f32_16x16x32_bf16 v[8:11], v[140:143], v[204:207], v[8:11]
	s_barrier
	s_add_u32 s48, vcc_lo, 0x40080
	s_addc_u32 s49, vcc_hi, 0
	s_add_i32 s74, s75, s7
	s_mov_b32 m0, s74
	s_nop 0
	global_load_lds_dwordx4 v174, s[48:49]
	s_add_i32 m0, s74, 0x2000
	s_nop 0
	global_load_lds_dwordx4 v156, s[48:49]
	s_waitcnt vmcnt(6)
	s_barrier
	v_mfma_f32_16x16x32_bf16 v[52:55], v[208:211], v[144:147], v[52:55]
	v_mfma_f32_16x16x32_bf16 v[48:51], v[232:235], v[144:147], v[48:51]
	v_mfma_f32_16x16x32_bf16 v[36:39], v[208:211], v[152:155], v[36:39]
	v_mfma_f32_16x16x32_bf16 v[32:35], v[232:235], v[152:155], v[32:35]
	v_mfma_f32_16x16x32_bf16 v[20:23], v[208:211], v[190:193], v[20:23]
	v_mfma_f32_16x16x32_bf16 v[16:19], v[232:235], v[190:193], v[16:19]
	v_mfma_f32_16x16x32_bf16 v[4:7], v[208:211], v[198:201], v[4:7]
	v_mfma_f32_16x16x32_bf16 v[0:3], v[232:235], v[198:201], v[0:3]
	v_mfma_f32_16x16x32_bf16 v[52:55], v[226:229], v[148:151], v[52:55]
	v_mfma_f32_16x16x32_bf16 v[48:51], v[236:239], v[148:151], v[48:51]
	v_mfma_f32_16x16x32_bf16 v[36:39], v[226:229], v[186:189], v[36:39]
	v_mfma_f32_16x16x32_bf16 v[32:35], v[236:239], v[186:189], v[32:35]
	v_mfma_f32_16x16x32_bf16 v[20:23], v[226:229], v[194:197], v[20:23]
	v_mfma_f32_16x16x32_bf16 v[16:19], v[236:239], v[194:197], v[16:19]
	v_mfma_f32_16x16x32_bf16 v[4:7], v[226:229], v[204:207], v[4:7]
	v_mfma_f32_16x16x32_bf16 v[0:3], v[236:239], v[204:207], v[0:3]
	s_add_i32 s73, s73, 2
	s_add_u32 s34, s34, 0x100
	s_addc_u32 s35, s35, 0
	s_add_u32 s52, s52, 0x100
	s_addc_u32 s72, s72, 0
	s_cmp_gt_u32 s73, 13
	s_barrier
	s_cbranch_scc0 .LBB0_863
	s_cmp_lt_u32 s101, 0x100
	s_cbranch_scc0 .Lxa_6
	s_barrier

; #define PG8_STAGE(bufoff, gbase, voff) do { _Pragma("unroll") for (int _i = 0; _i < 2; ++_i) \
;     __builtin_amdgcn_global_load_lds((const unsigned*)((const char*)(gbase) + (voff)[_i]), (LAS unsigned*)(lds + (bufoff) + ldsw + _i * 8192), 16, 0, 0); } while (0)
; #define PG8_LDA(dst, b, h) do { _Pragma("unroll") for (int m = 0; m < 4; ++m) _Pragma("unroll") for (int k = 0; k < 2; ++k) dst[m][k] = *(const LAS bf16x8*)(lds + PG8_SA(b, h) + aoff + m * 2048 + k * 1024); } while (0)
; #define PG8_LDB(dst, b, h) do { _Pragma("unroll") for (int n = 0; n < 2; ++n) _Pragma("unroll") for (int k = 0; k < 2; ++k) dst[n][k] = *(const LAS bf16x8*)(lds + PG8_SB(b, h) + boff + n * 2048 + k * 1024); } while (0)
; #define PG8_MMA(ai, bj, At, Bt) do { __builtin_amdgcn_s_setprio(1); _Pragma("unroll") for (int m = 0; m < 4; ++m) _Pragma("unroll") for (int n = 0; n < 2; ++n) _Pragma("unroll") for (int k = 0; k < 2; ++k) \
;     acc[ai][bj][m][n] = __builtin_amdgcn_mfma_f32_16x16x32_bf16(Bt[n][k], At[m][k], acc[ai][bj][m][n], 0, 0, 0); __builtin_amdgcn_s_setprio(0); } while (0)
; #define PG8_WAIT_V(n) asm volatile("s_waitcnt vmcnt(" #n ")" ::: "memory")
; #define PG8_WAIT_L(n) asm volatile("s_waitcnt lgkmcnt(" #n ")" ::: "memory")
; #define PG8_BAR __builtin_amdgcn_s_barrier()
; #define PG8_SCHED __builtin_amdgcn_sched_barrier(0)
; template <class Epi, class Sched>
; __device__ __forceinline__ void gemm_phase(LAS unsigned char* lds, const Gemm g, const Sched& S, const Epi& E) {
;     ...
;       PG8_LDB(B0, 0, 0); PG8_SCHED; PG8_LDA(At, 0, 0); PG8_STAGE(PG8_SA(1, 1), a1 + hstep, voffA);
;       PG8_WAIT_L(8); PG8_BAR; PG8_WAIT_L(0); PG8_MMA(0, 0, At, B0); PG8_BAR; PG8_SCHED;
;       PG8_LDB(B1, 0, 1); PG8_STAGE(PG8_SB(0, 0), b2, voffB);
;       PG8_BAR; PG8_WAIT_L(0); PG8_MMA(0, 1, At, B1); PG8_BAR;
;       PG8_LDA(At, 0, 1); PG8_STAGE(PG8_SA(0, 0), a2, voffA);
;       PG8_BAR; PG8_WAIT_L(0); PG8_MMA(1, 0, At, B0); PG8_BAR; PG8_SCHED;
;       PG8_STAGE(PG8_SB(0, 1), b2 + hstep, voffB);
;       PG8_WAIT_V(6); PG8_BAR; PG8_MMA(1, 1, At, B1); PG8_BAR;
.Lxs_e7:
.LBB0_890:
	s_add_u32 s44, s42, 0xfffc0080
	s_addc_u32 s45, s43, -1
	s_add_i32 s74, 0, 0x10000
	v_add_u32_e32 v143, s74, v141
	ds_read_b128 v[144:147], v143
	ds_read_b128 v[148:151], v143 offset:1024
	ds_read_b128 v[152:155], v143 offset:2048
	ds_read_b128 v[156:159], v143 offset:3072
	s_cmp_eq_u32 s73, 12
	s_cselect_b32 s49, s35, s45
	s_cselect_b32 s48, s70, s44
	s_cselect_b32 s45, s23, s72
	s_cselect_b32 s44, s71, s52
	s_add_i32 m0, s12, 0xc000
	ds_read_b128 v[174:177], v142
	ds_read_b128 v[178:181], v142 offset:1024
	ds_read_b128 v[182:185], v142 offset:2048
	ds_read_b128 v[186:189], v142 offset:3072
	ds_read_b128 v[190:193], v142 offset:4096
	ds_read_b128 v[194:197], v142 offset:5120
	ds_read_b128 v[198:201], v142 offset:6144
	ds_read_b128 v[202:205], v142 offset:7168
	global_load_lds_dwordx4 v136, s[42:43]
	s_add_i32 m0, s12, 0xe000
	s_nop 0
	global_load_lds_dwordx4 v138, s[42:43]
	s_waitcnt lgkmcnt(8)
	s_barrier
	s_waitcnt lgkmcnt(0)
	s_waitcnt lgkmcnt(0)
	v_mfma_f32_16x16x32_bf16 v[124:127], v[144:147], v[174:177], v[124:127]
	v_mfma_f32_16x16x32_bf16 v[120:123], v[152:155], v[174:177], v[120:123]
	v_mfma_f32_16x16x32_bf16 v[116:119], v[144:147], v[182:185], v[116:119]
	v_mfma_f32_16x16x32_bf16 v[112:115], v[152:155], v[182:185], v[112:115]
	v_mfma_f32_16x16x32_bf16 v[100:103], v[144:147], v[190:193], v[100:103]
	v_mfma_f32_16x16x32_bf16 v[96:99], v[152:155], v[190:193], v[96:99]
	v_mfma_f32_16x16x32_bf16 v[84:87], v[144:147], v[198:201], v[84:87]
	v_mfma_f32_16x16x32_bf16 v[80:83], v[152:155], v[198:201], v[80:83]
	v_mfma_f32_16x16x32_bf16 v[124:127], v[148:151], v[178:181], v[124:127]
	v_mfma_f32_16x16x32_bf16 v[120:123], v[156:159], v[178:181], v[120:123]
	v_mfma_f32_16x16x32_bf16 v[116:119], v[148:151], v[186:189], v[116:119]
	v_mfma_f32_16x16x32_bf16 v[112:115], v[156:159], v[186:189], v[112:115]
	v_mfma_f32_16x16x32_bf16 v[100:103], v[148:151], v[194:197], v[100:103]
	v_mfma_f32_16x16x32_bf16 v[96:99], v[156:159], v[194:197], v[96:99]
	v_mfma_f32_16x16x32_bf16 v[84:87], v[148:151], v[202:205], v[84:87]
	v_mfma_f32_16x16x32_bf16 v[80:83], v[156:159], v[202:205], v[80:83]
	s_barrier
	s_add_i32 s76, 0, 0x14000
	s_add_i32 s74, s74, s7
	v_add_u32_e32 v143, s76, v141
	s_mov_b32 m0, s74
	ds_read_b128 v[206:209], v143
	ds_read_b128 v[210:213], v143 offset:1024
	ds_read_b128 v[226:229], v143 offset:2048
	ds_read_b128 v[232:235], v143 offset:3072
	global_load_lds_dwordx4 v132, s[44:45]
	s_add_i32 m0, s74, 0x2000
	s_nop 0
	global_load_lds_dwordx4 v128, s[44:45]
	s_barrier
	s_waitcnt lgkmcnt(0)
	s_waitcnt lgkmcnt(0)
	v_mfma_f32_16x16x32_bf16 v[108:111], v[206:209], v[174:177], v[108:111]
	v_mfma_f32_16x16x32_bf16 v[104:107], v[226:229], v[174:177], v[104:107]
	v_mfma_f32_16x16x32_bf16 v[92:95], v[206:209], v[182:185], v[92:95]
	v_mfma_f32_16x16x32_bf16 v[88:91], v[226:229], v[182:185], v[88:91]
	v_mfma_f32_16x16x32_bf16 v[76:79], v[206:209], v[190:193], v[76:79]
	v_mfma_f32_16x16x32_bf16 v[72:75], v[226:229], v[190:193], v[72:75]
	v_mfma_f32_16x16x32_bf16 v[68:71], v[206:209], v[198:201], v[68:71]
	v_mfma_f32_16x16x32_bf16 v[64:67], v[226:229], v[198:201], v[64:67]
	v_mfma_f32_16x16x32_bf16 v[108:111], v[210:213], v[178:181], v[108:111]
	v_mfma_f32_16x16x32_bf16 v[104:107], v[232:235], v[178:181], v[104:107]
	v_mfma_f32_16x16x32_bf16 v[92:95], v[210:213], v[186:189], v[92:95]
	v_mfma_f32_16x16x32_bf16 v[88:91], v[232:235], v[186:189], v[88:91]
	v_mfma_f32_16x16x32_bf16 v[76:79], v[210:213], v[194:197], v[76:79]
	v_mfma_f32_16x16x32_bf16 v[72:75], v[232:235], v[194:197], v[72:75]
	v_mfma_f32_16x16x32_bf16 v[68:71], v[210:213], v[202:205], v[68:71]
	v_mfma_f32_16x16x32_bf16 v[64:67], v[232:235], v[202:205], v[64:67]
	s_mov_b32 m0, s12
	v_lshl_add_u64 v[238:239], s[48:49], 0, v[134:135]
	s_barrier
	ds_read_b128 v[174:177], v142 offset:16384
	ds_read_b128 v[178:181], v142 offset:17408
	ds_read_b128 v[182:185], v142 offset:18432
	ds_read_b128 v[186:189], v142 offset:19456
	ds_read_b128 v[190:193], v142 offset:20480
	ds_read_b128 v[194:197], v142 offset:21504
	ds_read_b128 v[198:201], v142 offset:22528
	ds_read_b128 v[202:205], v142 offset:23552
	global_load_lds_dwordx4 v134, s[48:49]
	v_lshl_add_u64 v[240:241], s[48:49], 0, v[130:131]
	s_mov_b32 m0, s13
	s_nop 0
	global_load_lds_dwordx4 v130, s[48:49]
	s_barrier
	s_waitcnt lgkmcnt(0)
	s_waitcnt lgkmcnt(0)
	v_mfma_f32_16x16x32_bf16 v[60:63], v[144:147], v[174:177], v[60:63]
	v_mfma_f32_16x16x32_bf16 v[56:59], v[152:155], v[174:177], v[56:59]
	v_mfma_f32_16x16x32_bf16 v[52:55], v[144:147], v[182:185], v[52:55]
	v_mfma_f32_16x16x32_bf16 v[48:51], v[152:155], v[182:185], v[48:51]
	v_mfma_f32_16x16x32_bf16 v[36:39], v[144:147], v[190:193], v[36:39]
	v_mfma_f32_16x16x32_bf16 v[32:35], v[152:155], v[190:193], v[32:35]
	v_mfma_f32_16x16x32_bf16 v[20:23], v[144:147], v[198:201], v[20:23]
	v_mfma_f32_16x16x32_bf16 v[16:19], v[152:155], v[198:201], v[16:19]
	v_mfma_f32_16x16x32_bf16 v[60:63], v[148:151], v[178:181], v[60:63]
	v_mfma_f32_16x16x32_bf16 v[56:59], v[156:159], v[178:181], v[56:59]
	v_mfma_f32_16x16x32_bf16 v[52:55], v[148:151], v[186:189], v[52:55]
	v_mfma_f32_16x16x32_bf16 v[48:51], v[156:159], v[186:189], v[48:51]
	v_mfma_f32_16x16x32_bf16 v[36:39], v[148:151], v[194:197], v[36:39]
	v_mfma_f32_16x16x32_bf16 v[32:35], v[156:159], v[194:197], v[32:35]
	v_mfma_f32_16x16x32_bf16 v[20:23], v[148:151], v[202:205], v[20:23]
	v_mfma_f32_16x16x32_bf16 v[16:19], v[156:159], v[202:205], v[16:19]
	s_barrier
	s_add_u32 s74, s44, 0x40000
	s_addc_u32 s75, s45, 0
	s_add_i32 s76, s76, s7
	s_mov_b32 m0, s76
	s_nop 0
	global_load_lds_dwordx4 v132, s[74:75]
	s_add_i32 m0, s76, 0x2000
	s_nop 0
	global_load_lds_dwordx4 v128, s[74:75]
	s_waitcnt vmcnt(6)
	s_barrier
; #define PG8_STAGE(bufoff, gbase, voff) do { _Pragma("unroll") for (int _i = 0; _i < 2; ++_i) \
;     __builtin_amdgcn_global_load_lds((const unsigned*)((const char*)(gbase) + (voff)[_i]), (LAS unsigned*)(lds + (bufoff) + ldsw + _i * 8192), 16, 0, 0); } while (0)
; #define PG8_LDA(dst, b, h) do { _Pragma("unroll") for (int m = 0; m < 4; ++m) _Pragma("unroll") for (int k = 0; k < 2; ++k) dst[m][k] = *(const LAS bf16x8*)(lds + PG8_SA(b, h) + aoff + m * 2048 + k * 1024); } while (0)
; #define PG8_LDB(dst, b, h) do { _Pragma("unroll") for (int n = 0; n < 2; ++n) _Pragma("unroll") for (int k = 0; k < 2; ++k) dst[n][k] = *(const LAS bf16x8*)(lds + PG8_SB(b, h) + boff + n * 2048 + k * 1024); } while (0)
; #define PG8_MMA(ai, bj, At, Bt) do { __builtin_amdgcn_s_setprio(1); _Pragma("unroll") for (int m = 0; m < 4; ++m) _Pragma("unroll") for (int n = 0; n < 2; ++n) _Pragma("unroll") for (int k = 0; k < 2; ++k) \
;     acc[ai][bj][m][n] = __builtin_amdgcn_mfma_f32_16x16x32_bf16(Bt[n][k], At[m][k], acc[ai][bj][m][n], 0, 0, 0); __builtin_amdgcn_s_setprio(0); } while (0)
; #define PG8_WAIT_V(n) asm volatile("s_waitcnt vmcnt(" #n ")" ::: "memory")
; #define PG8_WAIT_L(n) asm volatile("s_waitcnt lgkmcnt(" #n ")" ::: "memory")
; #define PG8_BAR __builtin_amdgcn_s_barrier()
; #define PG8_SCHED __builtin_amdgcn_sched_barrier(0)
; template <class Epi, class Sched>
; __device__ __forceinline__ void gemm_phase(LAS unsigned char* lds, const Gemm g, const Sched& S, const Epi& E) {
;     ...
;       PG8_WAIT_V(6); PG8_BAR; PG8_MMA(1, 1, At, B1); PG8_BAR;
;       PG8_LDB(B0, 1, 0); PG8_SCHED; PG8_LDA(At, 1, 0); PG8_STAGE(PG8_SA(0, 1), a2 + hstep, voffA);
;       PG8_WAIT_L(8); PG8_BAR; PG8_WAIT_L(0); PG8_MMA(0, 0, At, B0); PG8_BAR; PG8_SCHED;
;       PG8_LDB(B1, 1, 1); PG8_STAGE(PG8_SB(1, 0), b3, voffB);
	v_mfma_f32_16x16x32_bf16 v[44:47], v[206:209], v[174:177], v[44:47]
	v_mfma_f32_16x16x32_bf16 v[40:43], v[226:229], v[174:177], v[40:43]
	v_mfma_f32_16x16x32_bf16 v[28:31], v[206:209], v[182:185], v[28:31]
	v_mfma_f32_16x16x32_bf16 v[24:27], v[226:229], v[182:185], v[24:27]
	v_mfma_f32_16x16x32_bf16 v[12:15], v[206:209], v[190:193], v[12:15]
	v_mfma_f32_16x16x32_bf16 v[8:11], v[226:229], v[190:193], v[8:11]
	v_mfma_f32_16x16x32_bf16 v[4:7], v[206:209], v[198:201], v[4:7]
	v_mfma_f32_16x16x32_bf16 v[0:3], v[226:229], v[198:201], v[0:3]
	v_mfma_f32_16x16x32_bf16 v[44:47], v[210:213], v[178:181], v[44:47]
	v_mfma_f32_16x16x32_bf16 v[40:43], v[232:235], v[178:181], v[40:43]
	v_mfma_f32_16x16x32_bf16 v[28:31], v[210:213], v[186:189], v[28:31]
	v_mfma_f32_16x16x32_bf16 v[24:27], v[232:235], v[186:189], v[24:27]
	v_mfma_f32_16x16x32_bf16 v[12:15], v[210:213], v[194:197], v[12:15]
	v_mfma_f32_16x16x32_bf16 v[8:11], v[232:235], v[194:197], v[8:11]
	v_mfma_f32_16x16x32_bf16 v[4:7], v[210:213], v[202:205], v[4:7]
	v_mfma_f32_16x16x32_bf16 v[0:3], v[232:235], v[202:205], v[0:3]
	s_add_i32 s74, 0, 0x18000
	v_add_u32_e32 v143, s74, v141
	s_barrier
	ds_read_b128 v[144:147], v143
	ds_read_b128 v[148:151], v143 offset:1024
	ds_read_b128 v[152:155], v143 offset:2048
	ds_read_b128 v[156:159], v143 offset:3072
	s_add_u32 s48, s48, 0x40000
	s_addc_u32 s49, s49, 0
	s_mov_b32 m0, s51
	ds_read_b128 v[174:177], v142 offset:32768
	ds_read_b128 v[178:181], v142 offset:33792
	ds_read_b128 v[182:185], v142 offset:34816
	ds_read_b128 v[186:189], v142 offset:35840
	ds_read_b128 v[190:193], v142 offset:36864
	ds_read_b128 v[194:197], v142 offset:37888
	ds_read_b128 v[198:201], v142 offset:38912
	ds_read_b128 v[202:205], v142 offset:39936
	global_load_lds_dwordx4 v134, s[48:49]
	s_mov_b32 m0, s62
	s_nop 0
	global_load_lds_dwordx4 v130, s[48:49]
	s_waitcnt lgkmcnt(8)
	s_barrier
	s_waitcnt lgkmcnt(0)
	s_waitcnt lgkmcnt(0)
	v_mfma_f32_16x16x32_bf16 v[124:127], v[144:147], v[174:177], v[124:127]
	v_mfma_f32_16x16x32_bf16 v[120:123], v[152:155], v[174:177], v[120:123]
	v_mfma_f32_16x16x32_bf16 v[116:119], v[144:147], v[182:185], v[116:119]
	v_mfma_f32_16x16x32_bf16 v[112:115], v[152:155], v[182:185], v[112:115]
	v_mfma_f32_16x16x32_bf16 v[100:103], v[144:147], v[190:193], v[100:103]
	v_mfma_f32_16x16x32_bf16 v[96:99], v[152:155], v[190:193], v[96:99]
	v_mfma_f32_16x16x32_bf16 v[84:87], v[144:147], v[198:201], v[84:87]
	v_mfma_f32_16x16x32_bf16 v[80:83], v[152:155], v[198:201], v[80:83]
	v_mfma_f32_16x16x32_bf16 v[124:127], v[148:151], v[178:181], v[124:127]
	v_mfma_f32_16x16x32_bf16 v[120:123], v[156:159], v[178:181], v[120:123]
	v_mfma_f32_16x16x32_bf16 v[116:119], v[148:151], v[186:189], v[116:119]
	v_mfma_f32_16x16x32_bf16 v[112:115], v[156:159], v[186:189], v[112:115]
	v_mfma_f32_16x16x32_bf16 v[100:103], v[148:151], v[194:197], v[100:103]
	v_mfma_f32_16x16x32_bf16 v[96:99], v[156:159], v[194:197], v[96:99]
	v_mfma_f32_16x16x32_bf16 v[84:87], v[148:151], v[202:205], v[84:87]
	v_mfma_f32_16x16x32_bf16 v[80:83], v[156:159], v[202:205], v[80:83]
	s_barrier
	s_add_i32 s48, 0, 0x1c000
	s_add_i32 s49, s74, s7
	v_add_u32_e32 v143, s48, v141
	s_add_u32 s98, s44, s80
	s_addc_u32 s99, s45, s81
	s_mov_b32 m0, s49
	ds_read_b128 v[206:209], v143
	ds_read_b128 v[210:213], v143 offset:1024
	ds_read_b128 v[226:229], v143 offset:2048
	ds_read_b128 v[232:235], v143 offset:3072
	global_load_lds_dwordx4 v132, s[98:99]
	s_add_i32 m0, s49, 0x2000
	s_nop 0
	global_load_lds_dwordx4 v128, s[98:99]
	s_barrier
; #define PG8_STAGE(bufoff, gbase, voff) do { _Pragma("unroll") for (int _i = 0; _i < 2; ++_i) \
;     __builtin_amdgcn_global_load_lds((const unsigned*)((const char*)(gbase) + (voff)[_i]), (LAS unsigned*)(lds + (bufoff) + ldsw + _i * 8192), 16, 0, 0); } while (0)
; #define PG8_LDA(dst, b, h) do { _Pragma("unroll") for (int m = 0; m < 4; ++m) _Pragma("unroll") for (int k = 0; k < 2; ++k) dst[m][k] = *(const LAS bf16x8*)(lds + PG8_SA(b, h) + aoff + m * 2048 + k * 1024); } while (0)
; #define PG8_MMA(ai, bj, At, Bt) do { __builtin_amdgcn_s_setprio(1); _Pragma("unroll") for (int m = 0; m < 4; ++m) _Pragma("unroll") for (int n = 0; n < 2; ++n) _Pragma("unroll") for (int k = 0; k < 2; ++k) \
;     acc[ai][bj][m][n] = __builtin_amdgcn_mfma_f32_16x16x32_bf16(Bt[n][k], At[m][k], acc[ai][bj][m][n], 0, 0, 0); __builtin_amdgcn_s_setprio(0); } while (0)
; #define PG8_WAIT_V(n) asm volatile("s_waitcnt vmcnt(" #n ")" ::: "memory")
; #define PG8_WAIT_L(n) asm volatile("s_waitcnt lgkmcnt(" #n ")" ::: "memory")
; #define PG8_BAR __builtin_amdgcn_s_barrier()
; #define PG8_SCHED __builtin_amdgcn_sched_barrier(0)
; template <class Epi, class Sched>
; __device__ __forceinline__ void gemm_phase(LAS unsigned char* lds, const Gemm g, const Sched& S, const Epi& E) {
;     ...
;       PG8_BAR; PG8_WAIT_L(0); PG8_MMA(0, 1, At, B1); PG8_BAR;
;       PG8_LDA(At, 1, 1); PG8_STAGE(PG8_SA(1, 0), a3, voffA);
;       PG8_BAR; PG8_WAIT_L(0); PG8_MMA(1, 0, At, B0); PG8_BAR; PG8_SCHED;
;       PG8_STAGE(PG8_SB(1, 1), b3 + hstep, voffB);
;       PG8_WAIT_V(6); PG8_BAR; PG8_MMA(1, 1, At, B1); PG8_BAR;
	s_waitcnt lgkmcnt(0)
	s_waitcnt lgkmcnt(0)
	v_mfma_f32_16x16x32_bf16 v[108:111], v[206:209], v[174:177], v[108:111]
	v_mfma_f32_16x16x32_bf16 v[104:107], v[226:229], v[174:177], v[104:107]
	v_mfma_f32_16x16x32_bf16 v[92:95], v[206:209], v[182:185], v[92:95]
	v_mfma_f32_16x16x32_bf16 v[88:91], v[226:229], v[182:185], v[88:91]
	v_mfma_f32_16x16x32_bf16 v[76:79], v[206:209], v[190:193], v[76:79]
	v_mfma_f32_16x16x32_bf16 v[72:75], v[226:229], v[190:193], v[72:75]
	v_mfma_f32_16x16x32_bf16 v[68:71], v[206:209], v[198:201], v[68:71]
	v_mfma_f32_16x16x32_bf16 v[64:67], v[226:229], v[198:201], v[64:67]
	v_mfma_f32_16x16x32_bf16 v[108:111], v[210:213], v[178:181], v[108:111]
	v_mfma_f32_16x16x32_bf16 v[104:107], v[232:235], v[178:181], v[104:107]
	v_mfma_f32_16x16x32_bf16 v[92:95], v[210:213], v[186:189], v[92:95]
	v_mfma_f32_16x16x32_bf16 v[88:91], v[232:235], v[186:189], v[88:91]
	v_mfma_f32_16x16x32_bf16 v[76:79], v[210:213], v[194:197], v[76:79]
	v_mfma_f32_16x16x32_bf16 v[72:75], v[232:235], v[194:197], v[72:75]
	v_mfma_f32_16x16x32_bf16 v[68:71], v[210:213], v[202:205], v[68:71]
	v_mfma_f32_16x16x32_bf16 v[64:67], v[232:235], v[202:205], v[64:67]
	s_mov_b32 m0, s63
	v_lshl_add_u64 v[222:223], v[238:239], 0, s[80:81]
	s_barrier
	ds_read_b128 v[174:177], v142 offset:49152
	ds_read_b128 v[178:181], v142 offset:50176
	ds_read_b128 v[182:185], v142 offset:51200
	ds_read_b128 v[186:189], v142 offset:52224
	ds_read_b128 v[190:193], v142 offset:53248
	ds_read_b128 v[194:197], v142 offset:54272
	ds_read_b128 v[198:201], v142 offset:55296
	ds_read_b128 v[202:205], v142 offset:56320
	global_load_lds_dwordx4 v[222:223], off
	v_lshl_add_u64 v[222:223], v[240:241], 0, s[80:81]
	s_mov_b32 m0, s64
	s_nop 0
	global_load_lds_dwordx4 v[222:223], off
	s_barrier
	s_waitcnt lgkmcnt(0)
	s_waitcnt lgkmcnt(0)
	v_mfma_f32_16x16x32_bf16 v[60:63], v[144:147], v[174:177], v[60:63]
	v_mfma_f32_16x16x32_bf16 v[56:59], v[152:155], v[174:177], v[56:59]
	v_mfma_f32_16x16x32_bf16 v[52:55], v[144:147], v[182:185], v[52:55]
	v_mfma_f32_16x16x32_bf16 v[48:51], v[152:155], v[182:185], v[48:51]
	v_mfma_f32_16x16x32_bf16 v[36:39], v[144:147], v[190:193], v[36:39]
	v_mfma_f32_16x16x32_bf16 v[32:35], v[152:155], v[190:193], v[32:35]
	v_mfma_f32_16x16x32_bf16 v[20:23], v[144:147], v[198:201], v[20:23]
	v_mfma_f32_16x16x32_bf16 v[16:19], v[152:155], v[198:201], v[16:19]
	v_mfma_f32_16x16x32_bf16 v[60:63], v[148:151], v[178:181], v[60:63]
	v_mfma_f32_16x16x32_bf16 v[56:59], v[156:159], v[178:181], v[56:59]
	v_mfma_f32_16x16x32_bf16 v[52:55], v[148:151], v[186:189], v[52:55]
	v_mfma_f32_16x16x32_bf16 v[48:51], v[156:159], v[186:189], v[48:51]
	v_mfma_f32_16x16x32_bf16 v[36:39], v[148:151], v[194:197], v[36:39]
	v_mfma_f32_16x16x32_bf16 v[32:35], v[156:159], v[194:197], v[32:35]
	v_mfma_f32_16x16x32_bf16 v[20:23], v[148:151], v[202:205], v[20:23]
	v_mfma_f32_16x16x32_bf16 v[16:19], v[156:159], v[202:205], v[16:19]
	s_barrier
	s_add_u32 s44, s44, 0x40080
	s_addc_u32 s45, s45, 0
	s_add_i32 s48, s48, s7
	s_mov_b32 m0, s48
	s_nop 0
	global_load_lds_dwordx4 v132, s[44:45]
	s_add_i32 m0, s48, 0x2000
	s_nop 0
	global_load_lds_dwordx4 v128, s[44:45]
	s_waitcnt vmcnt(6)
	s_barrier
	v_mfma_f32_16x16x32_bf16 v[44:47], v[206:209], v[174:177], v[44:47]
	v_mfma_f32_16x16x32_bf16 v[40:43], v[226:229], v[174:177], v[40:43]
	v_mfma_f32_16x16x32_bf16 v[28:31], v[206:209], v[182:185], v[28:31]
	v_mfma_f32_16x16x32_bf16 v[24:27], v[226:229], v[182:185], v[24:27]
	v_mfma_f32_16x16x32_bf16 v[12:15], v[206:209], v[190:193], v[12:15]
	v_mfma_f32_16x16x32_bf16 v[8:11], v[226:229], v[190:193], v[8:11]
	v_mfma_f32_16x16x32_bf16 v[4:7], v[206:209], v[198:201], v[4:7]
	v_mfma_f32_16x16x32_bf16 v[0:3], v[226:229], v[198:201], v[0:3]
	v_mfma_f32_16x16x32_bf16 v[44:47], v[210:213], v[178:181], v[44:47]
	v_mfma_f32_16x16x32_bf16 v[40:43], v[232:235], v[178:181], v[40:43]
	v_mfma_f32_16x16x32_bf16 v[28:31], v[210:213], v[186:189], v[28:31]
	v_mfma_f32_16x16x32_bf16 v[24:27], v[232:235], v[186:189], v[24:27]
	v_mfma_f32_16x16x32_bf16 v[12:15], v[210:213], v[194:197], v[12:15]
	v_mfma_f32_16x16x32_bf16 v[8:11], v[232:235], v[194:197], v[8:11]
	v_mfma_f32_16x16x32_bf16 v[4:7], v[210:213], v[202:205], v[4:7]
	v_mfma_f32_16x16x32_bf16 v[0:3], v[232:235], v[202:205], v[0:3]
	s_add_i32 s73, s73, 2
	s_add_u32 s42, s42, 0x100
	s_addc_u32 s43, s43, 0
	s_add_u32 s52, s52, 0x100
	s_addc_u32 s72, s72, 0
	s_cmp_gt_u32 s73, 13
	s_barrier
	s_cbranch_scc0 .LBB0_890
	s_cmp_lt_u32 s101, 0x100
	s_cbranch_scc0 .Lxa_7
	s_barrier

; #define PG8_STAGE(bufoff, gbase, voff) do { _Pragma("unroll") for (int _i = 0; _i < 2; ++_i) \
;     __builtin_amdgcn_global_load_lds((const unsigned*)((const char*)(gbase) + (voff)[_i]), (LAS unsigned*)(lds + (bufoff) + ldsw + _i * 8192), 16, 0, 0); } while (0)
; #define PG8_LDA(dst, b, h) do { _Pragma("unroll") for (int m = 0; m < 4; ++m) _Pragma("unroll") for (int k = 0; k < 2; ++k) dst[m][k] = *(const LAS bf16x8*)(lds + PG8_SA(b, h) + aoff + m * 2048 + k * 1024); } while (0)
; #define PG8_LDB(dst, b, h) do { _Pragma("unroll") for (int n = 0; n < 2; ++n) _Pragma("unroll") for (int k = 0; k < 2; ++k) dst[n][k] = *(const LAS bf16x8*)(lds + PG8_SB(b, h) + boff + n * 2048 + k * 1024); } while (0)
; #define PG8_MMA(ai, bj, At, Bt) do { __builtin_amdgcn_s_setprio(1); _Pragma("unroll") for (int m = 0; m < 4; ++m) _Pragma("unroll") for (int n = 0; n < 2; ++n) _Pragma("unroll") for (int k = 0; k < 2; ++k) \
;     acc[ai][bj][m][n] = __builtin_amdgcn_mfma_f32_16x16x32_bf16(Bt[n][k], At[m][k], acc[ai][bj][m][n], 0, 0, 0); __builtin_amdgcn_s_setprio(0); } while (0)
; #define PG8_WAIT_V(n) asm volatile("s_waitcnt vmcnt(" #n ")" ::: "memory")
; #define PG8_WAIT_L(n) asm volatile("s_waitcnt lgkmcnt(" #n ")" ::: "memory")
; #define PG8_BAR __builtin_amdgcn_s_barrier()
; #define PG8_SCHED __builtin_amdgcn_sched_barrier(0)
; template <class Epi, class Sched>
; __device__ __forceinline__ void gemm_phase(LAS unsigned char* lds, const Gemm g, const Sched& S, const Epi& E) {
;     ...
;       PG8_LDB(B0, 0, 0); PG8_SCHED; PG8_LDA(At, 0, 0); PG8_STAGE(PG8_SA(1, 1), a1 + hstep, voffA);
;       PG8_WAIT_L(8); PG8_BAR; PG8_WAIT_L(0); PG8_MMA(0, 0, At, B0); PG8_BAR; PG8_SCHED;
;       PG8_LDB(B1, 0, 1); PG8_STAGE(PG8_SB(0, 0), b2, voffB);
;       PG8_BAR; PG8_WAIT_L(0); PG8_MMA(0, 1, At, B1); PG8_BAR;
;       PG8_LDA(At, 0, 1); PG8_STAGE(PG8_SA(0, 0), a2, voffA);
;       PG8_BAR; PG8_WAIT_L(0); PG8_MMA(1, 0, At, B0); PG8_BAR; PG8_SCHED;
;       PG8_STAGE(PG8_SB(0, 1), b2 + hstep, voffB);
;       PG8_WAIT_V(6); PG8_BAR; PG8_MMA(1, 1, At, B1); PG8_BAR;
.Lxs_e8:
.LBB0_968:
	s_add_u32 s44, s42, 0xfffc0080
	s_addc_u32 s45, s43, -1
	s_add_i32 s74, 0, 0x10000
	v_add_u32_e32 v140, s74, v143
	ds_read_b128 v[146:149], v140
	ds_read_b128 v[150:153], v140 offset:1024
	ds_read_b128 v[154:157], v140 offset:2048
	ds_read_b128 v[174:177], v140 offset:3072
	s_cmp_eq_u32 s73, 12
	s_cselect_b32 s49, s35, s45
	s_cselect_b32 s48, s71, s44
	s_cselect_b32 s45, s23, s72
	s_cselect_b32 s44, vcc_lo, s52
	s_add_i32 m0, s12, 0xc000
	ds_read_b128 v[178:181], v145
	ds_read_b128 v[182:185], v145 offset:1024
	ds_read_b128 v[186:189], v145 offset:2048
	ds_read_b128 v[190:193], v145 offset:3072
	ds_read_b128 v[194:197], v145 offset:4096
	ds_read_b128 v[198:201], v145 offset:5120
	ds_read_b128 v[202:205], v145 offset:6144
	ds_read_b128 v[206:209], v145 offset:7168
	global_load_lds_dwordx4 v136, s[42:43]
	s_add_i32 m0, s12, 0xe000
	s_nop 0
	global_load_lds_dwordx4 v138, s[42:43]
	s_waitcnt lgkmcnt(8)
	s_barrier
	s_waitcnt lgkmcnt(0)
	s_waitcnt lgkmcnt(0)
	v_mfma_f32_16x16x32_bf16 v[124:127], v[146:149], v[178:181], v[124:127]
	v_mfma_f32_16x16x32_bf16 v[120:123], v[154:157], v[178:181], v[120:123]
	v_mfma_f32_16x16x32_bf16 v[116:119], v[146:149], v[186:189], v[116:119]
	v_mfma_f32_16x16x32_bf16 v[108:111], v[154:157], v[186:189], v[108:111]
	v_mfma_f32_16x16x32_bf16 v[96:99], v[146:149], v[194:197], v[96:99]
	v_mfma_f32_16x16x32_bf16 v[88:91], v[154:157], v[194:197], v[88:91]
	v_mfma_f32_16x16x32_bf16 v[84:87], v[146:149], v[202:205], v[84:87]
	v_mfma_f32_16x16x32_bf16 v[76:79], v[154:157], v[202:205], v[76:79]
	v_mfma_f32_16x16x32_bf16 v[124:127], v[150:153], v[182:185], v[124:127]
	v_mfma_f32_16x16x32_bf16 v[120:123], v[174:177], v[182:185], v[120:123]
	v_mfma_f32_16x16x32_bf16 v[116:119], v[150:153], v[190:193], v[116:119]
	v_mfma_f32_16x16x32_bf16 v[108:111], v[174:177], v[190:193], v[108:111]
	v_mfma_f32_16x16x32_bf16 v[96:99], v[150:153], v[198:201], v[96:99]
	v_mfma_f32_16x16x32_bf16 v[88:91], v[174:177], v[198:201], v[88:91]
	v_mfma_f32_16x16x32_bf16 v[84:87], v[150:153], v[206:209], v[84:87]
	v_mfma_f32_16x16x32_bf16 v[76:79], v[174:177], v[206:209], v[76:79]
	s_barrier
	s_add_i32 s76, 0, 0x14000
	v_add_u32_e32 v140, s76, v143
	s_add_i32 s74, s74, s7
	ds_read_b128 v[210:213], v140
	ds_read_b128 v[226:229], v140 offset:1024
	ds_read_b128 v[232:235], v140 offset:2048
	ds_read_b128 v[236:239], v140 offset:3072
	s_mov_b32 m0, s74
	s_nop 0
	global_load_lds_dwordx4 v132, s[44:45]
	s_add_i32 m0, s74, 0x2000
	s_nop 0
	global_load_lds_dwordx4 v128, s[44:45]
	s_barrier
	s_waitcnt lgkmcnt(0)
	s_waitcnt lgkmcnt(0)
	v_mfma_f32_16x16x32_bf16 v[112:115], v[210:213], v[178:181], v[112:115]
	v_mfma_f32_16x16x32_bf16 v[104:107], v[232:235], v[178:181], v[104:107]
	v_mfma_f32_16x16x32_bf16 v[100:103], v[210:213], v[186:189], v[100:103]
	v_mfma_f32_16x16x32_bf16 v[92:95], v[232:235], v[186:189], v[92:95]
	v_mfma_f32_16x16x32_bf16 v[80:83], v[210:213], v[194:197], v[80:83]
	v_mfma_f32_16x16x32_bf16 v[72:75], v[232:235], v[194:197], v[72:75]
	v_mfma_f32_16x16x32_bf16 v[68:71], v[210:213], v[202:205], v[68:71]
	v_mfma_f32_16x16x32_bf16 v[64:67], v[232:235], v[202:205], v[64:67]
	v_mfma_f32_16x16x32_bf16 v[112:115], v[226:229], v[182:185], v[112:115]
	v_mfma_f32_16x16x32_bf16 v[104:107], v[236:239], v[182:185], v[104:107]
	v_mfma_f32_16x16x32_bf16 v[100:103], v[226:229], v[190:193], v[100:103]
	v_mfma_f32_16x16x32_bf16 v[92:95], v[236:239], v[190:193], v[92:95]
	v_mfma_f32_16x16x32_bf16 v[80:83], v[226:229], v[198:201], v[80:83]
	v_mfma_f32_16x16x32_bf16 v[72:75], v[236:239], v[198:201], v[72:75]
	v_mfma_f32_16x16x32_bf16 v[68:71], v[226:229], v[206:209], v[68:71]
	v_mfma_f32_16x16x32_bf16 v[64:67], v[236:239], v[206:209], v[64:67]
	s_mov_b32 m0, s12
	v_lshl_add_u64 v[222:223], s[48:49], 0, v[134:135]
	s_barrier
	ds_read_b128 v[178:181], v145 offset:16384
	ds_read_b128 v[182:185], v145 offset:17408
	ds_read_b128 v[186:189], v145 offset:18432
	ds_read_b128 v[190:193], v145 offset:19456
	ds_read_b128 v[194:197], v145 offset:20480
	ds_read_b128 v[198:201], v145 offset:21504
	ds_read_b128 v[202:205], v145 offset:22528
	ds_read_b128 v[206:209], v145 offset:23552
	global_load_lds_dwordx4 v134, s[48:49]
	v_lshl_add_u64 v[240:241], s[48:49], 0, v[130:131]
	s_mov_b32 m0, s13
	s_nop 0
	global_load_lds_dwordx4 v130, s[48:49]
	s_barrier
	s_waitcnt lgkmcnt(0)
	s_waitcnt lgkmcnt(0)
	v_mfma_f32_16x16x32_bf16 v[60:63], v[146:149], v[178:181], v[60:63]
	v_mfma_f32_16x16x32_bf16 v[56:59], v[154:157], v[178:181], v[56:59]
	v_mfma_f32_16x16x32_bf16 v[52:55], v[146:149], v[186:189], v[52:55]
	v_mfma_f32_16x16x32_bf16 v[44:47], v[154:157], v[186:189], v[44:47]
	v_mfma_f32_16x16x32_bf16 v[32:35], v[146:149], v[194:197], v[32:35]
	v_mfma_f32_16x16x32_bf16 v[24:27], v[154:157], v[194:197], v[24:27]
	v_mfma_f32_16x16x32_bf16 v[20:23], v[146:149], v[202:205], v[20:23]
	v_mfma_f32_16x16x32_bf16 v[12:15], v[154:157], v[202:205], v[12:15]
	v_mfma_f32_16x16x32_bf16 v[60:63], v[150:153], v[182:185], v[60:63]
	v_mfma_f32_16x16x32_bf16 v[56:59], v[174:177], v[182:185], v[56:59]
	v_mfma_f32_16x16x32_bf16 v[52:55], v[150:153], v[190:193], v[52:55]
	v_mfma_f32_16x16x32_bf16 v[44:47], v[174:177], v[190:193], v[44:47]
	v_mfma_f32_16x16x32_bf16 v[32:35], v[150:153], v[198:201], v[32:35]
	v_mfma_f32_16x16x32_bf16 v[24:27], v[174:177], v[198:201], v[24:27]
	v_mfma_f32_16x16x32_bf16 v[20:23], v[150:153], v[206:209], v[20:23]
	v_mfma_f32_16x16x32_bf16 v[12:15], v[174:177], v[206:209], v[12:15]
	s_barrier
	s_add_u32 s74, s44, 0x40000
	s_addc_u32 s75, s45, 0
	s_add_i32 s76, s76, s7
	s_mov_b32 m0, s76
	s_nop 0
	global_load_lds_dwordx4 v132, s[74:75]
	s_add_i32 m0, s76, 0x2000
	s_nop 0
	global_load_lds_dwordx4 v128, s[74:75]
	s_waitcnt vmcnt(6)
	s_barrier
; #define PG8_STAGE(bufoff, gbase, voff) do { _Pragma("unroll") for (int _i = 0; _i < 2; ++_i) \
;     __builtin_amdgcn_global_load_lds((const unsigned*)((const char*)(gbase) + (voff)[_i]), (LAS unsigned*)(lds + (bufoff) + ldsw + _i * 8192), 16, 0, 0); } while (0)
; #define PG8_LDA(dst, b, h) do { _Pragma("unroll") for (int m = 0; m < 4; ++m) _Pragma("unroll") for (int k = 0; k < 2; ++k) dst[m][k] = *(const LAS bf16x8*)(lds + PG8_SA(b, h) + aoff + m * 2048 + k * 1024); } while (0)
; #define PG8_LDB(dst, b, h) do { _Pragma("unroll") for (int n = 0; n < 2; ++n) _Pragma("unroll") for (int k = 0; k < 2; ++k) dst[n][k] = *(const LAS bf16x8*)(lds + PG8_SB(b, h) + boff + n * 2048 + k * 1024); } while (0)
; #define PG8_MMA(ai, bj, At, Bt) do { __builtin_amdgcn_s_setprio(1); _Pragma("unroll") for (int m = 0; m < 4; ++m) _Pragma("unroll") for (int n = 0; n < 2; ++n) _Pragma("unroll") for (int k = 0; k < 2; ++k) \
;     acc[ai][bj][m][n] = __builtin_amdgcn_mfma_f32_16x16x32_bf16(Bt[n][k], At[m][k], acc[ai][bj][m][n], 0, 0, 0); __builtin_amdgcn_s_setprio(0); } while (0)
; #define PG8_WAIT_V(n) asm volatile("s_waitcnt vmcnt(" #n ")" ::: "memory")
; #define PG8_WAIT_L(n) asm volatile("s_waitcnt lgkmcnt(" #n ")" ::: "memory")
; #define PG8_BAR __builtin_amdgcn_s_barrier()
; #define PG8_SCHED __builtin_amdgcn_sched_barrier(0)
; template <class Epi, class Sched>
; __device__ __forceinline__ void gemm_phase(LAS unsigned char* lds, const Gemm g, const Sched& S, const Epi& E) {
;     ...
;       PG8_WAIT_V(6); PG8_BAR; PG8_MMA(1, 1, At, B1); PG8_BAR;
;       PG8_LDB(B0, 1, 0); PG8_SCHED; PG8_LDA(At, 1, 0); PG8_STAGE(PG8_SA(0, 1), a2 + hstep, voffA);
;       PG8_WAIT_L(8); PG8_BAR; PG8_WAIT_L(0); PG8_MMA(0, 0, At, B0); PG8_BAR; PG8_SCHED;
;       PG8_LDB(B1, 1, 1); PG8_STAGE(PG8_SB(1, 0), b3, voffB);
	v_mfma_f32_16x16x32_bf16 v[48:51], v[210:213], v[178:181], v[48:51]
	v_mfma_f32_16x16x32_bf16 v[40:43], v[232:235], v[178:181], v[40:43]
	v_mfma_f32_16x16x32_bf16 v[36:39], v[210:213], v[186:189], v[36:39]
	v_mfma_f32_16x16x32_bf16 v[28:31], v[232:235], v[186:189], v[28:31]
	v_mfma_f32_16x16x32_bf16 v[16:19], v[210:213], v[194:197], v[16:19]
	v_mfma_f32_16x16x32_bf16 v[8:11], v[232:235], v[194:197], v[8:11]
	v_mfma_f32_16x16x32_bf16 v[4:7], v[210:213], v[202:205], v[4:7]
	v_mfma_f32_16x16x32_bf16 v[0:3], v[232:235], v[202:205], v[0:3]
	v_mfma_f32_16x16x32_bf16 v[48:51], v[226:229], v[182:185], v[48:51]
	v_mfma_f32_16x16x32_bf16 v[40:43], v[236:239], v[182:185], v[40:43]
	v_mfma_f32_16x16x32_bf16 v[36:39], v[226:229], v[190:193], v[36:39]
	v_mfma_f32_16x16x32_bf16 v[28:31], v[236:239], v[190:193], v[28:31]
	v_mfma_f32_16x16x32_bf16 v[16:19], v[226:229], v[198:201], v[16:19]
	v_mfma_f32_16x16x32_bf16 v[8:11], v[236:239], v[198:201], v[8:11]
	v_mfma_f32_16x16x32_bf16 v[4:7], v[226:229], v[206:209], v[4:7]
	v_mfma_f32_16x16x32_bf16 v[0:3], v[236:239], v[206:209], v[0:3]
	s_add_i32 s74, 0, 0x18000
	v_add_u32_e32 v174, s74, v143
	s_barrier
	ds_read_b128 v[146:149], v174
	ds_read_b128 v[150:153], v174 offset:1024
	ds_read_b128 v[154:157], v174 offset:2048
	ds_read_b128 v[174:177], v174 offset:3072
	s_add_u32 s48, s48, 0x40000
	s_addc_u32 s49, s49, 0
	s_mov_b32 m0, s51
	ds_read_b128 v[178:181], v145 offset:32768
	ds_read_b128 v[182:185], v145 offset:33792
	ds_read_b128 v[186:189], v145 offset:34816
	ds_read_b128 v[190:193], v145 offset:35840
	ds_read_b128 v[194:197], v145 offset:36864
	ds_read_b128 v[198:201], v145 offset:37888
	ds_read_b128 v[202:205], v145 offset:38912
	ds_read_b128 v[206:209], v145 offset:39936
	global_load_lds_dwordx4 v134, s[48:49]
	s_mov_b32 m0, s62
	s_nop 0
	global_load_lds_dwordx4 v130, s[48:49]
	s_waitcnt lgkmcnt(8)
	s_barrier
	s_waitcnt lgkmcnt(0)
	s_waitcnt lgkmcnt(0)
	v_mfma_f32_16x16x32_bf16 v[124:127], v[146:149], v[178:181], v[124:127]
	v_mfma_f32_16x16x32_bf16 v[120:123], v[154:157], v[178:181], v[120:123]
	v_mfma_f32_16x16x32_bf16 v[116:119], v[146:149], v[186:189], v[116:119]
	v_mfma_f32_16x16x32_bf16 v[108:111], v[154:157], v[186:189], v[108:111]
	v_mfma_f32_16x16x32_bf16 v[96:99], v[146:149], v[194:197], v[96:99]
	v_mfma_f32_16x16x32_bf16 v[88:91], v[154:157], v[194:197], v[88:91]
	v_mfma_f32_16x16x32_bf16 v[84:87], v[146:149], v[202:205], v[84:87]
	v_mfma_f32_16x16x32_bf16 v[76:79], v[154:157], v[202:205], v[76:79]
	v_mfma_f32_16x16x32_bf16 v[124:127], v[150:153], v[182:185], v[124:127]
	v_mfma_f32_16x16x32_bf16 v[120:123], v[174:177], v[182:185], v[120:123]
	v_mfma_f32_16x16x32_bf16 v[116:119], v[150:153], v[190:193], v[116:119]
	v_mfma_f32_16x16x32_bf16 v[108:111], v[174:177], v[190:193], v[108:111]
	v_mfma_f32_16x16x32_bf16 v[96:99], v[150:153], v[198:201], v[96:99]
	v_mfma_f32_16x16x32_bf16 v[88:91], v[174:177], v[198:201], v[88:91]
	v_mfma_f32_16x16x32_bf16 v[84:87], v[150:153], v[206:209], v[84:87]
	v_mfma_f32_16x16x32_bf16 v[76:79], v[174:177], v[206:209], v[76:79]
	s_barrier
	s_add_i32 s48, 0, 0x1c000
	s_add_i32 s49, s74, s7
	v_add_u32_e32 v225, s48, v143
	s_add_u32 s60, s44, s80
	s_addc_u32 s61, s45, s81
	s_mov_b32 m0, s49
	ds_read_b128 v[210:213], v225
	ds_read_b128 v[226:229], v225 offset:1024
	ds_read_b128 v[232:235], v225 offset:2048
	ds_read_b128 v[236:239], v225 offset:3072
	global_load_lds_dwordx4 v132, s[60:61]
	s_add_i32 m0, s49, 0x2000
	s_nop 0
	global_load_lds_dwordx4 v128, s[60:61]
	s_barrier
; #define PG8_STAGE(bufoff, gbase, voff) do { _Pragma("unroll") for (int _i = 0; _i < 2; ++_i) \
;     __builtin_amdgcn_global_load_lds((const unsigned*)((const char*)(gbase) + (voff)[_i]), (LAS unsigned*)(lds + (bufoff) + ldsw + _i * 8192), 16, 0, 0); } while (0)
; #define PG8_LDA(dst, b, h) do { _Pragma("unroll") for (int m = 0; m < 4; ++m) _Pragma("unroll") for (int k = 0; k < 2; ++k) dst[m][k] = *(const LAS bf16x8*)(lds + PG8_SA(b, h) + aoff + m * 2048 + k * 1024); } while (0)
; #define PG8_MMA(ai, bj, At, Bt) do { __builtin_amdgcn_s_setprio(1); _Pragma("unroll") for (int m = 0; m < 4; ++m) _Pragma("unroll") for (int n = 0; n < 2; ++n) _Pragma("unroll") for (int k = 0; k < 2; ++k) \
;     acc[ai][bj][m][n] = __builtin_amdgcn_mfma_f32_16x16x32_bf16(Bt[n][k], At[m][k], acc[ai][bj][m][n], 0, 0, 0); __builtin_amdgcn_s_setprio(0); } while (0)
; #define PG8_WAIT_V(n) asm volatile("s_waitcnt vmcnt(" #n ")" ::: "memory")
; #define PG8_WAIT_L(n) asm volatile("s_waitcnt lgkmcnt(" #n ")" ::: "memory")
; #define PG8_BAR __builtin_amdgcn_s_barrier()
; #define PG8_SCHED __builtin_amdgcn_sched_barrier(0)
; template <class Epi, class Sched>
; __device__ __forceinline__ void gemm_phase(LAS unsigned char* lds, const Gemm g, const Sched& S, const Epi& E) {
;     ...
;       PG8_BAR; PG8_WAIT_L(0); PG8_MMA(0, 1, At, B1); PG8_BAR;
;       PG8_LDA(At, 1, 1); PG8_STAGE(PG8_SA(1, 0), a3, voffA);
;       PG8_BAR; PG8_WAIT_L(0); PG8_MMA(1, 0, At, B0); PG8_BAR; PG8_SCHED;
;       PG8_STAGE(PG8_SB(1, 1), b3 + hstep, voffB);
;       PG8_WAIT_V(6); PG8_BAR; PG8_MMA(1, 1, At, B1); PG8_BAR;
	s_waitcnt lgkmcnt(0)
	s_waitcnt lgkmcnt(0)
	v_mfma_f32_16x16x32_bf16 v[112:115], v[210:213], v[178:181], v[112:115]
	v_mfma_f32_16x16x32_bf16 v[104:107], v[232:235], v[178:181], v[104:107]
	v_mfma_f32_16x16x32_bf16 v[100:103], v[210:213], v[186:189], v[100:103]
	v_mfma_f32_16x16x32_bf16 v[92:95], v[232:235], v[186:189], v[92:95]
	v_mfma_f32_16x16x32_bf16 v[80:83], v[210:213], v[194:197], v[80:83]
	v_mfma_f32_16x16x32_bf16 v[72:75], v[232:235], v[194:197], v[72:75]
	v_mfma_f32_16x16x32_bf16 v[68:71], v[210:213], v[202:205], v[68:71]
	v_mfma_f32_16x16x32_bf16 v[64:67], v[232:235], v[202:205], v[64:67]
	v_mfma_f32_16x16x32_bf16 v[112:115], v[226:229], v[182:185], v[112:115]
	v_mfma_f32_16x16x32_bf16 v[104:107], v[236:239], v[182:185], v[104:107]
	v_mfma_f32_16x16x32_bf16 v[100:103], v[226:229], v[190:193], v[100:103]
	v_mfma_f32_16x16x32_bf16 v[92:95], v[236:239], v[190:193], v[92:95]
	v_mfma_f32_16x16x32_bf16 v[80:83], v[226:229], v[198:201], v[80:83]
	v_mfma_f32_16x16x32_bf16 v[72:75], v[236:239], v[198:201], v[72:75]
	v_mfma_f32_16x16x32_bf16 v[68:71], v[226:229], v[206:209], v[68:71]
	v_mfma_f32_16x16x32_bf16 v[64:67], v[236:239], v[206:209], v[64:67]
	s_mov_b32 m0, s63
	v_lshl_add_u64 v[140:141], v[222:223], 0, s[80:81]
	s_barrier
	ds_read_b128 v[178:181], v145 offset:49152
	ds_read_b128 v[182:185], v145 offset:50176
	ds_read_b128 v[186:189], v145 offset:51200
	ds_read_b128 v[190:193], v145 offset:52224
	ds_read_b128 v[194:197], v145 offset:53248
	ds_read_b128 v[198:201], v145 offset:54272
	ds_read_b128 v[202:205], v145 offset:55296
	ds_read_b128 v[206:209], v145 offset:56320
	global_load_lds_dwordx4 v[140:141], off
	v_lshl_add_u64 v[140:141], v[240:241], 0, s[80:81]
	s_mov_b32 m0, s64
	s_nop 0
	global_load_lds_dwordx4 v[140:141], off
	s_barrier
	s_waitcnt lgkmcnt(0)
	s_waitcnt lgkmcnt(0)
	v_mfma_f32_16x16x32_bf16 v[60:63], v[146:149], v[178:181], v[60:63]
	v_mfma_f32_16x16x32_bf16 v[56:59], v[154:157], v[178:181], v[56:59]
	v_mfma_f32_16x16x32_bf16 v[52:55], v[146:149], v[186:189], v[52:55]
	v_mfma_f32_16x16x32_bf16 v[44:47], v[154:157], v[186:189], v[44:47]
	v_mfma_f32_16x16x32_bf16 v[32:35], v[146:149], v[194:197], v[32:35]
	v_mfma_f32_16x16x32_bf16 v[24:27], v[154:157], v[194:197], v[24:27]
	v_mfma_f32_16x16x32_bf16 v[20:23], v[146:149], v[202:205], v[20:23]
	v_mfma_f32_16x16x32_bf16 v[12:15], v[154:157], v[202:205], v[12:15]
	v_mfma_f32_16x16x32_bf16 v[60:63], v[150:153], v[182:185], v[60:63]
	v_mfma_f32_16x16x32_bf16 v[56:59], v[174:177], v[182:185], v[56:59]
	v_mfma_f32_16x16x32_bf16 v[52:55], v[150:153], v[190:193], v[52:55]
	v_mfma_f32_16x16x32_bf16 v[44:47], v[174:177], v[190:193], v[44:47]
	v_mfma_f32_16x16x32_bf16 v[32:35], v[150:153], v[198:201], v[32:35]
	v_mfma_f32_16x16x32_bf16 v[24:27], v[174:177], v[198:201], v[24:27]
	v_mfma_f32_16x16x32_bf16 v[20:23], v[150:153], v[206:209], v[20:23]
	v_mfma_f32_16x16x32_bf16 v[12:15], v[174:177], v[206:209], v[12:15]
	s_barrier
	s_add_u32 s44, s44, 0x40080
	s_addc_u32 s45, s45, 0
	s_add_i32 s48, s48, s7
	s_mov_b32 m0, s48
	s_nop 0
	global_load_lds_dwordx4 v132, s[44:45]
	s_add_i32 m0, s48, 0x2000
	s_nop 0
	global_load_lds_dwordx4 v128, s[44:45]
	s_waitcnt vmcnt(6)
	s_barrier
	v_mfma_f32_16x16x32_bf16 v[48:51], v[210:213], v[178:181], v[48:51]
	v_mfma_f32_16x16x32_bf16 v[40:43], v[232:235], v[178:181], v[40:43]
	v_mfma_f32_16x16x32_bf16 v[36:39], v[210:213], v[186:189], v[36:39]
	v_mfma_f32_16x16x32_bf16 v[28:31], v[232:235], v[186:189], v[28:31]
	v_mfma_f32_16x16x32_bf16 v[16:19], v[210:213], v[194:197], v[16:19]
	v_mfma_f32_16x16x32_bf16 v[8:11], v[232:235], v[194:197], v[8:11]
	v_mfma_f32_16x16x32_bf16 v[4:7], v[210:213], v[202:205], v[4:7]
	v_mfma_f32_16x16x32_bf16 v[0:3], v[232:235], v[202:205], v[0:3]
	v_mfma_f32_16x16x32_bf16 v[48:51], v[226:229], v[182:185], v[48:51]
	v_mfma_f32_16x16x32_bf16 v[40:43], v[236:239], v[182:185], v[40:43]
	v_mfma_f32_16x16x32_bf16 v[36:39], v[226:229], v[190:193], v[36:39]
	v_mfma_f32_16x16x32_bf16 v[28:31], v[236:239], v[190:193], v[28:31]
	v_mfma_f32_16x16x32_bf16 v[16:19], v[226:229], v[198:201], v[16:19]
	v_mfma_f32_16x16x32_bf16 v[8:11], v[236:239], v[198:201], v[8:11]
	v_mfma_f32_16x16x32_bf16 v[4:7], v[226:229], v[206:209], v[4:7]
	v_mfma_f32_16x16x32_bf16 v[0:3], v[236:239], v[206:209], v[0:3]
	s_add_i32 s73, s73, 2
	s_add_u32 s42, s42, 0x100
	s_addc_u32 s43, s43, 0
	s_add_u32 s52, s52, 0x100
	s_addc_u32 s72, s72, 0
	s_cmp_gt_u32 s73, 13
	s_barrier
	s_cbranch_scc0 .LBB0_968
	s_cmp_lt_u32 s101, 0x100
	s_cbranch_scc0 .Lxa_8
	s_barrier

; #define PG8_STAGE(bufoff, gbase, voff) do { _Pragma("unroll") for (int _i = 0; _i < 2; ++_i) \
;     __builtin_amdgcn_global_load_lds((const unsigned*)((const char*)(gbase) + (voff)[_i]), (LAS unsigned*)(lds + (bufoff) + ldsw + _i * 8192), 16, 0, 0); } while (0)
; #define PG8_LDA(dst, b, h) do { _Pragma("unroll") for (int m = 0; m < 4; ++m) _Pragma("unroll") for (int k = 0; k < 2; ++k) dst[m][k] = *(const LAS bf16x8*)(lds + PG8_SA(b, h) + aoff + m * 2048 + k * 1024); } while (0)
; #define PG8_LDB(dst, b, h) do { _Pragma("unroll") for (int n = 0; n < 2; ++n) _Pragma("unroll") for (int k = 0; k < 2; ++k) dst[n][k] = *(const LAS bf16x8*)(lds + PG8_SB(b, h) + boff + n * 2048 + k * 1024); } while (0)
; #define PG8_MMA(ai, bj, At, Bt) do { __builtin_amdgcn_s_setprio(1); _Pragma("unroll") for (int m = 0; m < 4; ++m) _Pragma("unroll") for (int n = 0; n < 2; ++n) _Pragma("unroll") for (int k = 0; k < 2; ++k) \
;     acc[ai][bj][m][n] = __builtin_amdgcn_mfma_f32_16x16x32_bf16(Bt[n][k], At[m][k], acc[ai][bj][m][n], 0, 0, 0); __builtin_amdgcn_s_setprio(0); } while (0)
; #define PG8_WAIT_V(n) asm volatile("s_waitcnt vmcnt(" #n ")" ::: "memory")
; #define PG8_WAIT_L(n) asm volatile("s_waitcnt lgkmcnt(" #n ")" ::: "memory")
; #define PG8_BAR __builtin_amdgcn_s_barrier()
; #define PG8_SCHED __builtin_amdgcn_sched_barrier(0)
; template <class Epi, class Sched>
; __device__ __forceinline__ void gemm_phase(LAS unsigned char* lds, const Gemm g, const Sched& S, const Epi& E) {
;     ...
;       PG8_LDB(B0, 0, 0); PG8_SCHED; PG8_LDA(At, 0, 0); PG8_STAGE(PG8_SA(1, 1), a1 + hstep, voffA);
;       PG8_WAIT_L(8); PG8_BAR; PG8_WAIT_L(0); PG8_MMA(0, 0, At, B0); PG8_BAR; PG8_SCHED;
;       PG8_LDB(B1, 0, 1); PG8_STAGE(PG8_SB(0, 0), b2, voffB);
;       PG8_BAR; PG8_WAIT_L(0); PG8_MMA(0, 1, At, B1); PG8_BAR;
;       PG8_LDA(At, 0, 1); PG8_STAGE(PG8_SA(0, 0), a2, voffA);
;       PG8_BAR; PG8_WAIT_L(0); PG8_MMA(1, 0, At, B0); PG8_BAR; PG8_SCHED;
;       PG8_STAGE(PG8_SB(0, 1), b2 + hstep, voffB);
;       PG8_WAIT_V(6); PG8_BAR; PG8_MMA(1, 1, At, B1); PG8_BAR;
.Lxs_e9:
.LBB0_1057:
	s_add_u32 s48, s34, 0xfffc0080
	s_addc_u32 s49, s35, -1
	s_add_i32 s74, 0, 0x10000
	v_add_u32_e32 v140, s74, v202
	ds_read_b128 v[128:131], v140
	ds_read_b128 v[132:135], v140 offset:1024
	ds_read_b128 v[136:139], v140 offset:2048
	ds_read_b128 v[140:143], v140 offset:3072
	s_cmp_eq_u32 s73, 12
	s_cselect_b32 s49, s37, s49
	s_cselect_b32 s48, s68, s48
	s_cselect_b32 vcc_hi, s23, s72
	s_cselect_b32 vcc_lo, s69, s52
	s_add_i32 m0, s51, 0xc000
	ds_read_b128 v[144:147], v203
	ds_read_b128 v[148:151], v203 offset:1024
	ds_read_b128 v[152:155], v203 offset:2048
	ds_read_b128 v[186:189], v203 offset:3072
	ds_read_b128 v[190:193], v203 offset:4096
	ds_read_b128 v[194:197], v203 offset:5120
	ds_read_b128 v[198:201], v203 offset:6144
	ds_read_b128 v[204:207], v203 offset:7168
	global_load_lds_dwordx4 v182, s[34:35]
	s_add_i32 m0, s51, 0xe000
	s_nop 0
	global_load_lds_dwordx4 v184, s[34:35]
	s_waitcnt lgkmcnt(8)
	s_barrier
	s_waitcnt lgkmcnt(0)
	s_waitcnt lgkmcnt(0)
	v_mfma_f32_16x16x32_bf16 v[124:127], v[128:131], v[144:147], v[124:127]
	v_mfma_f32_16x16x32_bf16 v[120:123], v[136:139], v[144:147], v[120:123]
	v_mfma_f32_16x16x32_bf16 v[108:111], v[128:131], v[152:155], v[108:111]
	v_mfma_f32_16x16x32_bf16 v[104:107], v[136:139], v[152:155], v[104:107]
	v_mfma_f32_16x16x32_bf16 v[92:95], v[128:131], v[190:193], v[92:95]
	v_mfma_f32_16x16x32_bf16 v[88:91], v[136:139], v[190:193], v[88:91]
	v_mfma_f32_16x16x32_bf16 v[76:79], v[128:131], v[198:201], v[76:79]
	v_mfma_f32_16x16x32_bf16 v[72:75], v[136:139], v[198:201], v[72:75]
	v_mfma_f32_16x16x32_bf16 v[124:127], v[132:135], v[148:151], v[124:127]
	v_mfma_f32_16x16x32_bf16 v[120:123], v[140:143], v[148:151], v[120:123]
	v_mfma_f32_16x16x32_bf16 v[108:111], v[132:135], v[186:189], v[108:111]
	v_mfma_f32_16x16x32_bf16 v[104:107], v[140:143], v[186:189], v[104:107]
	v_mfma_f32_16x16x32_bf16 v[92:95], v[132:135], v[194:197], v[92:95]
	v_mfma_f32_16x16x32_bf16 v[88:91], v[140:143], v[194:197], v[88:91]
	v_mfma_f32_16x16x32_bf16 v[76:79], v[132:135], v[204:207], v[76:79]
	v_mfma_f32_16x16x32_bf16 v[72:75], v[140:143], v[204:207], v[72:75]
	s_barrier
	s_add_i32 s76, 0, 0x14000
	s_add_i32 s74, s74, s7
	v_add_u32_e32 v160, s76, v202
	s_mov_b32 m0, s74
	ds_read_b128 v[208:211], v160
	ds_read_b128 v[226:229], v160 offset:1024
	ds_read_b128 v[232:235], v160 offset:2048
	ds_read_b128 v[236:239], v160 offset:3072
	global_load_lds_dwordx4 v174, vcc
	s_add_i32 m0, s74, 0x2000
	s_nop 0
	global_load_lds_dwordx4 v156, vcc
	s_barrier
	s_waitcnt lgkmcnt(0)
	s_waitcnt lgkmcnt(0)
	v_mfma_f32_16x16x32_bf16 v[116:119], v[208:211], v[144:147], v[116:119]
	v_mfma_f32_16x16x32_bf16 v[112:115], v[232:235], v[144:147], v[112:115]
	v_mfma_f32_16x16x32_bf16 v[100:103], v[208:211], v[152:155], v[100:103]
	v_mfma_f32_16x16x32_bf16 v[96:99], v[232:235], v[152:155], v[96:99]
	v_mfma_f32_16x16x32_bf16 v[84:87], v[208:211], v[190:193], v[84:87]
	v_mfma_f32_16x16x32_bf16 v[80:83], v[232:235], v[190:193], v[80:83]
	v_mfma_f32_16x16x32_bf16 v[68:71], v[208:211], v[198:201], v[68:71]
	v_mfma_f32_16x16x32_bf16 v[64:67], v[232:235], v[198:201], v[64:67]
	v_mfma_f32_16x16x32_bf16 v[116:119], v[226:229], v[148:151], v[116:119]
	v_mfma_f32_16x16x32_bf16 v[112:115], v[236:239], v[148:151], v[112:115]
	v_mfma_f32_16x16x32_bf16 v[100:103], v[226:229], v[186:189], v[100:103]
	v_mfma_f32_16x16x32_bf16 v[96:99], v[236:239], v[186:189], v[96:99]
	v_mfma_f32_16x16x32_bf16 v[84:87], v[226:229], v[194:197], v[84:87]
	v_mfma_f32_16x16x32_bf16 v[80:83], v[236:239], v[194:197], v[80:83]
	v_mfma_f32_16x16x32_bf16 v[68:71], v[226:229], v[204:207], v[68:71]
	v_mfma_f32_16x16x32_bf16 v[64:67], v[236:239], v[204:207], v[64:67]
	s_mov_b32 m0, s51
	v_lshl_add_u64 v[240:241], s[48:49], 0, v[176:177]
	s_barrier
	ds_read_b128 v[144:147], v203 offset:16384
	ds_read_b128 v[148:151], v203 offset:17408
	ds_read_b128 v[152:155], v203 offset:18432
	ds_read_b128 v[186:189], v203 offset:19456
	ds_read_b128 v[190:193], v203 offset:20480
	ds_read_b128 v[194:197], v203 offset:21504
	ds_read_b128 v[198:201], v203 offset:22528
	ds_read_b128 v[204:207], v203 offset:23552
	global_load_lds_dwordx4 v176, s[48:49]
	v_lshl_add_u64 v[242:243], s[48:49], 0, v[158:159]
	s_mov_b32 m0, s62
	s_nop 0
	global_load_lds_dwordx4 v158, s[48:49]
	s_barrier
	s_waitcnt lgkmcnt(0)
	s_waitcnt lgkmcnt(0)
	v_mfma_f32_16x16x32_bf16 v[60:63], v[128:131], v[144:147], v[60:63]
	v_mfma_f32_16x16x32_bf16 v[56:59], v[136:139], v[144:147], v[56:59]
	v_mfma_f32_16x16x32_bf16 v[44:47], v[128:131], v[152:155], v[44:47]
	v_mfma_f32_16x16x32_bf16 v[40:43], v[136:139], v[152:155], v[40:43]
	v_mfma_f32_16x16x32_bf16 v[28:31], v[128:131], v[190:193], v[28:31]
	v_mfma_f32_16x16x32_bf16 v[24:27], v[136:139], v[190:193], v[24:27]
	v_mfma_f32_16x16x32_bf16 v[12:15], v[128:131], v[198:201], v[12:15]
	v_mfma_f32_16x16x32_bf16 v[8:11], v[136:139], v[198:201], v[8:11]
	v_mfma_f32_16x16x32_bf16 v[60:63], v[132:135], v[148:151], v[60:63]
	v_mfma_f32_16x16x32_bf16 v[56:59], v[140:143], v[148:151], v[56:59]
	v_mfma_f32_16x16x32_bf16 v[44:47], v[132:135], v[186:189], v[44:47]
	v_mfma_f32_16x16x32_bf16 v[40:43], v[140:143], v[186:189], v[40:43]
	v_mfma_f32_16x16x32_bf16 v[28:31], v[132:135], v[194:197], v[28:31]
	v_mfma_f32_16x16x32_bf16 v[24:27], v[140:143], v[194:197], v[24:27]
	v_mfma_f32_16x16x32_bf16 v[12:15], v[132:135], v[204:207], v[12:15]
	v_mfma_f32_16x16x32_bf16 v[8:11], v[140:143], v[204:207], v[8:11]
	s_barrier
	s_add_u32 s74, vcc_lo, 0x40000
	s_addc_u32 s75, vcc_hi, 0
	s_add_i32 s76, s76, s7
	s_mov_b32 m0, s76
	s_nop 0
	global_load_lds_dwordx4 v174, s[74:75]
	s_add_i32 m0, s76, 0x2000
	s_nop 0
	global_load_lds_dwordx4 v156, s[74:75]
	s_waitcnt vmcnt(6)
	s_barrier
; #define PG8_STAGE(bufoff, gbase, voff) do { _Pragma("unroll") for (int _i = 0; _i < 2; ++_i) \
;     __builtin_amdgcn_global_load_lds((const unsigned*)((const char*)(gbase) + (voff)[_i]), (LAS unsigned*)(lds + (bufoff) + ldsw + _i * 8192), 16, 0, 0); } while (0)
; #define PG8_LDA(dst, b, h) do { _Pragma("unroll") for (int m = 0; m < 4; ++m) _Pragma("unroll") for (int k = 0; k < 2; ++k) dst[m][k] = *(const LAS bf16x8*)(lds + PG8_SA(b, h) + aoff + m * 2048 + k * 1024); } while (0)
; #define PG8_LDB(dst, b, h) do { _Pragma("unroll") for (int n = 0; n < 2; ++n) _Pragma("unroll") for (int k = 0; k < 2; ++k) dst[n][k] = *(const LAS bf16x8*)(lds + PG8_SB(b, h) + boff + n * 2048 + k * 1024); } while (0)
; #define PG8_MMA(ai, bj, At, Bt) do { __builtin_amdgcn_s_setprio(1); _Pragma("unroll") for (int m = 0; m < 4; ++m) _Pragma("unroll") for (int n = 0; n < 2; ++n) _Pragma("unroll") for (int k = 0; k < 2; ++k) \
;     acc[ai][bj][m][n] = __builtin_amdgcn_mfma_f32_16x16x32_bf16(Bt[n][k], At[m][k], acc[ai][bj][m][n], 0, 0, 0); __builtin_amdgcn_s_setprio(0); } while (0)
; #define PG8_WAIT_V(n) asm volatile("s_waitcnt vmcnt(" #n ")" ::: "memory")
; #define PG8_WAIT_L(n) asm volatile("s_waitcnt lgkmcnt(" #n ")" ::: "memory")
; #define PG8_BAR __builtin_amdgcn_s_barrier()
; #define PG8_SCHED __builtin_amdgcn_sched_barrier(0)
; template <class Epi, class Sched>
; __device__ __forceinline__ void gemm_phase(LAS unsigned char* lds, const Gemm g, const Sched& S, const Epi& E) {
;     ...
;       PG8_WAIT_V(6); PG8_BAR; PG8_MMA(1, 1, At, B1); PG8_BAR;
;       PG8_LDB(B0, 1, 0); PG8_SCHED; PG8_LDA(At, 1, 0); PG8_STAGE(PG8_SA(0, 1), a2 + hstep, voffA);
;       PG8_WAIT_L(8); PG8_BAR; PG8_WAIT_L(0); PG8_MMA(0, 0, At, B0); PG8_BAR; PG8_SCHED;
;       PG8_LDB(B1, 1, 1); PG8_STAGE(PG8_SB(1, 0), b3, voffB);
	v_mfma_f32_16x16x32_bf16 v[52:55], v[208:211], v[144:147], v[52:55]
	v_mfma_f32_16x16x32_bf16 v[48:51], v[232:235], v[144:147], v[48:51]
	v_mfma_f32_16x16x32_bf16 v[36:39], v[208:211], v[152:155], v[36:39]
	v_mfma_f32_16x16x32_bf16 v[32:35], v[232:235], v[152:155], v[32:35]
	v_mfma_f32_16x16x32_bf16 v[20:23], v[208:211], v[190:193], v[20:23]
	v_mfma_f32_16x16x32_bf16 v[16:19], v[232:235], v[190:193], v[16:19]
	v_mfma_f32_16x16x32_bf16 v[4:7], v[208:211], v[198:201], v[4:7]
	v_mfma_f32_16x16x32_bf16 v[0:3], v[232:235], v[198:201], v[0:3]
	v_mfma_f32_16x16x32_bf16 v[52:55], v[226:229], v[148:151], v[52:55]
	v_mfma_f32_16x16x32_bf16 v[48:51], v[236:239], v[148:151], v[48:51]
	v_mfma_f32_16x16x32_bf16 v[36:39], v[226:229], v[186:189], v[36:39]
	v_mfma_f32_16x16x32_bf16 v[32:35], v[236:239], v[186:189], v[32:35]
	v_mfma_f32_16x16x32_bf16 v[20:23], v[226:229], v[194:197], v[20:23]
	v_mfma_f32_16x16x32_bf16 v[16:19], v[236:239], v[194:197], v[16:19]
	v_mfma_f32_16x16x32_bf16 v[4:7], v[226:229], v[204:207], v[4:7]
	v_mfma_f32_16x16x32_bf16 v[0:3], v[236:239], v[204:207], v[0:3]
	s_add_i32 s74, 0, 0x18000
	v_add_u32_e32 v140, s74, v202
	s_barrier
	ds_read_b128 v[128:131], v140
	ds_read_b128 v[132:135], v140 offset:1024
	ds_read_b128 v[136:139], v140 offset:2048
	ds_read_b128 v[140:143], v140 offset:3072
	s_add_u32 s48, s48, 0x40000
	s_addc_u32 s49, s49, 0
	s_mov_b32 m0, s63
	ds_read_b128 v[144:147], v203 offset:32768
	ds_read_b128 v[148:151], v203 offset:33792
	ds_read_b128 v[152:155], v203 offset:34816
	ds_read_b128 v[186:189], v203 offset:35840
	ds_read_b128 v[190:193], v203 offset:36864
	ds_read_b128 v[194:197], v203 offset:37888
	ds_read_b128 v[198:201], v203 offset:38912
	ds_read_b128 v[204:207], v203 offset:39936
	global_load_lds_dwordx4 v176, s[48:49]
	s_mov_b32 m0, s64
	s_nop 0
	global_load_lds_dwordx4 v158, s[48:49]
	s_waitcnt lgkmcnt(8)
	s_barrier
	s_waitcnt lgkmcnt(0)
	s_waitcnt lgkmcnt(0)
	v_mfma_f32_16x16x32_bf16 v[124:127], v[128:131], v[144:147], v[124:127]
	v_mfma_f32_16x16x32_bf16 v[120:123], v[136:139], v[144:147], v[120:123]
	v_mfma_f32_16x16x32_bf16 v[108:111], v[128:131], v[152:155], v[108:111]
	v_mfma_f32_16x16x32_bf16 v[104:107], v[136:139], v[152:155], v[104:107]
	v_mfma_f32_16x16x32_bf16 v[92:95], v[128:131], v[190:193], v[92:95]
	v_mfma_f32_16x16x32_bf16 v[88:91], v[136:139], v[190:193], v[88:91]
	v_mfma_f32_16x16x32_bf16 v[76:79], v[128:131], v[198:201], v[76:79]
	v_mfma_f32_16x16x32_bf16 v[72:75], v[136:139], v[198:201], v[72:75]
	v_mfma_f32_16x16x32_bf16 v[124:127], v[132:135], v[148:151], v[124:127]
	v_mfma_f32_16x16x32_bf16 v[120:123], v[140:143], v[148:151], v[120:123]
	v_mfma_f32_16x16x32_bf16 v[108:111], v[132:135], v[186:189], v[108:111]
	v_mfma_f32_16x16x32_bf16 v[104:107], v[140:143], v[186:189], v[104:107]
	v_mfma_f32_16x16x32_bf16 v[92:95], v[132:135], v[194:197], v[92:95]
	v_mfma_f32_16x16x32_bf16 v[88:91], v[140:143], v[194:197], v[88:91]
	v_mfma_f32_16x16x32_bf16 v[76:79], v[132:135], v[204:207], v[76:79]
	v_mfma_f32_16x16x32_bf16 v[72:75], v[140:143], v[204:207], v[72:75]
	s_barrier
	s_add_i32 s75, 0, 0x1c000
	s_add_i32 s48, s74, s7
	v_add_u32_e32 v160, s75, v202
	s_add_u32 s60, vcc_lo, s80
	s_addc_u32 s61, vcc_hi, s81
	s_mov_b32 m0, s48
	ds_read_b128 v[208:211], v160
	ds_read_b128 v[226:229], v160 offset:1024
	ds_read_b128 v[232:235], v160 offset:2048
	ds_read_b128 v[236:239], v160 offset:3072
	global_load_lds_dwordx4 v174, s[60:61]
	s_add_i32 m0, s48, 0x2000
	s_nop 0
	global_load_lds_dwordx4 v156, s[60:61]
	s_barrier
; #define PG8_STAGE(bufoff, gbase, voff) do { _Pragma("unroll") for (int _i = 0; _i < 2; ++_i) \
;     __builtin_amdgcn_global_load_lds((const unsigned*)((const char*)(gbase) + (voff)[_i]), (LAS unsigned*)(lds + (bufoff) + ldsw + _i * 8192), 16, 0, 0); } while (0)
; #define PG8_LDA(dst, b, h) do { _Pragma("unroll") for (int m = 0; m < 4; ++m) _Pragma("unroll") for (int k = 0; k < 2; ++k) dst[m][k] = *(const LAS bf16x8*)(lds + PG8_SA(b, h) + aoff + m * 2048 + k * 1024); } while (0)
; #define PG8_MMA(ai, bj, At, Bt) do { __builtin_amdgcn_s_setprio(1); _Pragma("unroll") for (int m = 0; m < 4; ++m) _Pragma("unroll") for (int n = 0; n < 2; ++n) _Pragma("unroll") for (int k = 0; k < 2; ++k) \
;     acc[ai][bj][m][n] = __builtin_amdgcn_mfma_f32_16x16x32_bf16(Bt[n][k], At[m][k], acc[ai][bj][m][n], 0, 0, 0); __builtin_amdgcn_s_setprio(0); } while (0)
; #define PG8_WAIT_V(n) asm volatile("s_waitcnt vmcnt(" #n ")" ::: "memory")
; #define PG8_WAIT_L(n) asm volatile("s_waitcnt lgkmcnt(" #n ")" ::: "memory")
; #define PG8_BAR __builtin_amdgcn_s_barrier()
; #define PG8_SCHED __builtin_amdgcn_sched_barrier(0)
; template <class Epi, class Sched>
; __device__ __forceinline__ void gemm_phase(LAS unsigned char* lds, const Gemm g, const Sched& S, const Epi& E) {
;     ...
;       PG8_BAR; PG8_WAIT_L(0); PG8_MMA(0, 1, At, B1); PG8_BAR;
;       PG8_LDA(At, 1, 1); PG8_STAGE(PG8_SA(1, 0), a3, voffA);
;       PG8_BAR; PG8_WAIT_L(0); PG8_MMA(1, 0, At, B0); PG8_BAR; PG8_SCHED;
;       PG8_STAGE(PG8_SB(1, 1), b3 + hstep, voffB);
;       PG8_WAIT_V(6); PG8_BAR; PG8_MMA(1, 1, At, B1); PG8_BAR;
	s_waitcnt lgkmcnt(0)
	s_waitcnt lgkmcnt(0)
	v_mfma_f32_16x16x32_bf16 v[116:119], v[208:211], v[144:147], v[116:119]
	v_mfma_f32_16x16x32_bf16 v[112:115], v[232:235], v[144:147], v[112:115]
	v_mfma_f32_16x16x32_bf16 v[100:103], v[208:211], v[152:155], v[100:103]
	v_mfma_f32_16x16x32_bf16 v[96:99], v[232:235], v[152:155], v[96:99]
	v_mfma_f32_16x16x32_bf16 v[84:87], v[208:211], v[190:193], v[84:87]
	v_mfma_f32_16x16x32_bf16 v[80:83], v[232:235], v[190:193], v[80:83]
	v_mfma_f32_16x16x32_bf16 v[68:71], v[208:211], v[198:201], v[68:71]
	v_mfma_f32_16x16x32_bf16 v[64:67], v[232:235], v[198:201], v[64:67]
	v_mfma_f32_16x16x32_bf16 v[116:119], v[226:229], v[148:151], v[116:119]
	v_mfma_f32_16x16x32_bf16 v[112:115], v[236:239], v[148:151], v[112:115]
	v_mfma_f32_16x16x32_bf16 v[100:103], v[226:229], v[186:189], v[100:103]
	v_mfma_f32_16x16x32_bf16 v[96:99], v[236:239], v[186:189], v[96:99]
	v_mfma_f32_16x16x32_bf16 v[84:87], v[226:229], v[194:197], v[84:87]
	v_mfma_f32_16x16x32_bf16 v[80:83], v[236:239], v[194:197], v[80:83]
	v_mfma_f32_16x16x32_bf16 v[68:71], v[226:229], v[204:207], v[68:71]
	v_mfma_f32_16x16x32_bf16 v[64:67], v[236:239], v[204:207], v[64:67]
	s_mov_b32 m0, s65
	v_lshl_add_u64 v[212:213], v[240:241], 0, s[80:81]
	s_barrier
	ds_read_b128 v[144:147], v203 offset:49152
	ds_read_b128 v[148:151], v203 offset:50176
	ds_read_b128 v[152:155], v203 offset:51200
	ds_read_b128 v[186:189], v203 offset:52224
	ds_read_b128 v[190:193], v203 offset:53248
	ds_read_b128 v[194:197], v203 offset:54272
	ds_read_b128 v[198:201], v203 offset:55296
	ds_read_b128 v[204:207], v203 offset:56320
	global_load_lds_dwordx4 v[212:213], off
	v_lshl_add_u64 v[212:213], v[242:243], 0, s[80:81]
	s_mov_b32 m0, s70
	s_nop 0
	global_load_lds_dwordx4 v[212:213], off
	s_barrier
	s_waitcnt lgkmcnt(0)
	s_waitcnt lgkmcnt(0)
	v_mfma_f32_16x16x32_bf16 v[60:63], v[128:131], v[144:147], v[60:63]
	v_mfma_f32_16x16x32_bf16 v[56:59], v[136:139], v[144:147], v[56:59]
	v_mfma_f32_16x16x32_bf16 v[44:47], v[128:131], v[152:155], v[44:47]
	v_mfma_f32_16x16x32_bf16 v[40:43], v[136:139], v[152:155], v[40:43]
	v_mfma_f32_16x16x32_bf16 v[28:31], v[128:131], v[190:193], v[28:31]
	v_mfma_f32_16x16x32_bf16 v[24:27], v[136:139], v[190:193], v[24:27]
	v_mfma_f32_16x16x32_bf16 v[12:15], v[128:131], v[198:201], v[12:15]
	v_mfma_f32_16x16x32_bf16 v[8:11], v[136:139], v[198:201], v[8:11]
	v_mfma_f32_16x16x32_bf16 v[60:63], v[132:135], v[148:151], v[60:63]
	v_mfma_f32_16x16x32_bf16 v[56:59], v[140:143], v[148:151], v[56:59]
	v_mfma_f32_16x16x32_bf16 v[44:47], v[132:135], v[186:189], v[44:47]
	v_mfma_f32_16x16x32_bf16 v[40:43], v[140:143], v[186:189], v[40:43]
	v_mfma_f32_16x16x32_bf16 v[28:31], v[132:135], v[194:197], v[28:31]
	v_mfma_f32_16x16x32_bf16 v[24:27], v[140:143], v[194:197], v[24:27]
	v_mfma_f32_16x16x32_bf16 v[12:15], v[132:135], v[204:207], v[12:15]
	v_mfma_f32_16x16x32_bf16 v[8:11], v[140:143], v[204:207], v[8:11]
	s_barrier
	s_add_u32 s48, vcc_lo, 0x40080
	s_addc_u32 s49, vcc_hi, 0
	s_add_i32 s74, s75, s7
	s_mov_b32 m0, s74
	s_nop 0
	global_load_lds_dwordx4 v174, s[48:49]
	s_add_i32 m0, s74, 0x2000
	s_nop 0
	global_load_lds_dwordx4 v156, s[48:49]
	s_waitcnt vmcnt(6)
	s_barrier
	v_mfma_f32_16x16x32_bf16 v[52:55], v[208:211], v[144:147], v[52:55]
	v_mfma_f32_16x16x32_bf16 v[48:51], v[232:235], v[144:147], v[48:51]
	v_mfma_f32_16x16x32_bf16 v[36:39], v[208:211], v[152:155], v[36:39]
	v_mfma_f32_16x16x32_bf16 v[32:35], v[232:235], v[152:155], v[32:35]
	v_mfma_f32_16x16x32_bf16 v[20:23], v[208:211], v[190:193], v[20:23]
	v_mfma_f32_16x16x32_bf16 v[16:19], v[232:235], v[190:193], v[16:19]
	v_mfma_f32_16x16x32_bf16 v[4:7], v[208:211], v[198:201], v[4:7]
	v_mfma_f32_16x16x32_bf16 v[0:3], v[232:235], v[198:201], v[0:3]
	v_mfma_f32_16x16x32_bf16 v[52:55], v[226:229], v[148:151], v[52:55]
	v_mfma_f32_16x16x32_bf16 v[48:51], v[236:239], v[148:151], v[48:51]
	v_mfma_f32_16x16x32_bf16 v[36:39], v[226:229], v[186:189], v[36:39]
	v_mfma_f32_16x16x32_bf16 v[32:35], v[236:239], v[186:189], v[32:35]
	v_mfma_f32_16x16x32_bf16 v[20:23], v[226:229], v[194:197], v[20:23]
	v_mfma_f32_16x16x32_bf16 v[16:19], v[236:239], v[194:197], v[16:19]
	v_mfma_f32_16x16x32_bf16 v[4:7], v[226:229], v[204:207], v[4:7]
	v_mfma_f32_16x16x32_bf16 v[0:3], v[236:239], v[204:207], v[0:3]
	s_add_i32 s73, s73, 2
	s_add_u32 s34, s34, 0x100
	s_addc_u32 s35, s35, 0
	s_add_u32 s52, s52, 0x100
	s_addc_u32 s72, s72, 0
	s_cmp_gt_u32 s73, 13
	s_barrier
	s_cbranch_scc0 .LBB0_1057
	s_cmp_lt_u32 s101, 0x100
	s_cbranch_scc0 .Lxa_9
	s_barrier

; #define PG8_STAGE(bufoff, gbase, voff) do { _Pragma("unroll") for (int _i = 0; _i < 2; ++_i) \
;     __builtin_amdgcn_global_load_lds((const unsigned*)((const char*)(gbase) + (voff)[_i]), (LAS unsigned*)(lds + (bufoff) + ldsw + _i * 8192), 16, 0, 0); } while (0)
; #define PG8_LDA(dst, b, h) do { _Pragma("unroll") for (int m = 0; m < 4; ++m) _Pragma("unroll") for (int k = 0; k < 2; ++k) dst[m][k] = *(const LAS bf16x8*)(lds + PG8_SA(b, h) + aoff + m * 2048 + k * 1024); } while (0)
; #define PG8_LDB(dst, b, h) do { _Pragma("unroll") for (int n = 0; n < 2; ++n) _Pragma("unroll") for (int k = 0; k < 2; ++k) dst[n][k] = *(const LAS bf16x8*)(lds + PG8_SB(b, h) + boff + n * 2048 + k * 1024); } while (0)
; #define PG8_MMA(ai, bj, At, Bt) do { __builtin_amdgcn_s_setprio(1); _Pragma("unroll") for (int m = 0; m < 4; ++m) _Pragma("unroll") for (int n = 0; n < 2; ++n) _Pragma("unroll") for (int k = 0; k < 2; ++k) \
;     acc[ai][bj][m][n] = __builtin_amdgcn_mfma_f32_16x16x32_bf16(Bt[n][k], At[m][k], acc[ai][bj][m][n], 0, 0, 0); __builtin_amdgcn_s_setprio(0); } while (0)
; #define PG8_WAIT_V(n) asm volatile("s_waitcnt vmcnt(" #n ")" ::: "memory")
; #define PG8_WAIT_L(n) asm volatile("s_waitcnt lgkmcnt(" #n ")" ::: "memory")
; #define PG8_BAR __builtin_amdgcn_s_barrier()
; #define PG8_SCHED __builtin_amdgcn_sched_barrier(0)
; template <class Epi, class Sched>
; __device__ __forceinline__ void gemm_phase(LAS unsigned char* lds, const Gemm g, const Sched& S, const Epi& E) {
;     ...
;       PG8_LDB(B0, 0, 0); PG8_SCHED; PG8_LDA(At, 0, 0); PG8_STAGE(PG8_SA(1, 1), a1 + hstep, voffA);
;       PG8_WAIT_L(8); PG8_BAR; PG8_WAIT_L(0); PG8_MMA(0, 0, At, B0); PG8_BAR; PG8_SCHED;
;       PG8_LDB(B1, 0, 1); PG8_STAGE(PG8_SB(0, 0), b2, voffB);
;       PG8_BAR; PG8_WAIT_L(0); PG8_MMA(0, 1, At, B1); PG8_BAR;
;       PG8_LDA(At, 0, 1); PG8_STAGE(PG8_SA(0, 0), a2, voffA);
;       PG8_BAR; PG8_WAIT_L(0); PG8_MMA(1, 0, At, B0); PG8_BAR; PG8_SCHED;
;       PG8_STAGE(PG8_SB(0, 1), b2 + hstep, voffB);
;       PG8_WAIT_V(6); PG8_BAR; PG8_MMA(1, 1, At, B1); PG8_BAR;
.Lxs_e10:
.LBB0_1142:
	s_add_u32 s44, s42, 0xfffc0080
	s_addc_u32 s45, s43, -1
	s_add_i32 s74, 0, 0x10000
	v_add_u32_e32 v151, s74, v141
	ds_read_b128 v[152:155], v151
	ds_read_b128 v[156:159], v151 offset:1024
	ds_read_b128 v[174:177], v151 offset:2048
	ds_read_b128 v[178:181], v151 offset:3072
	s_cmp_eq_u32 s73, 12
	s_cselect_b32 s49, s35, s45
	s_cselect_b32 s48, s71, s44
	s_cselect_b32 s45, s23, s72
	s_cselect_b32 s44, vcc_lo, s52
	s_add_i32 m0, s12, 0xc000
	ds_read_b128 v[182:185], v150
	ds_read_b128 v[186:189], v150 offset:1024
	ds_read_b128 v[190:193], v150 offset:2048
	ds_read_b128 v[194:197], v150 offset:3072
	ds_read_b128 v[198:201], v150 offset:4096
	ds_read_b128 v[202:205], v150 offset:5120
	ds_read_b128 v[206:209], v150 offset:6144
	ds_read_b128 v[210:213], v150 offset:7168
	global_load_lds_dwordx4 v136, s[42:43]
	s_add_i32 m0, s12, 0xe000
	s_nop 0
	global_load_lds_dwordx4 v138, s[42:43]
	s_waitcnt lgkmcnt(8)
	s_barrier
	s_waitcnt lgkmcnt(0)
	s_waitcnt lgkmcnt(0)
	v_mfma_f32_16x16x32_bf16 v[124:127], v[152:155], v[182:185], v[124:127]
	v_mfma_f32_16x16x32_bf16 v[116:119], v[174:177], v[182:185], v[116:119]
	v_mfma_f32_16x16x32_bf16 v[108:111], v[152:155], v[190:193], v[108:111]
	v_mfma_f32_16x16x32_bf16 v[100:103], v[174:177], v[190:193], v[100:103]
	v_mfma_f32_16x16x32_bf16 v[92:95], v[152:155], v[198:201], v[92:95]
	v_mfma_f32_16x16x32_bf16 v[84:87], v[174:177], v[198:201], v[84:87]
	v_mfma_f32_16x16x32_bf16 v[76:79], v[152:155], v[206:209], v[76:79]
	v_mfma_f32_16x16x32_bf16 v[68:71], v[174:177], v[206:209], v[68:71]
	v_mfma_f32_16x16x32_bf16 v[124:127], v[156:159], v[186:189], v[124:127]
	v_mfma_f32_16x16x32_bf16 v[116:119], v[178:181], v[186:189], v[116:119]
	v_mfma_f32_16x16x32_bf16 v[108:111], v[156:159], v[194:197], v[108:111]
	v_mfma_f32_16x16x32_bf16 v[100:103], v[178:181], v[194:197], v[100:103]
	v_mfma_f32_16x16x32_bf16 v[92:95], v[156:159], v[202:205], v[92:95]
	v_mfma_f32_16x16x32_bf16 v[84:87], v[178:181], v[202:205], v[84:87]
	v_mfma_f32_16x16x32_bf16 v[76:79], v[156:159], v[210:213], v[76:79]
	v_mfma_f32_16x16x32_bf16 v[68:71], v[178:181], v[210:213], v[68:71]
	s_barrier
	s_add_i32 s76, 0, 0x14000
	s_add_i32 s74, s74, s7
	v_add_u32_e32 v151, s76, v141
	s_mov_b32 m0, s74
	ds_read_b128 v[226:229], v151
	ds_read_b128 v[232:235], v151 offset:1024
	ds_read_b128 v[236:239], v151 offset:2048
	ds_read_b128 v[240:243], v151 offset:3072
	global_load_lds_dwordx4 v132, s[44:45]
	s_add_i32 m0, s74, 0x2000
	s_nop 0
	global_load_lds_dwordx4 v128, s[44:45]
	s_barrier
	s_waitcnt lgkmcnt(0)
	s_waitcnt lgkmcnt(0)
	v_mfma_f32_16x16x32_bf16 v[120:123], v[226:229], v[182:185], v[120:123]
	v_mfma_f32_16x16x32_bf16 v[112:115], v[236:239], v[182:185], v[112:115]
	v_mfma_f32_16x16x32_bf16 v[104:107], v[226:229], v[190:193], v[104:107]
	v_mfma_f32_16x16x32_bf16 v[96:99], v[236:239], v[190:193], v[96:99]
	v_mfma_f32_16x16x32_bf16 v[88:91], v[226:229], v[198:201], v[88:91]
	v_mfma_f32_16x16x32_bf16 v[80:83], v[236:239], v[198:201], v[80:83]
	v_mfma_f32_16x16x32_bf16 v[72:75], v[226:229], v[206:209], v[72:75]
	v_mfma_f32_16x16x32_bf16 v[64:67], v[236:239], v[206:209], v[64:67]
	v_mfma_f32_16x16x32_bf16 v[120:123], v[232:235], v[186:189], v[120:123]
	v_mfma_f32_16x16x32_bf16 v[112:115], v[240:243], v[186:189], v[112:115]
	v_mfma_f32_16x16x32_bf16 v[104:107], v[232:235], v[194:197], v[104:107]
	v_mfma_f32_16x16x32_bf16 v[96:99], v[240:243], v[194:197], v[96:99]
	v_mfma_f32_16x16x32_bf16 v[88:91], v[232:235], v[202:205], v[88:91]
	v_mfma_f32_16x16x32_bf16 v[80:83], v[240:243], v[202:205], v[80:83]
	v_mfma_f32_16x16x32_bf16 v[72:75], v[232:235], v[210:213], v[72:75]
	v_mfma_f32_16x16x32_bf16 v[64:67], v[240:243], v[210:213], v[64:67]
	s_mov_b32 m0, s12
	v_lshl_add_u64 v[246:247], s[48:49], 0, v[134:135]
	s_barrier
	ds_read_b128 v[182:185], v150 offset:16384
	ds_read_b128 v[186:189], v150 offset:17408
	ds_read_b128 v[190:193], v150 offset:18432
	ds_read_b128 v[194:197], v150 offset:19456
	ds_read_b128 v[198:201], v150 offset:20480
	ds_read_b128 v[202:205], v150 offset:21504
	ds_read_b128 v[206:209], v150 offset:22528
	ds_read_b128 v[210:213], v150 offset:23552
	global_load_lds_dwordx4 v134, s[48:49]
	v_lshl_add_u64 v[248:249], s[48:49], 0, v[130:131]
	s_mov_b32 m0, s13
	s_nop 0
	global_load_lds_dwordx4 v130, s[48:49]
	s_barrier
	s_waitcnt lgkmcnt(0)
	s_waitcnt lgkmcnt(0)
	v_mfma_f32_16x16x32_bf16 v[60:63], v[152:155], v[182:185], v[60:63]
	v_mfma_f32_16x16x32_bf16 v[52:55], v[174:177], v[182:185], v[52:55]
	v_mfma_f32_16x16x32_bf16 v[44:47], v[152:155], v[190:193], v[44:47]
	v_mfma_f32_16x16x32_bf16 v[36:39], v[174:177], v[190:193], v[36:39]
	v_mfma_f32_16x16x32_bf16 v[28:31], v[152:155], v[198:201], v[28:31]
	v_mfma_f32_16x16x32_bf16 v[20:23], v[174:177], v[198:201], v[20:23]
	v_mfma_f32_16x16x32_bf16 v[12:15], v[152:155], v[206:209], v[12:15]
	v_mfma_f32_16x16x32_bf16 v[4:7], v[174:177], v[206:209], v[4:7]
	v_mfma_f32_16x16x32_bf16 v[60:63], v[156:159], v[186:189], v[60:63]
	v_mfma_f32_16x16x32_bf16 v[52:55], v[178:181], v[186:189], v[52:55]
	v_mfma_f32_16x16x32_bf16 v[44:47], v[156:159], v[194:197], v[44:47]
	v_mfma_f32_16x16x32_bf16 v[36:39], v[178:181], v[194:197], v[36:39]
	v_mfma_f32_16x16x32_bf16 v[28:31], v[156:159], v[202:205], v[28:31]
	v_mfma_f32_16x16x32_bf16 v[20:23], v[178:181], v[202:205], v[20:23]
	v_mfma_f32_16x16x32_bf16 v[12:15], v[156:159], v[210:213], v[12:15]
	v_mfma_f32_16x16x32_bf16 v[4:7], v[178:181], v[210:213], v[4:7]
	s_barrier
	s_add_u32 s74, s44, 0x40000
	s_addc_u32 s75, s45, 0
	s_add_i32 s76, s76, s7
	s_mov_b32 m0, s76
	s_nop 0
	global_load_lds_dwordx4 v132, s[74:75]
	s_add_i32 m0, s76, 0x2000
	s_nop 0
	global_load_lds_dwordx4 v128, s[74:75]
	s_waitcnt vmcnt(6)
	s_barrier
; #define PG8_STAGE(bufoff, gbase, voff) do { _Pragma("unroll") for (int _i = 0; _i < 2; ++_i) \
;     __builtin_amdgcn_global_load_lds((const unsigned*)((const char*)(gbase) + (voff)[_i]), (LAS unsigned*)(lds + (bufoff) + ldsw + _i * 8192), 16, 0, 0); } while (0)
; #define PG8_LDA(dst, b, h) do { _Pragma("unroll") for (int m = 0; m < 4; ++m) _Pragma("unroll") for (int k = 0; k < 2; ++k) dst[m][k] = *(const LAS bf16x8*)(lds + PG8_SA(b, h) + aoff + m * 2048 + k * 1024); } while (0)
; #define PG8_LDB(dst, b, h) do { _Pragma("unroll") for (int n = 0; n < 2; ++n) _Pragma("unroll") for (int k = 0; k < 2; ++k) dst[n][k] = *(const LAS bf16x8*)(lds + PG8_SB(b, h) + boff + n * 2048 + k * 1024); } while (0)
; #define PG8_MMA(ai, bj, At, Bt) do { __builtin_amdgcn_s_setprio(1); _Pragma("unroll") for (int m = 0; m < 4; ++m) _Pragma("unroll") for (int n = 0; n < 2; ++n) _Pragma("unroll") for (int k = 0; k < 2; ++k) \
;     acc[ai][bj][m][n] = __builtin_amdgcn_mfma_f32_16x16x32_bf16(Bt[n][k], At[m][k], acc[ai][bj][m][n], 0, 0, 0); __builtin_amdgcn_s_setprio(0); } while (0)
; #define PG8_WAIT_V(n) asm volatile("s_waitcnt vmcnt(" #n ")" ::: "memory")
; #define PG8_WAIT_L(n) asm volatile("s_waitcnt lgkmcnt(" #n ")" ::: "memory")
; #define PG8_BAR __builtin_amdgcn_s_barrier()
; #define PG8_SCHED __builtin_amdgcn_sched_barrier(0)
; template <class Epi, class Sched>
; __device__ __forceinline__ void gemm_phase(LAS unsigned char* lds, const Gemm g, const Sched& S, const Epi& E) {
;     ...
;       PG8_WAIT_V(6); PG8_BAR; PG8_MMA(1, 1, At, B1); PG8_BAR;
;       PG8_LDB(B0, 1, 0); PG8_SCHED; PG8_LDA(At, 1, 0); PG8_STAGE(PG8_SA(0, 1), a2 + hstep, voffA);
;       PG8_WAIT_L(8); PG8_BAR; PG8_WAIT_L(0); PG8_MMA(0, 0, At, B0); PG8_BAR; PG8_SCHED;
;       PG8_LDB(B1, 1, 1); PG8_STAGE(PG8_SB(1, 0), b3, voffB);
	v_mfma_f32_16x16x32_bf16 v[56:59], v[226:229], v[182:185], v[56:59]
	v_mfma_f32_16x16x32_bf16 v[48:51], v[236:239], v[182:185], v[48:51]
	v_mfma_f32_16x16x32_bf16 v[40:43], v[226:229], v[190:193], v[40:43]
	v_mfma_f32_16x16x32_bf16 v[32:35], v[236:239], v[190:193], v[32:35]
	v_mfma_f32_16x16x32_bf16 v[24:27], v[226:229], v[198:201], v[24:27]
	v_mfma_f32_16x16x32_bf16 v[16:19], v[236:239], v[198:201], v[16:19]
	v_mfma_f32_16x16x32_bf16 v[8:11], v[226:229], v[206:209], v[8:11]
	v_mfma_f32_16x16x32_bf16 v[0:3], v[236:239], v[206:209], v[0:3]
	v_mfma_f32_16x16x32_bf16 v[56:59], v[232:235], v[186:189], v[56:59]
	v_mfma_f32_16x16x32_bf16 v[48:51], v[240:243], v[186:189], v[48:51]
	v_mfma_f32_16x16x32_bf16 v[40:43], v[232:235], v[194:197], v[40:43]
	v_mfma_f32_16x16x32_bf16 v[32:35], v[240:243], v[194:197], v[32:35]
	v_mfma_f32_16x16x32_bf16 v[24:27], v[232:235], v[202:205], v[24:27]
	v_mfma_f32_16x16x32_bf16 v[16:19], v[240:243], v[202:205], v[16:19]
	v_mfma_f32_16x16x32_bf16 v[8:11], v[232:235], v[210:213], v[8:11]
	v_mfma_f32_16x16x32_bf16 v[0:3], v[240:243], v[210:213], v[0:3]
	s_add_i32 s74, 0, 0x18000
	v_add_u32_e32 v151, s74, v141
	s_barrier
	ds_read_b128 v[152:155], v151
	ds_read_b128 v[156:159], v151 offset:1024
	ds_read_b128 v[174:177], v151 offset:2048
	ds_read_b128 v[178:181], v151 offset:3072
	s_add_u32 s48, s48, 0x40000
	s_addc_u32 s49, s49, 0
	s_mov_b32 m0, s51
	ds_read_b128 v[182:185], v150 offset:32768
	ds_read_b128 v[186:189], v150 offset:33792
	ds_read_b128 v[190:193], v150 offset:34816
	ds_read_b128 v[194:197], v150 offset:35840
	ds_read_b128 v[198:201], v150 offset:36864
	ds_read_b128 v[202:205], v150 offset:37888
	ds_read_b128 v[206:209], v150 offset:38912
	ds_read_b128 v[210:213], v150 offset:39936
	global_load_lds_dwordx4 v134, s[48:49]
	s_mov_b32 m0, s62
	s_nop 0
	global_load_lds_dwordx4 v130, s[48:49]
	s_waitcnt lgkmcnt(8)
	s_barrier
	s_waitcnt lgkmcnt(0)
	s_waitcnt lgkmcnt(0)
	v_mfma_f32_16x16x32_bf16 v[124:127], v[152:155], v[182:185], v[124:127]
	v_mfma_f32_16x16x32_bf16 v[116:119], v[174:177], v[182:185], v[116:119]
	v_mfma_f32_16x16x32_bf16 v[108:111], v[152:155], v[190:193], v[108:111]
	v_mfma_f32_16x16x32_bf16 v[100:103], v[174:177], v[190:193], v[100:103]
	v_mfma_f32_16x16x32_bf16 v[92:95], v[152:155], v[198:201], v[92:95]
	v_mfma_f32_16x16x32_bf16 v[84:87], v[174:177], v[198:201], v[84:87]
	v_mfma_f32_16x16x32_bf16 v[76:79], v[152:155], v[206:209], v[76:79]
	v_mfma_f32_16x16x32_bf16 v[68:71], v[174:177], v[206:209], v[68:71]
	v_mfma_f32_16x16x32_bf16 v[124:127], v[156:159], v[186:189], v[124:127]
	v_mfma_f32_16x16x32_bf16 v[116:119], v[178:181], v[186:189], v[116:119]
	v_mfma_f32_16x16x32_bf16 v[108:111], v[156:159], v[194:197], v[108:111]
	v_mfma_f32_16x16x32_bf16 v[100:103], v[178:181], v[194:197], v[100:103]
	v_mfma_f32_16x16x32_bf16 v[92:95], v[156:159], v[202:205], v[92:95]
	v_mfma_f32_16x16x32_bf16 v[84:87], v[178:181], v[202:205], v[84:87]
	v_mfma_f32_16x16x32_bf16 v[76:79], v[156:159], v[210:213], v[76:79]
	v_mfma_f32_16x16x32_bf16 v[68:71], v[178:181], v[210:213], v[68:71]
	s_barrier
	s_add_i32 s48, 0, 0x1c000
	s_add_i32 s49, s74, s7
	v_add_u32_e32 v151, s48, v141
	s_add_u32 s60, s44, s80
	s_addc_u32 s61, s45, s81
	s_mov_b32 m0, s49
	ds_read_b128 v[226:229], v151
	ds_read_b128 v[232:235], v151 offset:1024
	ds_read_b128 v[236:239], v151 offset:2048
	ds_read_b128 v[240:243], v151 offset:3072
	global_load_lds_dwordx4 v132, s[60:61]
	s_add_i32 m0, s49, 0x2000
	s_nop 0
	global_load_lds_dwordx4 v128, s[60:61]
	s_barrier
; #define PG8_STAGE(bufoff, gbase, voff) do { _Pragma("unroll") for (int _i = 0; _i < 2; ++_i) \
;     __builtin_amdgcn_global_load_lds((const unsigned*)((const char*)(gbase) + (voff)[_i]), (LAS unsigned*)(lds + (bufoff) + ldsw + _i * 8192), 16, 0, 0); } while (0)
; #define PG8_LDA(dst, b, h) do { _Pragma("unroll") for (int m = 0; m < 4; ++m) _Pragma("unroll") for (int k = 0; k < 2; ++k) dst[m][k] = *(const LAS bf16x8*)(lds + PG8_SA(b, h) + aoff + m * 2048 + k * 1024); } while (0)
; #define PG8_MMA(ai, bj, At, Bt) do { __builtin_amdgcn_s_setprio(1); _Pragma("unroll") for (int m = 0; m < 4; ++m) _Pragma("unroll") for (int n = 0; n < 2; ++n) _Pragma("unroll") for (int k = 0; k < 2; ++k) \
;     acc[ai][bj][m][n] = __builtin_amdgcn_mfma_f32_16x16x32_bf16(Bt[n][k], At[m][k], acc[ai][bj][m][n], 0, 0, 0); __builtin_amdgcn_s_setprio(0); } while (0)
; #define PG8_WAIT_V(n) asm volatile("s_waitcnt vmcnt(" #n ")" ::: "memory")
; #define PG8_WAIT_L(n) asm volatile("s_waitcnt lgkmcnt(" #n ")" ::: "memory")
; #define PG8_BAR __builtin_amdgcn_s_barrier()
; #define PG8_SCHED __builtin_amdgcn_sched_barrier(0)
; template <class Epi, class Sched>
; __device__ __forceinline__ void gemm_phase(LAS unsigned char* lds, const Gemm g, const Sched& S, const Epi& E) {
;     ...
;       PG8_BAR; PG8_WAIT_L(0); PG8_MMA(0, 1, At, B1); PG8_BAR;
;       PG8_LDA(At, 1, 1); PG8_STAGE(PG8_SA(1, 0), a3, voffA);
;       PG8_BAR; PG8_WAIT_L(0); PG8_MMA(1, 0, At, B0); PG8_BAR; PG8_SCHED;
;       PG8_STAGE(PG8_SB(1, 1), b3 + hstep, voffB);
;       PG8_WAIT_V(6); PG8_BAR; PG8_MMA(1, 1, At, B1); PG8_BAR;
	s_waitcnt lgkmcnt(0)
	s_waitcnt lgkmcnt(0)
	v_mfma_f32_16x16x32_bf16 v[120:123], v[226:229], v[182:185], v[120:123]
	v_mfma_f32_16x16x32_bf16 v[112:115], v[236:239], v[182:185], v[112:115]
	v_mfma_f32_16x16x32_bf16 v[104:107], v[226:229], v[190:193], v[104:107]
	v_mfma_f32_16x16x32_bf16 v[96:99], v[236:239], v[190:193], v[96:99]
	v_mfma_f32_16x16x32_bf16 v[88:91], v[226:229], v[198:201], v[88:91]
	v_mfma_f32_16x16x32_bf16 v[80:83], v[236:239], v[198:201], v[80:83]
	v_mfma_f32_16x16x32_bf16 v[72:75], v[226:229], v[206:209], v[72:75]
	v_mfma_f32_16x16x32_bf16 v[64:67], v[236:239], v[206:209], v[64:67]
	v_mfma_f32_16x16x32_bf16 v[120:123], v[232:235], v[186:189], v[120:123]
	v_mfma_f32_16x16x32_bf16 v[112:115], v[240:243], v[186:189], v[112:115]
	v_mfma_f32_16x16x32_bf16 v[104:107], v[232:235], v[194:197], v[104:107]
	v_mfma_f32_16x16x32_bf16 v[96:99], v[240:243], v[194:197], v[96:99]
	v_mfma_f32_16x16x32_bf16 v[88:91], v[232:235], v[202:205], v[88:91]
	v_mfma_f32_16x16x32_bf16 v[80:83], v[240:243], v[202:205], v[80:83]
	v_mfma_f32_16x16x32_bf16 v[72:75], v[232:235], v[210:213], v[72:75]
	v_mfma_f32_16x16x32_bf16 v[64:67], v[240:243], v[210:213], v[64:67]
	s_mov_b32 m0, s63
	v_lshl_add_u64 v[222:223], v[246:247], 0, s[80:81]
	s_barrier
	ds_read_b128 v[182:185], v150 offset:49152
	ds_read_b128 v[186:189], v150 offset:50176
	ds_read_b128 v[190:193], v150 offset:51200
	ds_read_b128 v[194:197], v150 offset:52224
	ds_read_b128 v[198:201], v150 offset:53248
	ds_read_b128 v[202:205], v150 offset:54272
	ds_read_b128 v[206:209], v150 offset:55296
	ds_read_b128 v[210:213], v150 offset:56320
	global_load_lds_dwordx4 v[222:223], off
	v_lshl_add_u64 v[222:223], v[248:249], 0, s[80:81]
	s_mov_b32 m0, s64
	s_nop 0
	global_load_lds_dwordx4 v[222:223], off
	s_barrier
	s_waitcnt lgkmcnt(0)
	s_waitcnt lgkmcnt(0)
	v_mfma_f32_16x16x32_bf16 v[60:63], v[152:155], v[182:185], v[60:63]
	v_mfma_f32_16x16x32_bf16 v[52:55], v[174:177], v[182:185], v[52:55]
	v_mfma_f32_16x16x32_bf16 v[44:47], v[152:155], v[190:193], v[44:47]
	v_mfma_f32_16x16x32_bf16 v[36:39], v[174:177], v[190:193], v[36:39]
	v_mfma_f32_16x16x32_bf16 v[28:31], v[152:155], v[198:201], v[28:31]
	v_mfma_f32_16x16x32_bf16 v[20:23], v[174:177], v[198:201], v[20:23]
	v_mfma_f32_16x16x32_bf16 v[12:15], v[152:155], v[206:209], v[12:15]
	v_mfma_f32_16x16x32_bf16 v[4:7], v[174:177], v[206:209], v[4:7]
	v_mfma_f32_16x16x32_bf16 v[60:63], v[156:159], v[186:189], v[60:63]
	v_mfma_f32_16x16x32_bf16 v[52:55], v[178:181], v[186:189], v[52:55]
	v_mfma_f32_16x16x32_bf16 v[44:47], v[156:159], v[194:197], v[44:47]
	v_mfma_f32_16x16x32_bf16 v[36:39], v[178:181], v[194:197], v[36:39]
	v_mfma_f32_16x16x32_bf16 v[28:31], v[156:159], v[202:205], v[28:31]
	v_mfma_f32_16x16x32_bf16 v[20:23], v[178:181], v[202:205], v[20:23]
	v_mfma_f32_16x16x32_bf16 v[12:15], v[156:159], v[210:213], v[12:15]
	v_mfma_f32_16x16x32_bf16 v[4:7], v[178:181], v[210:213], v[4:7]
	s_barrier
	s_add_u32 s44, s44, 0x40080
	s_addc_u32 s45, s45, 0
	s_add_i32 s48, s48, s7
	s_mov_b32 m0, s48
	s_nop 0
	global_load_lds_dwordx4 v132, s[44:45]
	s_add_i32 m0, s48, 0x2000
	s_nop 0
	global_load_lds_dwordx4 v128, s[44:45]
	s_waitcnt vmcnt(6)
	s_barrier
	v_mfma_f32_16x16x32_bf16 v[56:59], v[226:229], v[182:185], v[56:59]
	v_mfma_f32_16x16x32_bf16 v[48:51], v[236:239], v[182:185], v[48:51]
	v_mfma_f32_16x16x32_bf16 v[40:43], v[226:229], v[190:193], v[40:43]
	v_mfma_f32_16x16x32_bf16 v[32:35], v[236:239], v[190:193], v[32:35]
	v_mfma_f32_16x16x32_bf16 v[24:27], v[226:229], v[198:201], v[24:27]
	v_mfma_f32_16x16x32_bf16 v[16:19], v[236:239], v[198:201], v[16:19]
	v_mfma_f32_16x16x32_bf16 v[8:11], v[226:229], v[206:209], v[8:11]
	v_mfma_f32_16x16x32_bf16 v[0:3], v[236:239], v[206:209], v[0:3]
	v_mfma_f32_16x16x32_bf16 v[56:59], v[232:235], v[186:189], v[56:59]
	v_mfma_f32_16x16x32_bf16 v[48:51], v[240:243], v[186:189], v[48:51]
	v_mfma_f32_16x16x32_bf16 v[40:43], v[232:235], v[194:197], v[40:43]
	v_mfma_f32_16x16x32_bf16 v[32:35], v[240:243], v[194:197], v[32:35]
	v_mfma_f32_16x16x32_bf16 v[24:27], v[232:235], v[202:205], v[24:27]
	v_mfma_f32_16x16x32_bf16 v[16:19], v[240:243], v[202:205], v[16:19]
	v_mfma_f32_16x16x32_bf16 v[8:11], v[232:235], v[210:213], v[8:11]
	v_mfma_f32_16x16x32_bf16 v[0:3], v[240:243], v[210:213], v[0:3]
	s_add_i32 s73, s73, 2
	s_add_u32 s42, s42, 0x100
	s_addc_u32 s43, s43, 0
	s_add_u32 s52, s52, 0x100
	s_addc_u32 s72, s72, 0
	s_cmp_gt_u32 s73, 13
	s_barrier
	s_cbranch_scc0 .LBB0_1142
	s_cmp_lt_u32 s101, 0x100
	s_cbranch_scc0 .Lxa_10
	s_barrier

; #define PG8_STAGE(bufoff, gbase, voff) do { _Pragma("unroll") for (int _i = 0; _i < 2; ++_i) \
;     __builtin_amdgcn_global_load_lds((const unsigned*)((const char*)(gbase) + (voff)[_i]), (LAS unsigned*)(lds + (bufoff) + ldsw + _i * 8192), 16, 0, 0); } while (0)
; #define PG8_LDA(dst, b, h) do { _Pragma("unroll") for (int m = 0; m < 4; ++m) _Pragma("unroll") for (int k = 0; k < 2; ++k) dst[m][k] = *(const LAS bf16x8*)(lds + PG8_SA(b, h) + aoff + m * 2048 + k * 1024); } while (0)
; #define PG8_LDB(dst, b, h) do { _Pragma("unroll") for (int n = 0; n < 2; ++n) _Pragma("unroll") for (int k = 0; k < 2; ++k) dst[n][k] = *(const LAS bf16x8*)(lds + PG8_SB(b, h) + boff + n * 2048 + k * 1024); } while (0)
; #define PG8_MMA(ai, bj, At, Bt) do { __builtin_amdgcn_s_setprio(1); _Pragma("unroll") for (int m = 0; m < 4; ++m) _Pragma("unroll") for (int n = 0; n < 2; ++n) _Pragma("unroll") for (int k = 0; k < 2; ++k) \
;     acc[ai][bj][m][n] = __builtin_amdgcn_mfma_f32_16x16x32_bf16(Bt[n][k], At[m][k], acc[ai][bj][m][n], 0, 0, 0); __builtin_amdgcn_s_setprio(0); } while (0)
; #define PG8_WAIT_V(n) asm volatile("s_waitcnt vmcnt(" #n ")" ::: "memory")
; #define PG8_WAIT_L(n) asm volatile("s_waitcnt lgkmcnt(" #n ")" ::: "memory")
; #define PG8_BAR __builtin_amdgcn_s_barrier()
; #define PG8_SCHED __builtin_amdgcn_sched_barrier(0)
; template <class Epi, class Sched>
; __device__ __forceinline__ void gemm_phase(LAS unsigned char* lds, const Gemm g, const Sched& S, const Epi& E) {
;     ...
;       PG8_LDB(B0, 0, 0); PG8_SCHED; PG8_LDA(At, 0, 0); PG8_STAGE(PG8_SA(1, 1), a1 + hstep, voffA);
;       PG8_WAIT_L(8); PG8_BAR; PG8_WAIT_L(0); PG8_MMA(0, 0, At, B0); PG8_BAR; PG8_SCHED;
;       PG8_LDB(B1, 0, 1); PG8_STAGE(PG8_SB(0, 0), b2, voffB);
;       PG8_BAR; PG8_WAIT_L(0); PG8_MMA(0, 1, At, B1); PG8_BAR;
;       PG8_LDA(At, 0, 1); PG8_STAGE(PG8_SA(0, 0), a2, voffA);
;       PG8_BAR; PG8_WAIT_L(0); PG8_MMA(1, 0, At, B0); PG8_BAR; PG8_SCHED;
;       PG8_STAGE(PG8_SB(0, 1), b2 + hstep, voffB);
;       PG8_WAIT_V(6); PG8_BAR; PG8_MMA(1, 1, At, B1); PG8_BAR;
.Lxs_e11:
.LBB0_1215:
	s_add_u32 s42, s34, 0x100
	s_addc_u32 s43, s35, 0
	s_add_i32 s74, 0, 0x10000
	v_add_u32_e32 v140, s74, v202
	ds_read_b128 v[128:131], v140
	ds_read_b128 v[132:135], v140 offset:1024
	ds_read_b128 v[136:139], v140 offset:2048
	ds_read_b128 v[140:143], v140 offset:3072
	s_cmp_eq_u32 s73, 40
	s_cselect_b32 s49, s23, s43
	s_cselect_b32 s48, s22, s42
	s_cselect_b32 s45, s41, s72
	s_cselect_b32 s44, s40, s52
	s_add_i32 m0, s51, 0xc000
	ds_read_b128 v[144:147], v203
	ds_read_b128 v[148:151], v203 offset:1024
	ds_read_b128 v[152:155], v203 offset:2048
	ds_read_b128 v[186:189], v203 offset:3072
	ds_read_b128 v[190:193], v203 offset:4096
	ds_read_b128 v[194:197], v203 offset:5120
	ds_read_b128 v[198:201], v203 offset:6144
	ds_read_b128 v[204:207], v203 offset:7168
	global_load_lds_dwordx4 v182, s[34:35]
	s_add_i32 m0, s51, 0xe000
	s_nop 0
	global_load_lds_dwordx4 v184, s[34:35]
	s_waitcnt lgkmcnt(8)
	s_barrier
	s_waitcnt lgkmcnt(0)
	s_waitcnt lgkmcnt(0)
	v_mfma_f32_16x16x32_bf16 v[124:127], v[128:131], v[144:147], v[124:127]
	v_mfma_f32_16x16x32_bf16 v[120:123], v[136:139], v[144:147], v[120:123]
	v_mfma_f32_16x16x32_bf16 v[108:111], v[128:131], v[152:155], v[108:111]
	v_mfma_f32_16x16x32_bf16 v[104:107], v[136:139], v[152:155], v[104:107]
	v_mfma_f32_16x16x32_bf16 v[92:95], v[128:131], v[190:193], v[92:95]
	v_mfma_f32_16x16x32_bf16 v[88:91], v[136:139], v[190:193], v[88:91]
	v_mfma_f32_16x16x32_bf16 v[76:79], v[128:131], v[198:201], v[76:79]
	v_mfma_f32_16x16x32_bf16 v[72:75], v[136:139], v[198:201], v[72:75]
	v_mfma_f32_16x16x32_bf16 v[124:127], v[132:135], v[148:151], v[124:127]
	v_mfma_f32_16x16x32_bf16 v[120:123], v[140:143], v[148:151], v[120:123]
	v_mfma_f32_16x16x32_bf16 v[108:111], v[132:135], v[186:189], v[108:111]
	v_mfma_f32_16x16x32_bf16 v[104:107], v[140:143], v[186:189], v[104:107]
	v_mfma_f32_16x16x32_bf16 v[92:95], v[132:135], v[194:197], v[92:95]
	v_mfma_f32_16x16x32_bf16 v[88:91], v[140:143], v[194:197], v[88:91]
	v_mfma_f32_16x16x32_bf16 v[76:79], v[132:135], v[204:207], v[76:79]
	v_mfma_f32_16x16x32_bf16 v[72:75], v[140:143], v[204:207], v[72:75]
	s_barrier
	s_add_i32 s75, 0, 0x14000
	s_add_i32 s34, s74, s7
	v_add_u32_e32 v160, s75, v202
	s_mov_b32 m0, s34
	ds_read_b128 v[208:211], v160
	ds_read_b128 v[226:229], v160 offset:1024
	ds_read_b128 v[232:235], v160 offset:2048
	ds_read_b128 v[236:239], v160 offset:3072
	global_load_lds_dwordx4 v174, s[44:45]
	s_add_i32 m0, s34, 0x2000
	s_nop 0
	global_load_lds_dwordx4 v156, s[44:45]
	s_barrier
	s_waitcnt lgkmcnt(0)
	s_waitcnt lgkmcnt(0)
	v_mfma_f32_16x16x32_bf16 v[116:119], v[208:211], v[144:147], v[116:119]
	v_mfma_f32_16x16x32_bf16 v[112:115], v[232:235], v[144:147], v[112:115]
	v_mfma_f32_16x16x32_bf16 v[100:103], v[208:211], v[152:155], v[100:103]
	v_mfma_f32_16x16x32_bf16 v[96:99], v[232:235], v[152:155], v[96:99]
	v_mfma_f32_16x16x32_bf16 v[84:87], v[208:211], v[190:193], v[84:87]
	v_mfma_f32_16x16x32_bf16 v[80:83], v[232:235], v[190:193], v[80:83]
	v_mfma_f32_16x16x32_bf16 v[68:71], v[208:211], v[198:201], v[68:71]
	v_mfma_f32_16x16x32_bf16 v[64:67], v[232:235], v[198:201], v[64:67]
	v_mfma_f32_16x16x32_bf16 v[116:119], v[226:229], v[148:151], v[116:119]
	v_mfma_f32_16x16x32_bf16 v[112:115], v[236:239], v[148:151], v[112:115]
	v_mfma_f32_16x16x32_bf16 v[100:103], v[226:229], v[186:189], v[100:103]
	v_mfma_f32_16x16x32_bf16 v[96:99], v[236:239], v[186:189], v[96:99]
	v_mfma_f32_16x16x32_bf16 v[84:87], v[226:229], v[194:197], v[84:87]
	v_mfma_f32_16x16x32_bf16 v[80:83], v[236:239], v[194:197], v[80:83]
	v_mfma_f32_16x16x32_bf16 v[68:71], v[226:229], v[204:207], v[68:71]
	v_mfma_f32_16x16x32_bf16 v[64:67], v[236:239], v[204:207], v[64:67]
	s_mov_b32 m0, s51
	v_lshl_add_u64 v[240:241], s[48:49], 0, v[176:177]
	s_barrier
	ds_read_b128 v[144:147], v203 offset:16384
	ds_read_b128 v[148:151], v203 offset:17408
	ds_read_b128 v[152:155], v203 offset:18432
	ds_read_b128 v[186:189], v203 offset:19456
	ds_read_b128 v[190:193], v203 offset:20480
	ds_read_b128 v[194:197], v203 offset:21504
	ds_read_b128 v[198:201], v203 offset:22528
	ds_read_b128 v[204:207], v203 offset:23552
	global_load_lds_dwordx4 v176, s[48:49]
	v_lshl_add_u64 v[242:243], s[48:49], 0, v[158:159]
	s_mov_b32 m0, s62
	s_nop 0
	global_load_lds_dwordx4 v158, s[48:49]
	s_barrier
	s_waitcnt lgkmcnt(0)
	s_waitcnt lgkmcnt(0)
	v_mfma_f32_16x16x32_bf16 v[60:63], v[128:131], v[144:147], v[60:63]
	v_mfma_f32_16x16x32_bf16 v[56:59], v[136:139], v[144:147], v[56:59]
	v_mfma_f32_16x16x32_bf16 v[44:47], v[128:131], v[152:155], v[44:47]
	v_mfma_f32_16x16x32_bf16 v[40:43], v[136:139], v[152:155], v[40:43]
	v_mfma_f32_16x16x32_bf16 v[28:31], v[128:131], v[190:193], v[28:31]
	v_mfma_f32_16x16x32_bf16 v[24:27], v[136:139], v[190:193], v[24:27]
	v_mfma_f32_16x16x32_bf16 v[12:15], v[128:131], v[198:201], v[12:15]
	v_mfma_f32_16x16x32_bf16 v[8:11], v[136:139], v[198:201], v[8:11]
	v_mfma_f32_16x16x32_bf16 v[60:63], v[132:135], v[148:151], v[60:63]
	v_mfma_f32_16x16x32_bf16 v[56:59], v[140:143], v[148:151], v[56:59]
	v_mfma_f32_16x16x32_bf16 v[44:47], v[132:135], v[186:189], v[44:47]
	v_mfma_f32_16x16x32_bf16 v[40:43], v[140:143], v[186:189], v[40:43]
	v_mfma_f32_16x16x32_bf16 v[28:31], v[132:135], v[194:197], v[28:31]
	v_mfma_f32_16x16x32_bf16 v[24:27], v[140:143], v[194:197], v[24:27]
	v_mfma_f32_16x16x32_bf16 v[12:15], v[132:135], v[204:207], v[12:15]
	v_mfma_f32_16x16x32_bf16 v[8:11], v[140:143], v[204:207], v[8:11]
	s_barrier
	s_add_u32 s34, s44, 0xb0000
	s_addc_u32 s35, s45, 0
	s_add_i32 s74, s75, s7
	s_mov_b32 m0, s74
	s_nop 0
	global_load_lds_dwordx4 v174, s[34:35]
	s_add_i32 m0, s74, 0x2000
	s_nop 0
	global_load_lds_dwordx4 v156, s[34:35]
	s_waitcnt vmcnt(6)
	s_barrier
; #define PG8_STAGE(bufoff, gbase, voff) do { _Pragma("unroll") for (int _i = 0; _i < 2; ++_i) \
;     __builtin_amdgcn_global_load_lds((const unsigned*)((const char*)(gbase) + (voff)[_i]), (LAS unsigned*)(lds + (bufoff) + ldsw + _i * 8192), 16, 0, 0); } while (0)
; #define PG8_LDA(dst, b, h) do { _Pragma("unroll") for (int m = 0; m < 4; ++m) _Pragma("unroll") for (int k = 0; k < 2; ++k) dst[m][k] = *(const LAS bf16x8*)(lds + PG8_SA(b, h) + aoff + m * 2048 + k * 1024); } while (0)
; #define PG8_LDB(dst, b, h) do { _Pragma("unroll") for (int n = 0; n < 2; ++n) _Pragma("unroll") for (int k = 0; k < 2; ++k) dst[n][k] = *(const LAS bf16x8*)(lds + PG8_SB(b, h) + boff + n * 2048 + k * 1024); } while (0)
; #define PG8_MMA(ai, bj, At, Bt) do { __builtin_amdgcn_s_setprio(1); _Pragma("unroll") for (int m = 0; m < 4; ++m) _Pragma("unroll") for (int n = 0; n < 2; ++n) _Pragma("unroll") for (int k = 0; k < 2; ++k) \
;     acc[ai][bj][m][n] = __builtin_amdgcn_mfma_f32_16x16x32_bf16(Bt[n][k], At[m][k], acc[ai][bj][m][n], 0, 0, 0); __builtin_amdgcn_s_setprio(0); } while (0)
; #define PG8_WAIT_V(n) asm volatile("s_waitcnt vmcnt(" #n ")" ::: "memory")
; #define PG8_WAIT_L(n) asm volatile("s_waitcnt lgkmcnt(" #n ")" ::: "memory")
; #define PG8_BAR __builtin_amdgcn_s_barrier()
; #define PG8_SCHED __builtin_amdgcn_sched_barrier(0)
; template <class Epi, class Sched>
; __device__ __forceinline__ void gemm_phase(LAS unsigned char* lds, const Gemm g, const Sched& S, const Epi& E) {
;     ...
;       PG8_WAIT_V(6); PG8_BAR; PG8_MMA(1, 1, At, B1); PG8_BAR;
;       PG8_LDB(B0, 1, 0); PG8_SCHED; PG8_LDA(At, 1, 0); PG8_STAGE(PG8_SA(0, 1), a2 + hstep, voffA);
;       PG8_WAIT_L(8); PG8_BAR; PG8_WAIT_L(0); PG8_MMA(0, 0, At, B0); PG8_BAR; PG8_SCHED;
;       PG8_LDB(B1, 1, 1); PG8_STAGE(PG8_SB(1, 0), b3, voffB);
	v_mfma_f32_16x16x32_bf16 v[52:55], v[208:211], v[144:147], v[52:55]
	v_mfma_f32_16x16x32_bf16 v[48:51], v[232:235], v[144:147], v[48:51]
	v_mfma_f32_16x16x32_bf16 v[36:39], v[208:211], v[152:155], v[36:39]
	v_mfma_f32_16x16x32_bf16 v[32:35], v[232:235], v[152:155], v[32:35]
	v_mfma_f32_16x16x32_bf16 v[20:23], v[208:211], v[190:193], v[20:23]
	v_mfma_f32_16x16x32_bf16 v[16:19], v[232:235], v[190:193], v[16:19]
	v_mfma_f32_16x16x32_bf16 v[4:7], v[208:211], v[198:201], v[4:7]
	v_mfma_f32_16x16x32_bf16 v[0:3], v[232:235], v[198:201], v[0:3]
	v_mfma_f32_16x16x32_bf16 v[52:55], v[226:229], v[148:151], v[52:55]
	v_mfma_f32_16x16x32_bf16 v[48:51], v[236:239], v[148:151], v[48:51]
	v_mfma_f32_16x16x32_bf16 v[36:39], v[226:229], v[186:189], v[36:39]
	v_mfma_f32_16x16x32_bf16 v[32:35], v[236:239], v[186:189], v[32:35]
	v_mfma_f32_16x16x32_bf16 v[20:23], v[226:229], v[194:197], v[20:23]
	v_mfma_f32_16x16x32_bf16 v[16:19], v[236:239], v[194:197], v[16:19]
	v_mfma_f32_16x16x32_bf16 v[4:7], v[226:229], v[204:207], v[4:7]
	v_mfma_f32_16x16x32_bf16 v[0:3], v[236:239], v[204:207], v[0:3]
	s_add_i32 s74, 0, 0x18000
	v_add_u32_e32 v140, s74, v202
	s_barrier
	ds_read_b128 v[128:131], v140
	ds_read_b128 v[132:135], v140 offset:1024
	ds_read_b128 v[136:139], v140 offset:2048
	ds_read_b128 v[140:143], v140 offset:3072
	s_add_u32 s34, s48, 0xb0000
	s_addc_u32 s35, s49, 0
	s_mov_b32 m0, s63
	ds_read_b128 v[144:147], v203 offset:32768
	ds_read_b128 v[148:151], v203 offset:33792
	ds_read_b128 v[152:155], v203 offset:34816
	ds_read_b128 v[186:189], v203 offset:35840
	ds_read_b128 v[190:193], v203 offset:36864
	ds_read_b128 v[194:197], v203 offset:37888
	ds_read_b128 v[198:201], v203 offset:38912
	ds_read_b128 v[204:207], v203 offset:39936
	global_load_lds_dwordx4 v176, s[34:35]
	s_mov_b32 m0, s64
	s_nop 0
	global_load_lds_dwordx4 v158, s[34:35]
	s_waitcnt lgkmcnt(8)
	s_barrier
	s_waitcnt lgkmcnt(0)
	s_waitcnt lgkmcnt(0)
	v_mfma_f32_16x16x32_bf16 v[124:127], v[128:131], v[144:147], v[124:127]
	v_mfma_f32_16x16x32_bf16 v[120:123], v[136:139], v[144:147], v[120:123]
	v_mfma_f32_16x16x32_bf16 v[108:111], v[128:131], v[152:155], v[108:111]
	v_mfma_f32_16x16x32_bf16 v[104:107], v[136:139], v[152:155], v[104:107]
	v_mfma_f32_16x16x32_bf16 v[92:95], v[128:131], v[190:193], v[92:95]
	v_mfma_f32_16x16x32_bf16 v[88:91], v[136:139], v[190:193], v[88:91]
	v_mfma_f32_16x16x32_bf16 v[76:79], v[128:131], v[198:201], v[76:79]
	v_mfma_f32_16x16x32_bf16 v[72:75], v[136:139], v[198:201], v[72:75]
	v_mfma_f32_16x16x32_bf16 v[124:127], v[132:135], v[148:151], v[124:127]
	v_mfma_f32_16x16x32_bf16 v[120:123], v[140:143], v[148:151], v[120:123]
	v_mfma_f32_16x16x32_bf16 v[108:111], v[132:135], v[186:189], v[108:111]
	v_mfma_f32_16x16x32_bf16 v[104:107], v[140:143], v[186:189], v[104:107]
	v_mfma_f32_16x16x32_bf16 v[92:95], v[132:135], v[194:197], v[92:95]
	v_mfma_f32_16x16x32_bf16 v[88:91], v[140:143], v[194:197], v[88:91]
	v_mfma_f32_16x16x32_bf16 v[76:79], v[132:135], v[204:207], v[76:79]
	v_mfma_f32_16x16x32_bf16 v[72:75], v[140:143], v[204:207], v[72:75]
	s_barrier
	s_add_i32 s48, 0, 0x1c000
	s_add_i32 s34, s74, s7
	v_add_u32_e32 v160, s48, v202
	s_add_u32 s60, s44, s80
	s_addc_u32 s61, s45, s81
	s_mov_b32 m0, s34
	ds_read_b128 v[208:211], v160
	ds_read_b128 v[226:229], v160 offset:1024
	ds_read_b128 v[232:235], v160 offset:2048
	ds_read_b128 v[236:239], v160 offset:3072
	global_load_lds_dwordx4 v174, s[60:61]
	s_add_i32 m0, s34, 0x2000
	s_nop 0
	global_load_lds_dwordx4 v156, s[60:61]
	s_barrier
; #define PG8_STAGE(bufoff, gbase, voff) do { _Pragma("unroll") for (int _i = 0; _i < 2; ++_i) \
;     __builtin_amdgcn_global_load_lds((const unsigned*)((const char*)(gbase) + (voff)[_i]), (LAS unsigned*)(lds + (bufoff) + ldsw + _i * 8192), 16, 0, 0); } while (0)
; #define PG8_LDA(dst, b, h) do { _Pragma("unroll") for (int m = 0; m < 4; ++m) _Pragma("unroll") for (int k = 0; k < 2; ++k) dst[m][k] = *(const LAS bf16x8*)(lds + PG8_SA(b, h) + aoff + m * 2048 + k * 1024); } while (0)
; #define PG8_MMA(ai, bj, At, Bt) do { __builtin_amdgcn_s_setprio(1); _Pragma("unroll") for (int m = 0; m < 4; ++m) _Pragma("unroll") for (int n = 0; n < 2; ++n) _Pragma("unroll") for (int k = 0; k < 2; ++k) \
;     acc[ai][bj][m][n] = __builtin_amdgcn_mfma_f32_16x16x32_bf16(Bt[n][k], At[m][k], acc[ai][bj][m][n], 0, 0, 0); __builtin_amdgcn_s_setprio(0); } while (0)
; #define PG8_WAIT_V(n) asm volatile("s_waitcnt vmcnt(" #n ")" ::: "memory")
; #define PG8_WAIT_L(n) asm volatile("s_waitcnt lgkmcnt(" #n ")" ::: "memory")
; #define PG8_BAR __builtin_amdgcn_s_barrier()
; #define PG8_SCHED __builtin_amdgcn_sched_barrier(0)
; template <class Epi, class Sched>
; __device__ __forceinline__ void gemm_phase(LAS unsigned char* lds, const Gemm g, const Sched& S, const Epi& E) {
;     ...
;       PG8_BAR; PG8_WAIT_L(0); PG8_MMA(0, 1, At, B1); PG8_BAR;
;       PG8_LDA(At, 1, 1); PG8_STAGE(PG8_SA(1, 0), a3, voffA);
;       PG8_BAR; PG8_WAIT_L(0); PG8_MMA(1, 0, At, B0); PG8_BAR; PG8_SCHED;
;       PG8_STAGE(PG8_SB(1, 1), b3 + hstep, voffB);
;       PG8_WAIT_V(6); PG8_BAR; PG8_MMA(1, 1, At, B1); PG8_BAR;
	s_waitcnt lgkmcnt(0)
	s_waitcnt lgkmcnt(0)
	v_mfma_f32_16x16x32_bf16 v[116:119], v[208:211], v[144:147], v[116:119]
	v_mfma_f32_16x16x32_bf16 v[112:115], v[232:235], v[144:147], v[112:115]
	v_mfma_f32_16x16x32_bf16 v[100:103], v[208:211], v[152:155], v[100:103]
	v_mfma_f32_16x16x32_bf16 v[96:99], v[232:235], v[152:155], v[96:99]
	v_mfma_f32_16x16x32_bf16 v[84:87], v[208:211], v[190:193], v[84:87]
	v_mfma_f32_16x16x32_bf16 v[80:83], v[232:235], v[190:193], v[80:83]
	v_mfma_f32_16x16x32_bf16 v[68:71], v[208:211], v[198:201], v[68:71]
	v_mfma_f32_16x16x32_bf16 v[64:67], v[232:235], v[198:201], v[64:67]
	v_mfma_f32_16x16x32_bf16 v[116:119], v[226:229], v[148:151], v[116:119]
	v_mfma_f32_16x16x32_bf16 v[112:115], v[236:239], v[148:151], v[112:115]
	v_mfma_f32_16x16x32_bf16 v[100:103], v[226:229], v[186:189], v[100:103]
	v_mfma_f32_16x16x32_bf16 v[96:99], v[236:239], v[186:189], v[96:99]
	v_mfma_f32_16x16x32_bf16 v[84:87], v[226:229], v[194:197], v[84:87]
	v_mfma_f32_16x16x32_bf16 v[80:83], v[236:239], v[194:197], v[80:83]
	v_mfma_f32_16x16x32_bf16 v[68:71], v[226:229], v[204:207], v[68:71]
	v_mfma_f32_16x16x32_bf16 v[64:67], v[236:239], v[204:207], v[64:67]
	s_mov_b32 m0, s65
	v_lshl_add_u64 v[212:213], v[240:241], 0, s[80:81]
	s_barrier
	ds_read_b128 v[144:147], v203 offset:49152
	ds_read_b128 v[148:151], v203 offset:50176
	ds_read_b128 v[152:155], v203 offset:51200
	ds_read_b128 v[186:189], v203 offset:52224
	ds_read_b128 v[190:193], v203 offset:53248
	ds_read_b128 v[194:197], v203 offset:54272
	ds_read_b128 v[198:201], v203 offset:55296
	ds_read_b128 v[204:207], v203 offset:56320
	global_load_lds_dwordx4 v[212:213], off
	v_lshl_add_u64 v[212:213], v[242:243], 0, s[80:81]
	s_mov_b32 m0, s70
	s_nop 0
	global_load_lds_dwordx4 v[212:213], off
	s_barrier
	s_waitcnt lgkmcnt(0)
	s_waitcnt lgkmcnt(0)
	v_mfma_f32_16x16x32_bf16 v[60:63], v[128:131], v[144:147], v[60:63]
	v_mfma_f32_16x16x32_bf16 v[56:59], v[136:139], v[144:147], v[56:59]
	v_mfma_f32_16x16x32_bf16 v[44:47], v[128:131], v[152:155], v[44:47]
	v_mfma_f32_16x16x32_bf16 v[40:43], v[136:139], v[152:155], v[40:43]
	v_mfma_f32_16x16x32_bf16 v[28:31], v[128:131], v[190:193], v[28:31]
	v_mfma_f32_16x16x32_bf16 v[24:27], v[136:139], v[190:193], v[24:27]
	v_mfma_f32_16x16x32_bf16 v[12:15], v[128:131], v[198:201], v[12:15]
	v_mfma_f32_16x16x32_bf16 v[8:11], v[136:139], v[198:201], v[8:11]
	v_mfma_f32_16x16x32_bf16 v[60:63], v[132:135], v[148:151], v[60:63]
	v_mfma_f32_16x16x32_bf16 v[56:59], v[140:143], v[148:151], v[56:59]
	v_mfma_f32_16x16x32_bf16 v[44:47], v[132:135], v[186:189], v[44:47]
	v_mfma_f32_16x16x32_bf16 v[40:43], v[140:143], v[186:189], v[40:43]
	v_mfma_f32_16x16x32_bf16 v[28:31], v[132:135], v[194:197], v[28:31]
	v_mfma_f32_16x16x32_bf16 v[24:27], v[140:143], v[194:197], v[24:27]
	v_mfma_f32_16x16x32_bf16 v[12:15], v[132:135], v[204:207], v[12:15]
	v_mfma_f32_16x16x32_bf16 v[8:11], v[140:143], v[204:207], v[8:11]
	s_barrier
	s_add_u32 s34, s44, 0xb0080
	s_addc_u32 s35, s45, 0
	s_add_i32 s44, s48, s7
	s_mov_b32 m0, s44
	s_nop 0
	global_load_lds_dwordx4 v174, s[34:35]
	s_add_i32 m0, s44, 0x2000
	s_nop 0
	global_load_lds_dwordx4 v156, s[34:35]
	s_waitcnt vmcnt(6)
	s_barrier
	v_mfma_f32_16x16x32_bf16 v[52:55], v[208:211], v[144:147], v[52:55]
	v_mfma_f32_16x16x32_bf16 v[48:51], v[232:235], v[144:147], v[48:51]
	v_mfma_f32_16x16x32_bf16 v[36:39], v[208:211], v[152:155], v[36:39]
	v_mfma_f32_16x16x32_bf16 v[32:35], v[232:235], v[152:155], v[32:35]
	v_mfma_f32_16x16x32_bf16 v[20:23], v[208:211], v[190:193], v[20:23]
	v_mfma_f32_16x16x32_bf16 v[16:19], v[232:235], v[190:193], v[16:19]
	v_mfma_f32_16x16x32_bf16 v[4:7], v[208:211], v[198:201], v[4:7]
	v_mfma_f32_16x16x32_bf16 v[0:3], v[232:235], v[198:201], v[0:3]
	v_mfma_f32_16x16x32_bf16 v[52:55], v[226:229], v[148:151], v[52:55]
	v_mfma_f32_16x16x32_bf16 v[48:51], v[236:239], v[148:151], v[48:51]
	v_mfma_f32_16x16x32_bf16 v[36:39], v[226:229], v[186:189], v[36:39]
	v_mfma_f32_16x16x32_bf16 v[32:35], v[236:239], v[186:189], v[32:35]
	v_mfma_f32_16x16x32_bf16 v[20:23], v[226:229], v[194:197], v[20:23]
	v_mfma_f32_16x16x32_bf16 v[16:19], v[236:239], v[194:197], v[16:19]
	v_mfma_f32_16x16x32_bf16 v[4:7], v[226:229], v[204:207], v[4:7]
	v_mfma_f32_16x16x32_bf16 v[0:3], v[236:239], v[204:207], v[0:3]
	s_add_i32 s73, s73, 2
	s_add_u32 s52, s52, 0x100
	s_addc_u32 s72, s72, 0
	s_cmp_gt_u32 s73, 41
	s_mov_b64 s[34:35], s[42:43]
	s_barrier
	s_cbranch_scc0 .LBB0_1215
	s_cmp_lt_u32 s101, 0x100
	s_cbranch_scc0 .Lxa_11
	s_barrier
